# all 6 norm passes rewritten (L0 f32 pass: 16 x rows + 1 ctx row per wave, 6 rows in flight)
# speedup vs baseline: 1.0036x; 1.0036x over previous
; __device__ __forceinline__ void norm_pass(const Ctx& X, const float* xs, const float* cs, int nrows, const float* gain, const float* modl, int si, bf16_t* HN) {
;     for (int r = X.gw; r < nrows; r += X.NGW) {
;         const float* row = r < MX ? xs + (size_t)r * D : cs + (size_t)(r - MX) * D;
;         const int mb = r < MX ? (r >> 12) : 8;
;         const float* sh = modl + (size_t)mb * 9216 + si * 1024; const float* scl = sh + 1024;
;         f32x4 v[4]; float s = 0.f;
; #pragma unroll
;         for (int j = 0; j < 4; ++j) { v[j] = *(const f32x4*)(row + (X.lane + 64 * j) * 4); s += (v[j].x * v[j].x + v[j].y * v[j].y) + (v[j].z * v[j].z + v[j].w * v[j].w); }
.LBB0_189:
	s_or_b64 exec, exec, s[0:1]
	v_mov_b32_e32 v0, v206
	s_add_u32 s18, s88, 0x13000000
	s_addc_u32 s19, s89, 0
	v_readfirstlane_b32 s0, v0
	s_ashr_i32 s0, s0, 6
	v_readlane_b32 s1, v254, 14
	s_lshl_b32 s20, s90, 3
	s_add_i32 s1, s0, s1
	s_cmp_lt_i32 s1, 0x8800
	v_mbcnt_lo_u32_b32 v207, -1, 0
	s_cbranch_scc0 .LBB0_194
	v_readfirstlane_b32 s0, v206
	s_ashr_i32 s0, s0, 6
	v_readlane_b32 s1, v254, 14
	s_add_i32 s14, s0, s1
	s_cmp_lt_i32 s14, 0x800
	s_cbranch_scc0 .LBB0_194
	v_mbcnt_hi_u32_b32 v0, -1, v207
	v_lshlrev_b32_e32 v1, 4, v0
	v_lshlrev_b32_e32 v2, 5, v0
	v_mov_b32_e32 v3, 0x358637bd
.Lhn32_blk:
	global_load_dwordx4 v[16:19], v2, s[48:49]
	global_load_dwordx4 v[20:23], v2, s[48:49] offset:16
	global_load_dwordx4 v[24:27], v2, s[48:49] offset:2048
	global_load_dwordx4 v[28:31], v2, s[48:49] offset:2064
	s_lshr_b32 s1, s14, 8
	s_mul_i32 s1, s1, 0x9000
	s_add_u32 s4, s88, s1
	s_addc_u32 s5, s89, 0
	global_load_dwordx4 v[48:51], v2, s[4:5]
	global_load_dwordx4 v[52:55], v2, s[4:5] offset:16
	global_load_dwordx4 v[56:59], v2, s[4:5] offset:2048
	global_load_dwordx4 v[60:63], v2, s[4:5] offset:2064
	s_add_u32 s4, s4, 0x1000
	s_addc_u32 s5, s5, 0
	global_load_dwordx4 v[32:35], v2, s[4:5]
	global_load_dwordx4 v[36:39], v2, s[4:5] offset:16
	global_load_dwordx4 v[40:43], v2, s[4:5] offset:2048
	global_load_dwordx4 v[44:47], v2, s[4:5] offset:2064
	s_add_u32 s4, s88, 0x48000
	s_addc_u32 s5, s89, 0
	global_load_dwordx4 v[176:179], v2, s[4:5]
	global_load_dwordx4 v[180:183], v2, s[4:5] offset:16
	global_load_dwordx4 v[184:187], v2, s[4:5] offset:2048
	global_load_dwordx4 v[188:191], v2, s[4:5] offset:2064
	s_add_u32 s4, s4, 0x1000
	s_addc_u32 s5, s5, 0
	global_load_dwordx4 v[160:163], v2, s[4:5]
	global_load_dwordx4 v[164:167], v2, s[4:5] offset:16
	global_load_dwordx4 v[168:171], v2, s[4:5] offset:2048
	global_load_dwordx4 v[172:175], v2, s[4:5] offset:2064
	s_lshl_b32 s1, s14, 16
	s_add_u32 s6, s36, s1
	s_addc_u32 s7, s37, 0
	s_lshl_b32 s1, s14, 15
	s_add_u32 s8, s18, s1
	s_addc_u32 s9, s19, 0
	s_lshl_b32 s1, s14, 12
	s_add_u32 s10, s40, s1
	s_addc_u32 s11, s41, 0
	s_lshl_b32 s1, s14, 11
	s_add_u32 s12, s18, s1
	s_addc_u32 s13, s19, 0
	s_add_u32 s12, s12, 0x4000000
	s_addc_u32 s13, s13, 0
	global_load_dwordx4 v[64:67], v2, s[6:7]
	global_load_dwordx4 v[68:71], v2, s[6:7] offset:16
	global_load_dwordx4 v[72:75], v2, s[6:7] offset:2048
	global_load_dwordx4 v[76:79], v2, s[6:7] offset:2064
	s_add_u32 s6, s6, 0x1000
	s_addc_u32 s7, s7, 0
	global_load_dwordx4 v[80:83], v2, s[6:7]
	global_load_dwordx4 v[84:87], v2, s[6:7] offset:16
	global_load_dwordx4 v[88:91], v2, s[6:7] offset:2048
	global_load_dwordx4 v[92:95], v2, s[6:7] offset:2064
	s_add_u32 s6, s6, 0x1000
	s_addc_u32 s7, s7, 0
	global_load_dwordx4 v[96:99], v2, s[6:7]
	global_load_dwordx4 v[100:103], v2, s[6:7] offset:16
	global_load_dwordx4 v[104:107], v2, s[6:7] offset:2048
	global_load_dwordx4 v[108:111], v2, s[6:7] offset:2064
	s_add_u32 s6, s6, 0x1000
	s_addc_u32 s7, s7, 0
	global_load_dwordx4 v[112:115], v2, s[6:7]
	global_load_dwordx4 v[116:119], v2, s[6:7] offset:16
	global_load_dwordx4 v[120:123], v2, s[6:7] offset:2048
	global_load_dwordx4 v[124:127], v2, s[6:7] offset:2064
	s_add_u32 s6, s6, 0x1000
	s_addc_u32 s7, s7, 0
	global_load_dwordx4 v[128:131], v2, s[6:7]
	global_load_dwordx4 v[132:135], v2, s[6:7] offset:16
	global_load_dwordx4 v[136:139], v2, s[6:7] offset:2048
	global_load_dwordx4 v[140:143], v2, s[6:7] offset:2064
	s_add_u32 s6, s6, 0x1000
	s_addc_u32 s7, s7, 0
	global_load_dwordx4 v[144:147], v2, s[6:7]
	global_load_dwordx4 v[148:151], v2, s[6:7] offset:16
	global_load_dwordx4 v[152:155], v2, s[6:7] offset:2048
	global_load_dwordx4 v[156:159], v2, s[6:7] offset:2064
	s_add_u32 s6, s6, 0x1000
	s_addc_u32 s7, s7, 0
	s_waitcnt vmcnt(24)
	v_pk_add_f32 v[32:33], v[32:33], 1.0 op_sel_hi:[1,0]
	v_pk_add_f32 v[34:35], v[34:35], 1.0 op_sel_hi:[1,0]
	v_pk_add_f32 v[36:37], v[36:37], 1.0 op_sel_hi:[1,0]
	v_pk_add_f32 v[38:39], v[38:39], 1.0 op_sel_hi:[1,0]
	v_pk_add_f32 v[40:41], v[40:41], 1.0 op_sel_hi:[1,0]
	v_pk_add_f32 v[42:43], v[42:43], 1.0 op_sel_hi:[1,0]
	v_pk_add_f32 v[44:45], v[44:45], 1.0 op_sel_hi:[1,0]
	v_pk_add_f32 v[46:47], v[46:47], 1.0 op_sel_hi:[1,0]
	v_pk_add_f32 v[160:161], v[160:161], 1.0 op_sel_hi:[1,0]
	v_pk_add_f32 v[162:163], v[162:163], 1.0 op_sel_hi:[1,0]
	v_pk_add_f32 v[164:165], v[164:165], 1.0 op_sel_hi:[1,0]
	v_pk_add_f32 v[166:167], v[166:167], 1.0 op_sel_hi:[1,0]
	v_pk_add_f32 v[168:169], v[168:169], 1.0 op_sel_hi:[1,0]
	v_pk_add_f32 v[170:171], v[170:171], 1.0 op_sel_hi:[1,0]
	v_pk_add_f32 v[172:173], v[172:173], 1.0 op_sel_hi:[1,0]
	v_pk_add_f32 v[174:175], v[174:175], 1.0 op_sel_hi:[1,0]
	s_waitcnt vmcnt(20)
; __device__ __forceinline__ unsigned cvt_pk_bf16(float lo, float hi) { unsigned r; asm("v_cvt_pk_bf16_f32 %0, %1, %2" : "=v"(r) : "v"(lo), "v"(hi)); return r; }
; __device__ __forceinline__ void norm_pass(const Ctx& X, const float* xs, const float* cs, int nrows, const float* gain, const float* modl, int si, bf16_t* HN) {
;     ...
;         f32x4 v[4]; float s = 0.f;
; #pragma unroll
;         for (int j = 0; j < 4; ++j) { v[j] = *(const f32x4*)(row + (X.lane + 64 * j) * 4); s += (v[j].x * v[j].x + v[j].y * v[j].y) + (v[j].z * v[j].z + v[j].w * v[j].w); }
;         const float rstd = rsqrtf(wave_sum(s) * (1.0f / 1024.0f) + 1e-6f);
; #pragma unroll
;         for (int j = 0; j < 4; ++j) { const int c = (X.lane + 64 * j) * 4; const f32x4 gn = *(const f32x4*)(gain + c), a = *(const f32x4*)(scl + c), b = *(const f32x4*)(sh + c);
;             const f32x4 o = v[j] * rstd * gn * (a + 1.0f) + b; u32x2 w; w.x = cvt_pk_bf16(o.x, o.y); w.y = cvt_pk_bf16(o.z, o.w); *(u32x2*)(HN + (size_t)r * D + c) = w; }
	v_pk_mul_f32 v[200:201], v[64:65], v[64:65]
	v_pk_fma_f32 v[200:201], v[66:67], v[66:67], v[200:201]
	v_pk_fma_f32 v[200:201], v[68:69], v[68:69], v[200:201]
	v_pk_fma_f32 v[200:201], v[70:71], v[70:71], v[200:201]
	v_pk_fma_f32 v[200:201], v[72:73], v[72:73], v[200:201]
	v_pk_fma_f32 v[200:201], v[74:75], v[74:75], v[200:201]
	v_pk_fma_f32 v[200:201], v[76:77], v[76:77], v[200:201]
	v_pk_fma_f32 v[200:201], v[78:79], v[78:79], v[200:201]
	v_add_f32_e32 v200, v200, v201
	s_nop 1
	v_add_f32_dpp v200, v200, v200 quad_perm:[1,0,3,2] row_mask:0xf bank_mask:0xf
	s_nop 1
	v_add_f32_dpp v200, v200, v200 quad_perm:[2,3,0,1] row_mask:0xf bank_mask:0xf
	s_nop 1
	v_add_f32_dpp v200, v200, v200 row_half_mirror row_mask:0xf bank_mask:0xf
	s_nop 1
	v_add_f32_dpp v200, v200, v200 row_mirror row_mask:0xf bank_mask:0xf
	s_nop 1
	v_mov_b32_e32 v201, v200
	s_nop 1
	v_permlane16_swap_b32_e32 v200, v201
	s_nop 0
	v_add_f32_e32 v200, v200, v201
	v_mov_b32_e32 v201, v200
	s_nop 1
	v_permlane32_swap_b32_e32 v200, v201
	s_nop 0
	v_add_f32_e32 v200, v200, v201
	v_fmamk_f32 v200, v200, 0x3a800000, v3
	v_rsq_f32_e32 v200, v200
	s_nop 0
	v_pk_mul_f32 v[64:65], v[64:65], v[200:201] op_sel_hi:[1,0]
	v_pk_mul_f32 v[66:67], v[66:67], v[200:201] op_sel_hi:[1,0]
	v_pk_mul_f32 v[68:69], v[68:69], v[200:201] op_sel_hi:[1,0]
	v_pk_mul_f32 v[70:71], v[70:71], v[200:201] op_sel_hi:[1,0]
	v_pk_mul_f32 v[72:73], v[72:73], v[200:201] op_sel_hi:[1,0]
	v_pk_mul_f32 v[74:75], v[74:75], v[200:201] op_sel_hi:[1,0]
	v_pk_mul_f32 v[76:77], v[76:77], v[200:201] op_sel_hi:[1,0]
	v_pk_mul_f32 v[78:79], v[78:79], v[200:201] op_sel_hi:[1,0]
	v_pk_mul_f32 v[64:65], v[16:17], v[64:65]
	v_pk_mul_f32 v[66:67], v[18:19], v[66:67]
	v_pk_mul_f32 v[68:69], v[20:21], v[68:69]
	v_pk_mul_f32 v[70:71], v[22:23], v[70:71]
	v_pk_mul_f32 v[72:73], v[24:25], v[72:73]
	v_pk_mul_f32 v[74:75], v[26:27], v[74:75]
	v_pk_mul_f32 v[76:77], v[28:29], v[76:77]
	v_pk_mul_f32 v[78:79], v[30:31], v[78:79]
	v_pk_fma_f32 v[64:65], v[32:33], v[64:65], v[48:49]
	v_pk_fma_f32 v[66:67], v[34:35], v[66:67], v[50:51]
	v_pk_fma_f32 v[68:69], v[36:37], v[68:69], v[52:53]
	v_pk_fma_f32 v[70:71], v[38:39], v[70:71], v[54:55]
	v_pk_fma_f32 v[72:73], v[40:41], v[72:73], v[56:57]
	v_pk_fma_f32 v[74:75], v[42:43], v[74:75], v[58:59]
	v_pk_fma_f32 v[76:77], v[44:45], v[76:77], v[60:61]
	v_pk_fma_f32 v[78:79], v[46:47], v[78:79], v[62:63]
	v_cvt_pk_bf16_f32 v192, v64, v65
	v_cvt_pk_bf16_f32 v193, v66, v67
	v_cvt_pk_bf16_f32 v194, v68, v69
	v_cvt_pk_bf16_f32 v195, v70, v71
	v_cvt_pk_bf16_f32 v196, v72, v73
	v_cvt_pk_bf16_f32 v197, v74, v75
	v_cvt_pk_bf16_f32 v198, v76, v77
	v_cvt_pk_bf16_f32 v199, v78, v79
	global_store_dwordx4 v1, v[192:195], s[8:9]
	global_store_dwordx4 v1, v[196:199], s[8:9] offset:1024
	global_load_dwordx4 v[64:67], v2, s[6:7]
	global_load_dwordx4 v[68:71], v2, s[6:7] offset:16
	global_load_dwordx4 v[72:75], v2, s[6:7] offset:2048
	global_load_dwordx4 v[76:79], v2, s[6:7] offset:2064
	s_add_u32 s6, s6, 0x1000
	s_addc_u32 s7, s7, 0
	s_waitcnt vmcnt(22)
	v_pk_mul_f32 v[200:201], v[80:81], v[80:81]
	v_pk_fma_f32 v[200:201], v[82:83], v[82:83], v[200:201]
	v_pk_fma_f32 v[200:201], v[84:85], v[84:85], v[200:201]
	v_pk_fma_f32 v[200:201], v[86:87], v[86:87], v[200:201]
	v_pk_fma_f32 v[200:201], v[88:89], v[88:89], v[200:201]
	v_pk_fma_f32 v[200:201], v[90:91], v[90:91], v[200:201]
	v_pk_fma_f32 v[200:201], v[92:93], v[92:93], v[200:201]
	v_pk_fma_f32 v[200:201], v[94:95], v[94:95], v[200:201]
	v_add_f32_e32 v200, v200, v201
	s_nop 1
	v_add_f32_dpp v200, v200, v200 quad_perm:[1,0,3,2] row_mask:0xf bank_mask:0xf
	s_nop 1
	v_add_f32_dpp v200, v200, v200 quad_perm:[2,3,0,1] row_mask:0xf bank_mask:0xf
	s_nop 1
	v_add_f32_dpp v200, v200, v200 row_half_mirror row_mask:0xf bank_mask:0xf
	s_nop 1
	v_add_f32_dpp v200, v200, v200 row_mirror row_mask:0xf bank_mask:0xf
	s_nop 1
	v_mov_b32_e32 v201, v200
	s_nop 1
	v_permlane16_swap_b32_e32 v200, v201
	s_nop 0
	v_add_f32_e32 v200, v200, v201
	v_mov_b32_e32 v201, v200
	s_nop 1
	v_permlane32_swap_b32_e32 v200, v201
	s_nop 0
	v_add_f32_e32 v200, v200, v201
	v_fmamk_f32 v200, v200, 0x3a800000, v3
	v_rsq_f32_e32 v200, v200
	s_nop 0
	v_pk_mul_f32 v[80:81], v[80:81], v[200:201] op_sel_hi:[1,0]
	v_pk_mul_f32 v[82:83], v[82:83], v[200:201] op_sel_hi:[1,0]
	v_pk_mul_f32 v[84:85], v[84:85], v[200:201] op_sel_hi:[1,0]
	v_pk_mul_f32 v[86:87], v[86:87], v[200:201] op_sel_hi:[1,0]
	v_pk_mul_f32 v[88:89], v[88:89], v[200:201] op_sel_hi:[1,0]
	v_pk_mul_f32 v[90:91], v[90:91], v[200:201] op_sel_hi:[1,0]
	v_pk_mul_f32 v[92:93], v[92:93], v[200:201] op_sel_hi:[1,0]
	v_pk_mul_f32 v[94:95], v[94:95], v[200:201] op_sel_hi:[1,0]
	v_pk_mul_f32 v[80:81], v[16:17], v[80:81]
	v_pk_mul_f32 v[82:83], v[18:19], v[82:83]
	v_pk_mul_f32 v[84:85], v[20:21], v[84:85]
	v_pk_mul_f32 v[86:87], v[22:23], v[86:87]
	v_pk_mul_f32 v[88:89], v[24:25], v[88:89]
	v_pk_mul_f32 v[90:91], v[26:27], v[90:91]
	v_pk_mul_f32 v[92:93], v[28:29], v[92:93]
	v_pk_mul_f32 v[94:95], v[30:31], v[94:95]
	v_pk_fma_f32 v[80:81], v[32:33], v[80:81], v[48:49]
	v_pk_fma_f32 v[82:83], v[34:35], v[82:83], v[50:51]
	v_pk_fma_f32 v[84:85], v[36:37], v[84:85], v[52:53]
	v_pk_fma_f32 v[86:87], v[38:39], v[86:87], v[54:55]
	v_pk_fma_f32 v[88:89], v[40:41], v[88:89], v[56:57]
	v_pk_fma_f32 v[90:91], v[42:43], v[90:91], v[58:59]
	v_pk_fma_f32 v[92:93], v[44:45], v[92:93], v[60:61]
	v_pk_fma_f32 v[94:95], v[46:47], v[94:95], v[62:63]
	v_cvt_pk_bf16_f32 v192, v80, v81
	v_cvt_pk_bf16_f32 v193, v82, v83
	v_cvt_pk_bf16_f32 v194, v84, v85
	v_cvt_pk_bf16_f32 v195, v86, v87
	v_cvt_pk_bf16_f32 v196, v88, v89
	v_cvt_pk_bf16_f32 v197, v90, v91
	v_cvt_pk_bf16_f32 v198, v92, v93
	v_cvt_pk_bf16_f32 v199, v94, v95
	global_store_dwordx4 v1, v[192:195], s[8:9] offset:2048
	global_store_dwordx4 v1, v[196:199], s[8:9] offset:3072
	s_add_u32 s8, s8, 0x1000
	s_addc_u32 s9, s9, 0
	global_load_dwordx4 v[80:83], v2, s[6:7]
	global_load_dwordx4 v[84:87], v2, s[6:7] offset:16
	global_load_dwordx4 v[88:91], v2, s[6:7] offset:2048
	global_load_dwordx4 v[92:95], v2, s[6:7] offset:2064
	s_add_u32 s6, s6, 0x1000
	s_addc_u32 s7, s7, 0
	s_waitcnt vmcnt(24)
; __device__ __forceinline__ unsigned cvt_pk_bf16(float lo, float hi) { unsigned r; asm("v_cvt_pk_bf16_f32 %0, %1, %2" : "=v"(r) : "v"(lo), "v"(hi)); return r; }
; __device__ __forceinline__ void norm_pass(const Ctx& X, const float* xs, const float* cs, int nrows, const float* gain, const float* modl, int si, bf16_t* HN) {
;     ...
;         f32x4 v[4]; float s = 0.f;
; #pragma unroll
;         for (int j = 0; j < 4; ++j) { v[j] = *(const f32x4*)(row + (X.lane + 64 * j) * 4); s += (v[j].x * v[j].x + v[j].y * v[j].y) + (v[j].z * v[j].z + v[j].w * v[j].w); }
;         const float rstd = rsqrtf(wave_sum(s) * (1.0f / 1024.0f) + 1e-6f);
; #pragma unroll
;         for (int j = 0; j < 4; ++j) { const int c = (X.lane + 64 * j) * 4; const f32x4 gn = *(const f32x4*)(gain + c), a = *(const f32x4*)(scl + c), b = *(const f32x4*)(sh + c);
;             const f32x4 o = v[j] * rstd * gn * (a + 1.0f) + b; u32x2 w; w.x = cvt_pk_bf16(o.x, o.y); w.y = cvt_pk_bf16(o.z, o.w); *(u32x2*)(HN + (size_t)r * D + c) = w; }
	v_pk_mul_f32 v[200:201], v[96:97], v[96:97]
	v_pk_fma_f32 v[200:201], v[98:99], v[98:99], v[200:201]
	v_pk_fma_f32 v[200:201], v[100:101], v[100:101], v[200:201]
	v_pk_fma_f32 v[200:201], v[102:103], v[102:103], v[200:201]
	v_pk_fma_f32 v[200:201], v[104:105], v[104:105], v[200:201]
	v_pk_fma_f32 v[200:201], v[106:107], v[106:107], v[200:201]
	v_pk_fma_f32 v[200:201], v[108:109], v[108:109], v[200:201]
	v_pk_fma_f32 v[200:201], v[110:111], v[110:111], v[200:201]
	v_add_f32_e32 v200, v200, v201
	s_nop 1
	v_add_f32_dpp v200, v200, v200 quad_perm:[1,0,3,2] row_mask:0xf bank_mask:0xf
	s_nop 1
	v_add_f32_dpp v200, v200, v200 quad_perm:[2,3,0,1] row_mask:0xf bank_mask:0xf
	s_nop 1
	v_add_f32_dpp v200, v200, v200 row_half_mirror row_mask:0xf bank_mask:0xf
	s_nop 1
	v_add_f32_dpp v200, v200, v200 row_mirror row_mask:0xf bank_mask:0xf
	s_nop 1
	v_mov_b32_e32 v201, v200
	s_nop 1
	v_permlane16_swap_b32_e32 v200, v201
	s_nop 0
	v_add_f32_e32 v200, v200, v201
	v_mov_b32_e32 v201, v200
	s_nop 1
	v_permlane32_swap_b32_e32 v200, v201
	s_nop 0
	v_add_f32_e32 v200, v200, v201
	v_fmamk_f32 v200, v200, 0x3a800000, v3
	v_rsq_f32_e32 v200, v200
	s_nop 0
	v_pk_mul_f32 v[96:97], v[96:97], v[200:201] op_sel_hi:[1,0]
	v_pk_mul_f32 v[98:99], v[98:99], v[200:201] op_sel_hi:[1,0]
	v_pk_mul_f32 v[100:101], v[100:101], v[200:201] op_sel_hi:[1,0]
	v_pk_mul_f32 v[102:103], v[102:103], v[200:201] op_sel_hi:[1,0]
	v_pk_mul_f32 v[104:105], v[104:105], v[200:201] op_sel_hi:[1,0]
	v_pk_mul_f32 v[106:107], v[106:107], v[200:201] op_sel_hi:[1,0]
	v_pk_mul_f32 v[108:109], v[108:109], v[200:201] op_sel_hi:[1,0]
	v_pk_mul_f32 v[110:111], v[110:111], v[200:201] op_sel_hi:[1,0]
	v_pk_mul_f32 v[96:97], v[16:17], v[96:97]
	v_pk_mul_f32 v[98:99], v[18:19], v[98:99]
	v_pk_mul_f32 v[100:101], v[20:21], v[100:101]
	v_pk_mul_f32 v[102:103], v[22:23], v[102:103]
	v_pk_mul_f32 v[104:105], v[24:25], v[104:105]
	v_pk_mul_f32 v[106:107], v[26:27], v[106:107]
	v_pk_mul_f32 v[108:109], v[28:29], v[108:109]
	v_pk_mul_f32 v[110:111], v[30:31], v[110:111]
	v_pk_fma_f32 v[96:97], v[32:33], v[96:97], v[48:49]
	v_pk_fma_f32 v[98:99], v[34:35], v[98:99], v[50:51]
	v_pk_fma_f32 v[100:101], v[36:37], v[100:101], v[52:53]
	v_pk_fma_f32 v[102:103], v[38:39], v[102:103], v[54:55]
	v_pk_fma_f32 v[104:105], v[40:41], v[104:105], v[56:57]
	v_pk_fma_f32 v[106:107], v[42:43], v[106:107], v[58:59]
	v_pk_fma_f32 v[108:109], v[44:45], v[108:109], v[60:61]
	v_pk_fma_f32 v[110:111], v[46:47], v[110:111], v[62:63]
	v_cvt_pk_bf16_f32 v192, v96, v97
	v_cvt_pk_bf16_f32 v193, v98, v99
	v_cvt_pk_bf16_f32 v194, v100, v101
	v_cvt_pk_bf16_f32 v195, v102, v103
	v_cvt_pk_bf16_f32 v196, v104, v105
	v_cvt_pk_bf16_f32 v197, v106, v107
	v_cvt_pk_bf16_f32 v198, v108, v109
	v_cvt_pk_bf16_f32 v199, v110, v111
	global_store_dwordx4 v1, v[192:195], s[8:9]
	global_store_dwordx4 v1, v[196:199], s[8:9] offset:1024
	global_load_dwordx4 v[96:99], v2, s[6:7]
	global_load_dwordx4 v[100:103], v2, s[6:7] offset:16
	global_load_dwordx4 v[104:107], v2, s[6:7] offset:2048
	global_load_dwordx4 v[108:111], v2, s[6:7] offset:2064
	s_add_u32 s6, s6, 0x1000
	s_addc_u32 s7, s7, 0
	s_waitcnt vmcnt(26)
	v_pk_mul_f32 v[200:201], v[112:113], v[112:113]
	v_pk_fma_f32 v[200:201], v[114:115], v[114:115], v[200:201]
	v_pk_fma_f32 v[200:201], v[116:117], v[116:117], v[200:201]
	v_pk_fma_f32 v[200:201], v[118:119], v[118:119], v[200:201]
	v_pk_fma_f32 v[200:201], v[120:121], v[120:121], v[200:201]
	v_pk_fma_f32 v[200:201], v[122:123], v[122:123], v[200:201]
	v_pk_fma_f32 v[200:201], v[124:125], v[124:125], v[200:201]
	v_pk_fma_f32 v[200:201], v[126:127], v[126:127], v[200:201]
	v_add_f32_e32 v200, v200, v201
	s_nop 1
	v_add_f32_dpp v200, v200, v200 quad_perm:[1,0,3,2] row_mask:0xf bank_mask:0xf
	s_nop 1
	v_add_f32_dpp v200, v200, v200 quad_perm:[2,3,0,1] row_mask:0xf bank_mask:0xf
	s_nop 1
	v_add_f32_dpp v200, v200, v200 row_half_mirror row_mask:0xf bank_mask:0xf
	s_nop 1
	v_add_f32_dpp v200, v200, v200 row_mirror row_mask:0xf bank_mask:0xf
	s_nop 1
	v_mov_b32_e32 v201, v200
	s_nop 1
	v_permlane16_swap_b32_e32 v200, v201
	s_nop 0
	v_add_f32_e32 v200, v200, v201
	v_mov_b32_e32 v201, v200
	s_nop 1
	v_permlane32_swap_b32_e32 v200, v201
	s_nop 0
	v_add_f32_e32 v200, v200, v201
	v_fmamk_f32 v200, v200, 0x3a800000, v3
	v_rsq_f32_e32 v200, v200
	s_nop 0
	v_pk_mul_f32 v[112:113], v[112:113], v[200:201] op_sel_hi:[1,0]
	v_pk_mul_f32 v[114:115], v[114:115], v[200:201] op_sel_hi:[1,0]
	v_pk_mul_f32 v[116:117], v[116:117], v[200:201] op_sel_hi:[1,0]
	v_pk_mul_f32 v[118:119], v[118:119], v[200:201] op_sel_hi:[1,0]
	v_pk_mul_f32 v[120:121], v[120:121], v[200:201] op_sel_hi:[1,0]
	v_pk_mul_f32 v[122:123], v[122:123], v[200:201] op_sel_hi:[1,0]
	v_pk_mul_f32 v[124:125], v[124:125], v[200:201] op_sel_hi:[1,0]
	v_pk_mul_f32 v[126:127], v[126:127], v[200:201] op_sel_hi:[1,0]
	v_pk_mul_f32 v[112:113], v[16:17], v[112:113]
	v_pk_mul_f32 v[114:115], v[18:19], v[114:115]
	v_pk_mul_f32 v[116:117], v[20:21], v[116:117]
	v_pk_mul_f32 v[118:119], v[22:23], v[118:119]
	v_pk_mul_f32 v[120:121], v[24:25], v[120:121]
	v_pk_mul_f32 v[122:123], v[26:27], v[122:123]
	v_pk_mul_f32 v[124:125], v[28:29], v[124:125]
	v_pk_mul_f32 v[126:127], v[30:31], v[126:127]
	v_pk_fma_f32 v[112:113], v[32:33], v[112:113], v[48:49]
	v_pk_fma_f32 v[114:115], v[34:35], v[114:115], v[50:51]
	v_pk_fma_f32 v[116:117], v[36:37], v[116:117], v[52:53]
	v_pk_fma_f32 v[118:119], v[38:39], v[118:119], v[54:55]
	v_pk_fma_f32 v[120:121], v[40:41], v[120:121], v[56:57]
	v_pk_fma_f32 v[122:123], v[42:43], v[122:123], v[58:59]
	v_pk_fma_f32 v[124:125], v[44:45], v[124:125], v[60:61]
	v_pk_fma_f32 v[126:127], v[46:47], v[126:127], v[62:63]
	v_cvt_pk_bf16_f32 v192, v112, v113
	v_cvt_pk_bf16_f32 v193, v114, v115
	v_cvt_pk_bf16_f32 v194, v116, v117
	v_cvt_pk_bf16_f32 v195, v118, v119
	v_cvt_pk_bf16_f32 v196, v120, v121
	v_cvt_pk_bf16_f32 v197, v122, v123
	v_cvt_pk_bf16_f32 v198, v124, v125
	v_cvt_pk_bf16_f32 v199, v126, v127
	global_store_dwordx4 v1, v[192:195], s[8:9] offset:2048
	global_store_dwordx4 v1, v[196:199], s[8:9] offset:3072
	s_add_u32 s8, s8, 0x1000
	s_addc_u32 s9, s9, 0
	global_load_dwordx4 v[112:115], v2, s[6:7]
	global_load_dwordx4 v[116:119], v2, s[6:7] offset:16
	global_load_dwordx4 v[120:123], v2, s[6:7] offset:2048
	global_load_dwordx4 v[124:127], v2, s[6:7] offset:2064
	s_add_u32 s6, s6, 0x1000
	s_addc_u32 s7, s7, 0
	s_waitcnt vmcnt(28)
; __device__ __forceinline__ unsigned cvt_pk_bf16(float lo, float hi) { unsigned r; asm("v_cvt_pk_bf16_f32 %0, %1, %2" : "=v"(r) : "v"(lo), "v"(hi)); return r; }
; __device__ __forceinline__ void norm_pass(const Ctx& X, const float* xs, const float* cs, int nrows, const float* gain, const float* modl, int si, bf16_t* HN) {
;     ...
;         f32x4 v[4]; float s = 0.f;
; #pragma unroll
;         for (int j = 0; j < 4; ++j) { v[j] = *(const f32x4*)(row + (X.lane + 64 * j) * 4); s += (v[j].x * v[j].x + v[j].y * v[j].y) + (v[j].z * v[j].z + v[j].w * v[j].w); }
;         const float rstd = rsqrtf(wave_sum(s) * (1.0f / 1024.0f) + 1e-6f);
; #pragma unroll
;         for (int j = 0; j < 4; ++j) { const int c = (X.lane + 64 * j) * 4; const f32x4 gn = *(const f32x4*)(gain + c), a = *(const f32x4*)(scl + c), b = *(const f32x4*)(sh + c);
;             const f32x4 o = v[j] * rstd * gn * (a + 1.0f) + b; u32x2 w; w.x = cvt_pk_bf16(o.x, o.y); w.y = cvt_pk_bf16(o.z, o.w); *(u32x2*)(HN + (size_t)r * D + c) = w; }
	v_pk_mul_f32 v[200:201], v[128:129], v[128:129]
	v_pk_fma_f32 v[200:201], v[130:131], v[130:131], v[200:201]
	v_pk_fma_f32 v[200:201], v[132:133], v[132:133], v[200:201]
	v_pk_fma_f32 v[200:201], v[134:135], v[134:135], v[200:201]
	v_pk_fma_f32 v[200:201], v[136:137], v[136:137], v[200:201]
	v_pk_fma_f32 v[200:201], v[138:139], v[138:139], v[200:201]
	v_pk_fma_f32 v[200:201], v[140:141], v[140:141], v[200:201]
	v_pk_fma_f32 v[200:201], v[142:143], v[142:143], v[200:201]
	v_add_f32_e32 v200, v200, v201
	s_nop 1
	v_add_f32_dpp v200, v200, v200 quad_perm:[1,0,3,2] row_mask:0xf bank_mask:0xf
	s_nop 1
	v_add_f32_dpp v200, v200, v200 quad_perm:[2,3,0,1] row_mask:0xf bank_mask:0xf
	s_nop 1
	v_add_f32_dpp v200, v200, v200 row_half_mirror row_mask:0xf bank_mask:0xf
	s_nop 1
	v_add_f32_dpp v200, v200, v200 row_mirror row_mask:0xf bank_mask:0xf
	s_nop 1
	v_mov_b32_e32 v201, v200
	s_nop 1
	v_permlane16_swap_b32_e32 v200, v201
	s_nop 0
	v_add_f32_e32 v200, v200, v201
	v_mov_b32_e32 v201, v200
	s_nop 1
	v_permlane32_swap_b32_e32 v200, v201
	s_nop 0
	v_add_f32_e32 v200, v200, v201
	v_fmamk_f32 v200, v200, 0x3a800000, v3
	v_rsq_f32_e32 v200, v200
	s_nop 0
	v_pk_mul_f32 v[128:129], v[128:129], v[200:201] op_sel_hi:[1,0]
	v_pk_mul_f32 v[130:131], v[130:131], v[200:201] op_sel_hi:[1,0]
	v_pk_mul_f32 v[132:133], v[132:133], v[200:201] op_sel_hi:[1,0]
	v_pk_mul_f32 v[134:135], v[134:135], v[200:201] op_sel_hi:[1,0]
	v_pk_mul_f32 v[136:137], v[136:137], v[200:201] op_sel_hi:[1,0]
	v_pk_mul_f32 v[138:139], v[138:139], v[200:201] op_sel_hi:[1,0]
	v_pk_mul_f32 v[140:141], v[140:141], v[200:201] op_sel_hi:[1,0]
	v_pk_mul_f32 v[142:143], v[142:143], v[200:201] op_sel_hi:[1,0]
	v_pk_mul_f32 v[128:129], v[16:17], v[128:129]
	v_pk_mul_f32 v[130:131], v[18:19], v[130:131]
	v_pk_mul_f32 v[132:133], v[20:21], v[132:133]
	v_pk_mul_f32 v[134:135], v[22:23], v[134:135]
	v_pk_mul_f32 v[136:137], v[24:25], v[136:137]
	v_pk_mul_f32 v[138:139], v[26:27], v[138:139]
	v_pk_mul_f32 v[140:141], v[28:29], v[140:141]
	v_pk_mul_f32 v[142:143], v[30:31], v[142:143]
	v_pk_fma_f32 v[128:129], v[32:33], v[128:129], v[48:49]
	v_pk_fma_f32 v[130:131], v[34:35], v[130:131], v[50:51]
	v_pk_fma_f32 v[132:133], v[36:37], v[132:133], v[52:53]
	v_pk_fma_f32 v[134:135], v[38:39], v[134:135], v[54:55]
	v_pk_fma_f32 v[136:137], v[40:41], v[136:137], v[56:57]
	v_pk_fma_f32 v[138:139], v[42:43], v[138:139], v[58:59]
	v_pk_fma_f32 v[140:141], v[44:45], v[140:141], v[60:61]
	v_pk_fma_f32 v[142:143], v[46:47], v[142:143], v[62:63]
	v_cvt_pk_bf16_f32 v192, v128, v129
	v_cvt_pk_bf16_f32 v193, v130, v131
	v_cvt_pk_bf16_f32 v194, v132, v133
	v_cvt_pk_bf16_f32 v195, v134, v135
	v_cvt_pk_bf16_f32 v196, v136, v137
	v_cvt_pk_bf16_f32 v197, v138, v139
	v_cvt_pk_bf16_f32 v198, v140, v141
	v_cvt_pk_bf16_f32 v199, v142, v143
	global_store_dwordx4 v1, v[192:195], s[8:9]
	global_store_dwordx4 v1, v[196:199], s[8:9] offset:1024
	global_load_dwordx4 v[128:131], v2, s[6:7]
	global_load_dwordx4 v[132:135], v2, s[6:7] offset:16
	global_load_dwordx4 v[136:139], v2, s[6:7] offset:2048
	global_load_dwordx4 v[140:143], v2, s[6:7] offset:2064
	s_add_u32 s6, s6, 0x1000
	s_addc_u32 s7, s7, 0
	s_waitcnt vmcnt(30)
	v_pk_mul_f32 v[200:201], v[144:145], v[144:145]
	v_pk_fma_f32 v[200:201], v[146:147], v[146:147], v[200:201]
	v_pk_fma_f32 v[200:201], v[148:149], v[148:149], v[200:201]
	v_pk_fma_f32 v[200:201], v[150:151], v[150:151], v[200:201]
	v_pk_fma_f32 v[200:201], v[152:153], v[152:153], v[200:201]
	v_pk_fma_f32 v[200:201], v[154:155], v[154:155], v[200:201]
	v_pk_fma_f32 v[200:201], v[156:157], v[156:157], v[200:201]
	v_pk_fma_f32 v[200:201], v[158:159], v[158:159], v[200:201]
	v_add_f32_e32 v200, v200, v201
	s_nop 1
	v_add_f32_dpp v200, v200, v200 quad_perm:[1,0,3,2] row_mask:0xf bank_mask:0xf
	s_nop 1
	v_add_f32_dpp v200, v200, v200 quad_perm:[2,3,0,1] row_mask:0xf bank_mask:0xf
	s_nop 1
	v_add_f32_dpp v200, v200, v200 row_half_mirror row_mask:0xf bank_mask:0xf
	s_nop 1
	v_add_f32_dpp v200, v200, v200 row_mirror row_mask:0xf bank_mask:0xf
	s_nop 1
	v_mov_b32_e32 v201, v200
	s_nop 1
	v_permlane16_swap_b32_e32 v200, v201
	s_nop 0
	v_add_f32_e32 v200, v200, v201
	v_mov_b32_e32 v201, v200
	s_nop 1
	v_permlane32_swap_b32_e32 v200, v201
	s_nop 0
	v_add_f32_e32 v200, v200, v201
	v_fmamk_f32 v200, v200, 0x3a800000, v3
	v_rsq_f32_e32 v200, v200
	s_nop 0
	v_pk_mul_f32 v[144:145], v[144:145], v[200:201] op_sel_hi:[1,0]
	v_pk_mul_f32 v[146:147], v[146:147], v[200:201] op_sel_hi:[1,0]
	v_pk_mul_f32 v[148:149], v[148:149], v[200:201] op_sel_hi:[1,0]
	v_pk_mul_f32 v[150:151], v[150:151], v[200:201] op_sel_hi:[1,0]
	v_pk_mul_f32 v[152:153], v[152:153], v[200:201] op_sel_hi:[1,0]
	v_pk_mul_f32 v[154:155], v[154:155], v[200:201] op_sel_hi:[1,0]
	v_pk_mul_f32 v[156:157], v[156:157], v[200:201] op_sel_hi:[1,0]
	v_pk_mul_f32 v[158:159], v[158:159], v[200:201] op_sel_hi:[1,0]
	v_pk_mul_f32 v[144:145], v[16:17], v[144:145]
	v_pk_mul_f32 v[146:147], v[18:19], v[146:147]
	v_pk_mul_f32 v[148:149], v[20:21], v[148:149]
	v_pk_mul_f32 v[150:151], v[22:23], v[150:151]
	v_pk_mul_f32 v[152:153], v[24:25], v[152:153]
	v_pk_mul_f32 v[154:155], v[26:27], v[154:155]
	v_pk_mul_f32 v[156:157], v[28:29], v[156:157]
	v_pk_mul_f32 v[158:159], v[30:31], v[158:159]
	v_pk_fma_f32 v[144:145], v[32:33], v[144:145], v[48:49]
	v_pk_fma_f32 v[146:147], v[34:35], v[146:147], v[50:51]
	v_pk_fma_f32 v[148:149], v[36:37], v[148:149], v[52:53]
	v_pk_fma_f32 v[150:151], v[38:39], v[150:151], v[54:55]
	v_pk_fma_f32 v[152:153], v[40:41], v[152:153], v[56:57]
	v_pk_fma_f32 v[154:155], v[42:43], v[154:155], v[58:59]
	v_pk_fma_f32 v[156:157], v[44:45], v[156:157], v[60:61]
	v_pk_fma_f32 v[158:159], v[46:47], v[158:159], v[62:63]
	v_cvt_pk_bf16_f32 v192, v144, v145
	v_cvt_pk_bf16_f32 v193, v146, v147
	v_cvt_pk_bf16_f32 v194, v148, v149
	v_cvt_pk_bf16_f32 v195, v150, v151
	v_cvt_pk_bf16_f32 v196, v152, v153
	v_cvt_pk_bf16_f32 v197, v154, v155
	v_cvt_pk_bf16_f32 v198, v156, v157
	v_cvt_pk_bf16_f32 v199, v158, v159
	global_store_dwordx4 v1, v[192:195], s[8:9] offset:2048
	global_store_dwordx4 v1, v[196:199], s[8:9] offset:3072
	s_add_u32 s8, s8, 0x1000
	s_addc_u32 s9, s9, 0
	global_load_dwordx4 v[144:147], v2, s[6:7]
	global_load_dwordx4 v[148:151], v2, s[6:7] offset:16
	global_load_dwordx4 v[152:155], v2, s[6:7] offset:2048
	global_load_dwordx4 v[156:159], v2, s[6:7] offset:2064
	s_add_u32 s6, s6, 0x1000
	s_addc_u32 s7, s7, 0
	s_waitcnt vmcnt(30)
; __device__ __forceinline__ unsigned cvt_pk_bf16(float lo, float hi) { unsigned r; asm("v_cvt_pk_bf16_f32 %0, %1, %2" : "=v"(r) : "v"(lo), "v"(hi)); return r; }
; __device__ __forceinline__ void norm_pass(const Ctx& X, const float* xs, const float* cs, int nrows, const float* gain, const float* modl, int si, bf16_t* HN) {
;     ...
;         f32x4 v[4]; float s = 0.f;
; #pragma unroll
;         for (int j = 0; j < 4; ++j) { v[j] = *(const f32x4*)(row + (X.lane + 64 * j) * 4); s += (v[j].x * v[j].x + v[j].y * v[j].y) + (v[j].z * v[j].z + v[j].w * v[j].w); }
;         const float rstd = rsqrtf(wave_sum(s) * (1.0f / 1024.0f) + 1e-6f);
; #pragma unroll
;         for (int j = 0; j < 4; ++j) { const int c = (X.lane + 64 * j) * 4; const f32x4 gn = *(const f32x4*)(gain + c), a = *(const f32x4*)(scl + c), b = *(const f32x4*)(sh + c);
;             const f32x4 o = v[j] * rstd * gn * (a + 1.0f) + b; u32x2 w; w.x = cvt_pk_bf16(o.x, o.y); w.y = cvt_pk_bf16(o.z, o.w); *(u32x2*)(HN + (size_t)r * D + c) = w; }
	v_pk_mul_f32 v[200:201], v[64:65], v[64:65]
	v_pk_fma_f32 v[200:201], v[66:67], v[66:67], v[200:201]
	v_pk_fma_f32 v[200:201], v[68:69], v[68:69], v[200:201]
	v_pk_fma_f32 v[200:201], v[70:71], v[70:71], v[200:201]
	v_pk_fma_f32 v[200:201], v[72:73], v[72:73], v[200:201]
	v_pk_fma_f32 v[200:201], v[74:75], v[74:75], v[200:201]
	v_pk_fma_f32 v[200:201], v[76:77], v[76:77], v[200:201]
	v_pk_fma_f32 v[200:201], v[78:79], v[78:79], v[200:201]
	v_add_f32_e32 v200, v200, v201
	s_nop 1
	v_add_f32_dpp v200, v200, v200 quad_perm:[1,0,3,2] row_mask:0xf bank_mask:0xf
	s_nop 1
	v_add_f32_dpp v200, v200, v200 quad_perm:[2,3,0,1] row_mask:0xf bank_mask:0xf
	s_nop 1
	v_add_f32_dpp v200, v200, v200 row_half_mirror row_mask:0xf bank_mask:0xf
	s_nop 1
	v_add_f32_dpp v200, v200, v200 row_mirror row_mask:0xf bank_mask:0xf
	s_nop 1
	v_mov_b32_e32 v201, v200
	s_nop 1
	v_permlane16_swap_b32_e32 v200, v201
	s_nop 0
	v_add_f32_e32 v200, v200, v201
	v_mov_b32_e32 v201, v200
	s_nop 1
	v_permlane32_swap_b32_e32 v200, v201
	s_nop 0
	v_add_f32_e32 v200, v200, v201
	v_fmamk_f32 v200, v200, 0x3a800000, v3
	v_rsq_f32_e32 v200, v200
	s_nop 0
	v_pk_mul_f32 v[64:65], v[64:65], v[200:201] op_sel_hi:[1,0]
	v_pk_mul_f32 v[66:67], v[66:67], v[200:201] op_sel_hi:[1,0]
	v_pk_mul_f32 v[68:69], v[68:69], v[200:201] op_sel_hi:[1,0]
	v_pk_mul_f32 v[70:71], v[70:71], v[200:201] op_sel_hi:[1,0]
	v_pk_mul_f32 v[72:73], v[72:73], v[200:201] op_sel_hi:[1,0]
	v_pk_mul_f32 v[74:75], v[74:75], v[200:201] op_sel_hi:[1,0]
	v_pk_mul_f32 v[76:77], v[76:77], v[200:201] op_sel_hi:[1,0]
	v_pk_mul_f32 v[78:79], v[78:79], v[200:201] op_sel_hi:[1,0]
	v_pk_mul_f32 v[64:65], v[16:17], v[64:65]
	v_pk_mul_f32 v[66:67], v[18:19], v[66:67]
	v_pk_mul_f32 v[68:69], v[20:21], v[68:69]
	v_pk_mul_f32 v[70:71], v[22:23], v[70:71]
	v_pk_mul_f32 v[72:73], v[24:25], v[72:73]
	v_pk_mul_f32 v[74:75], v[26:27], v[74:75]
	v_pk_mul_f32 v[76:77], v[28:29], v[76:77]
	v_pk_mul_f32 v[78:79], v[30:31], v[78:79]
	v_pk_fma_f32 v[64:65], v[32:33], v[64:65], v[48:49]
	v_pk_fma_f32 v[66:67], v[34:35], v[66:67], v[50:51]
	v_pk_fma_f32 v[68:69], v[36:37], v[68:69], v[52:53]
	v_pk_fma_f32 v[70:71], v[38:39], v[70:71], v[54:55]
	v_pk_fma_f32 v[72:73], v[40:41], v[72:73], v[56:57]
	v_pk_fma_f32 v[74:75], v[42:43], v[74:75], v[58:59]
	v_pk_fma_f32 v[76:77], v[44:45], v[76:77], v[60:61]
	v_pk_fma_f32 v[78:79], v[46:47], v[78:79], v[62:63]
	v_cvt_pk_bf16_f32 v192, v64, v65
	v_cvt_pk_bf16_f32 v193, v66, v67
	v_cvt_pk_bf16_f32 v194, v68, v69
	v_cvt_pk_bf16_f32 v195, v70, v71
	v_cvt_pk_bf16_f32 v196, v72, v73
	v_cvt_pk_bf16_f32 v197, v74, v75
	v_cvt_pk_bf16_f32 v198, v76, v77
	v_cvt_pk_bf16_f32 v199, v78, v79
	global_store_dwordx4 v1, v[192:195], s[8:9]
	global_store_dwordx4 v1, v[196:199], s[8:9] offset:1024
	global_load_dwordx4 v[64:67], v2, s[6:7]
	global_load_dwordx4 v[68:71], v2, s[6:7] offset:16
	global_load_dwordx4 v[72:75], v2, s[6:7] offset:2048
	global_load_dwordx4 v[76:79], v2, s[6:7] offset:2064
	s_add_u32 s6, s6, 0x1000
	s_addc_u32 s7, s7, 0
	s_waitcnt vmcnt(30)
	v_pk_mul_f32 v[200:201], v[80:81], v[80:81]
	v_pk_fma_f32 v[200:201], v[82:83], v[82:83], v[200:201]
	v_pk_fma_f32 v[200:201], v[84:85], v[84:85], v[200:201]
	v_pk_fma_f32 v[200:201], v[86:87], v[86:87], v[200:201]
	v_pk_fma_f32 v[200:201], v[88:89], v[88:89], v[200:201]
	v_pk_fma_f32 v[200:201], v[90:91], v[90:91], v[200:201]
	v_pk_fma_f32 v[200:201], v[92:93], v[92:93], v[200:201]
	v_pk_fma_f32 v[200:201], v[94:95], v[94:95], v[200:201]
	v_add_f32_e32 v200, v200, v201
	s_nop 1
	v_add_f32_dpp v200, v200, v200 quad_perm:[1,0,3,2] row_mask:0xf bank_mask:0xf
	s_nop 1
	v_add_f32_dpp v200, v200, v200 quad_perm:[2,3,0,1] row_mask:0xf bank_mask:0xf
	s_nop 1
	v_add_f32_dpp v200, v200, v200 row_half_mirror row_mask:0xf bank_mask:0xf
	s_nop 1
	v_add_f32_dpp v200, v200, v200 row_mirror row_mask:0xf bank_mask:0xf
	s_nop 1
	v_mov_b32_e32 v201, v200
	s_nop 1
	v_permlane16_swap_b32_e32 v200, v201
	s_nop 0
	v_add_f32_e32 v200, v200, v201
	v_mov_b32_e32 v201, v200
	s_nop 1
	v_permlane32_swap_b32_e32 v200, v201
	s_nop 0
	v_add_f32_e32 v200, v200, v201
	v_fmamk_f32 v200, v200, 0x3a800000, v3
	v_rsq_f32_e32 v200, v200
	s_nop 0
	v_pk_mul_f32 v[80:81], v[80:81], v[200:201] op_sel_hi:[1,0]
	v_pk_mul_f32 v[82:83], v[82:83], v[200:201] op_sel_hi:[1,0]
	v_pk_mul_f32 v[84:85], v[84:85], v[200:201] op_sel_hi:[1,0]
	v_pk_mul_f32 v[86:87], v[86:87], v[200:201] op_sel_hi:[1,0]
	v_pk_mul_f32 v[88:89], v[88:89], v[200:201] op_sel_hi:[1,0]
	v_pk_mul_f32 v[90:91], v[90:91], v[200:201] op_sel_hi:[1,0]
	v_pk_mul_f32 v[92:93], v[92:93], v[200:201] op_sel_hi:[1,0]
	v_pk_mul_f32 v[94:95], v[94:95], v[200:201] op_sel_hi:[1,0]
	v_pk_mul_f32 v[80:81], v[16:17], v[80:81]
	v_pk_mul_f32 v[82:83], v[18:19], v[82:83]
	v_pk_mul_f32 v[84:85], v[20:21], v[84:85]
	v_pk_mul_f32 v[86:87], v[22:23], v[86:87]
	v_pk_mul_f32 v[88:89], v[24:25], v[88:89]
	v_pk_mul_f32 v[90:91], v[26:27], v[90:91]
	v_pk_mul_f32 v[92:93], v[28:29], v[92:93]
	v_pk_mul_f32 v[94:95], v[30:31], v[94:95]
	v_pk_fma_f32 v[80:81], v[32:33], v[80:81], v[48:49]
	v_pk_fma_f32 v[82:83], v[34:35], v[82:83], v[50:51]
	v_pk_fma_f32 v[84:85], v[36:37], v[84:85], v[52:53]
	v_pk_fma_f32 v[86:87], v[38:39], v[86:87], v[54:55]
	v_pk_fma_f32 v[88:89], v[40:41], v[88:89], v[56:57]
	v_pk_fma_f32 v[90:91], v[42:43], v[90:91], v[58:59]
	v_pk_fma_f32 v[92:93], v[44:45], v[92:93], v[60:61]
	v_pk_fma_f32 v[94:95], v[46:47], v[94:95], v[62:63]
	v_cvt_pk_bf16_f32 v192, v80, v81
	v_cvt_pk_bf16_f32 v193, v82, v83
	v_cvt_pk_bf16_f32 v194, v84, v85
	v_cvt_pk_bf16_f32 v195, v86, v87
	v_cvt_pk_bf16_f32 v196, v88, v89
	v_cvt_pk_bf16_f32 v197, v90, v91
	v_cvt_pk_bf16_f32 v198, v92, v93
	v_cvt_pk_bf16_f32 v199, v94, v95
	global_store_dwordx4 v1, v[192:195], s[8:9] offset:2048
	global_store_dwordx4 v1, v[196:199], s[8:9] offset:3072
	s_add_u32 s8, s8, 0x1000
	s_addc_u32 s9, s9, 0
	global_load_dwordx4 v[80:83], v2, s[6:7]
	global_load_dwordx4 v[84:87], v2, s[6:7] offset:16
	global_load_dwordx4 v[88:91], v2, s[6:7] offset:2048
	global_load_dwordx4 v[92:95], v2, s[6:7] offset:2064
	s_add_u32 s6, s6, 0x1000
	s_addc_u32 s7, s7, 0
	s_waitcnt vmcnt(30)
; __device__ __forceinline__ unsigned cvt_pk_bf16(float lo, float hi) { unsigned r; asm("v_cvt_pk_bf16_f32 %0, %1, %2" : "=v"(r) : "v"(lo), "v"(hi)); return r; }
; __device__ __forceinline__ void norm_pass(const Ctx& X, const float* xs, const float* cs, int nrows, const float* gain, const float* modl, int si, bf16_t* HN) {
;     ...
;         f32x4 v[4]; float s = 0.f;
; #pragma unroll
;         for (int j = 0; j < 4; ++j) { v[j] = *(const f32x4*)(row + (X.lane + 64 * j) * 4); s += (v[j].x * v[j].x + v[j].y * v[j].y) + (v[j].z * v[j].z + v[j].w * v[j].w); }
;         const float rstd = rsqrtf(wave_sum(s) * (1.0f / 1024.0f) + 1e-6f);
; #pragma unroll
;         for (int j = 0; j < 4; ++j) { const int c = (X.lane + 64 * j) * 4; const f32x4 gn = *(const f32x4*)(gain + c), a = *(const f32x4*)(scl + c), b = *(const f32x4*)(sh + c);
;             const f32x4 o = v[j] * rstd * gn * (a + 1.0f) + b; u32x2 w; w.x = cvt_pk_bf16(o.x, o.y); w.y = cvt_pk_bf16(o.z, o.w); *(u32x2*)(HN + (size_t)r * D + c) = w; }
	v_pk_mul_f32 v[200:201], v[96:97], v[96:97]
	v_pk_fma_f32 v[200:201], v[98:99], v[98:99], v[200:201]
	v_pk_fma_f32 v[200:201], v[100:101], v[100:101], v[200:201]
	v_pk_fma_f32 v[200:201], v[102:103], v[102:103], v[200:201]
	v_pk_fma_f32 v[200:201], v[104:105], v[104:105], v[200:201]
	v_pk_fma_f32 v[200:201], v[106:107], v[106:107], v[200:201]
	v_pk_fma_f32 v[200:201], v[108:109], v[108:109], v[200:201]
	v_pk_fma_f32 v[200:201], v[110:111], v[110:111], v[200:201]
	v_add_f32_e32 v200, v200, v201
	s_nop 1
	v_add_f32_dpp v200, v200, v200 quad_perm:[1,0,3,2] row_mask:0xf bank_mask:0xf
	s_nop 1
	v_add_f32_dpp v200, v200, v200 quad_perm:[2,3,0,1] row_mask:0xf bank_mask:0xf
	s_nop 1
	v_add_f32_dpp v200, v200, v200 row_half_mirror row_mask:0xf bank_mask:0xf
	s_nop 1
	v_add_f32_dpp v200, v200, v200 row_mirror row_mask:0xf bank_mask:0xf
	s_nop 1
	v_mov_b32_e32 v201, v200
	s_nop 1
	v_permlane16_swap_b32_e32 v200, v201
	s_nop 0
	v_add_f32_e32 v200, v200, v201
	v_mov_b32_e32 v201, v200
	s_nop 1
	v_permlane32_swap_b32_e32 v200, v201
	s_nop 0
	v_add_f32_e32 v200, v200, v201
	v_fmamk_f32 v200, v200, 0x3a800000, v3
	v_rsq_f32_e32 v200, v200
	s_nop 0
	v_pk_mul_f32 v[96:97], v[96:97], v[200:201] op_sel_hi:[1,0]
	v_pk_mul_f32 v[98:99], v[98:99], v[200:201] op_sel_hi:[1,0]
	v_pk_mul_f32 v[100:101], v[100:101], v[200:201] op_sel_hi:[1,0]
	v_pk_mul_f32 v[102:103], v[102:103], v[200:201] op_sel_hi:[1,0]
	v_pk_mul_f32 v[104:105], v[104:105], v[200:201] op_sel_hi:[1,0]
	v_pk_mul_f32 v[106:107], v[106:107], v[200:201] op_sel_hi:[1,0]
	v_pk_mul_f32 v[108:109], v[108:109], v[200:201] op_sel_hi:[1,0]
	v_pk_mul_f32 v[110:111], v[110:111], v[200:201] op_sel_hi:[1,0]
	v_pk_mul_f32 v[96:97], v[16:17], v[96:97]
	v_pk_mul_f32 v[98:99], v[18:19], v[98:99]
	v_pk_mul_f32 v[100:101], v[20:21], v[100:101]
	v_pk_mul_f32 v[102:103], v[22:23], v[102:103]
	v_pk_mul_f32 v[104:105], v[24:25], v[104:105]
	v_pk_mul_f32 v[106:107], v[26:27], v[106:107]
	v_pk_mul_f32 v[108:109], v[28:29], v[108:109]
	v_pk_mul_f32 v[110:111], v[30:31], v[110:111]
	v_pk_fma_f32 v[96:97], v[32:33], v[96:97], v[48:49]
	v_pk_fma_f32 v[98:99], v[34:35], v[98:99], v[50:51]
	v_pk_fma_f32 v[100:101], v[36:37], v[100:101], v[52:53]
	v_pk_fma_f32 v[102:103], v[38:39], v[102:103], v[54:55]
	v_pk_fma_f32 v[104:105], v[40:41], v[104:105], v[56:57]
	v_pk_fma_f32 v[106:107], v[42:43], v[106:107], v[58:59]
	v_pk_fma_f32 v[108:109], v[44:45], v[108:109], v[60:61]
	v_pk_fma_f32 v[110:111], v[46:47], v[110:111], v[62:63]
	v_cvt_pk_bf16_f32 v192, v96, v97
	v_cvt_pk_bf16_f32 v193, v98, v99
	v_cvt_pk_bf16_f32 v194, v100, v101
	v_cvt_pk_bf16_f32 v195, v102, v103
	v_cvt_pk_bf16_f32 v196, v104, v105
	v_cvt_pk_bf16_f32 v197, v106, v107
	v_cvt_pk_bf16_f32 v198, v108, v109
	v_cvt_pk_bf16_f32 v199, v110, v111
	global_store_dwordx4 v1, v[192:195], s[8:9]
	global_store_dwordx4 v1, v[196:199], s[8:9] offset:1024
	global_load_dwordx4 v[96:99], v2, s[6:7]
	global_load_dwordx4 v[100:103], v2, s[6:7] offset:16
	global_load_dwordx4 v[104:107], v2, s[6:7] offset:2048
	global_load_dwordx4 v[108:111], v2, s[6:7] offset:2064
	s_add_u32 s6, s6, 0x1000
	s_addc_u32 s7, s7, 0
	s_waitcnt vmcnt(30)
	v_pk_mul_f32 v[200:201], v[112:113], v[112:113]
	v_pk_fma_f32 v[200:201], v[114:115], v[114:115], v[200:201]
	v_pk_fma_f32 v[200:201], v[116:117], v[116:117], v[200:201]
	v_pk_fma_f32 v[200:201], v[118:119], v[118:119], v[200:201]
	v_pk_fma_f32 v[200:201], v[120:121], v[120:121], v[200:201]
	v_pk_fma_f32 v[200:201], v[122:123], v[122:123], v[200:201]
	v_pk_fma_f32 v[200:201], v[124:125], v[124:125], v[200:201]
	v_pk_fma_f32 v[200:201], v[126:127], v[126:127], v[200:201]
	v_add_f32_e32 v200, v200, v201
	s_nop 1
	v_add_f32_dpp v200, v200, v200 quad_perm:[1,0,3,2] row_mask:0xf bank_mask:0xf
	s_nop 1
	v_add_f32_dpp v200, v200, v200 quad_perm:[2,3,0,1] row_mask:0xf bank_mask:0xf
	s_nop 1
	v_add_f32_dpp v200, v200, v200 row_half_mirror row_mask:0xf bank_mask:0xf
	s_nop 1
	v_add_f32_dpp v200, v200, v200 row_mirror row_mask:0xf bank_mask:0xf
	s_nop 1
	v_mov_b32_e32 v201, v200
	s_nop 1
	v_permlane16_swap_b32_e32 v200, v201
	s_nop 0
	v_add_f32_e32 v200, v200, v201
	v_mov_b32_e32 v201, v200
	s_nop 1
	v_permlane32_swap_b32_e32 v200, v201
	s_nop 0
	v_add_f32_e32 v200, v200, v201
	v_fmamk_f32 v200, v200, 0x3a800000, v3
	v_rsq_f32_e32 v200, v200
	s_nop 0
	v_pk_mul_f32 v[112:113], v[112:113], v[200:201] op_sel_hi:[1,0]
	v_pk_mul_f32 v[114:115], v[114:115], v[200:201] op_sel_hi:[1,0]
	v_pk_mul_f32 v[116:117], v[116:117], v[200:201] op_sel_hi:[1,0]
	v_pk_mul_f32 v[118:119], v[118:119], v[200:201] op_sel_hi:[1,0]
	v_pk_mul_f32 v[120:121], v[120:121], v[200:201] op_sel_hi:[1,0]
	v_pk_mul_f32 v[122:123], v[122:123], v[200:201] op_sel_hi:[1,0]
	v_pk_mul_f32 v[124:125], v[124:125], v[200:201] op_sel_hi:[1,0]
	v_pk_mul_f32 v[126:127], v[126:127], v[200:201] op_sel_hi:[1,0]
	v_pk_mul_f32 v[112:113], v[16:17], v[112:113]
	v_pk_mul_f32 v[114:115], v[18:19], v[114:115]
	v_pk_mul_f32 v[116:117], v[20:21], v[116:117]
	v_pk_mul_f32 v[118:119], v[22:23], v[118:119]
	v_pk_mul_f32 v[120:121], v[24:25], v[120:121]
	v_pk_mul_f32 v[122:123], v[26:27], v[122:123]
	v_pk_mul_f32 v[124:125], v[28:29], v[124:125]
	v_pk_mul_f32 v[126:127], v[30:31], v[126:127]
	v_pk_fma_f32 v[112:113], v[32:33], v[112:113], v[48:49]
	v_pk_fma_f32 v[114:115], v[34:35], v[114:115], v[50:51]
	v_pk_fma_f32 v[116:117], v[36:37], v[116:117], v[52:53]
	v_pk_fma_f32 v[118:119], v[38:39], v[118:119], v[54:55]
	v_pk_fma_f32 v[120:121], v[40:41], v[120:121], v[56:57]
	v_pk_fma_f32 v[122:123], v[42:43], v[122:123], v[58:59]
	v_pk_fma_f32 v[124:125], v[44:45], v[124:125], v[60:61]
	v_pk_fma_f32 v[126:127], v[46:47], v[126:127], v[62:63]
	v_cvt_pk_bf16_f32 v192, v112, v113
	v_cvt_pk_bf16_f32 v193, v114, v115
	v_cvt_pk_bf16_f32 v194, v116, v117
	v_cvt_pk_bf16_f32 v195, v118, v119
	v_cvt_pk_bf16_f32 v196, v120, v121
	v_cvt_pk_bf16_f32 v197, v122, v123
	v_cvt_pk_bf16_f32 v198, v124, v125
	v_cvt_pk_bf16_f32 v199, v126, v127
	global_store_dwordx4 v1, v[192:195], s[8:9] offset:2048
	global_store_dwordx4 v1, v[196:199], s[8:9] offset:3072
	s_add_u32 s8, s8, 0x1000
	s_addc_u32 s9, s9, 0
	global_load_dwordx4 v[112:115], v2, s[6:7]
	global_load_dwordx4 v[116:119], v2, s[6:7] offset:16
	global_load_dwordx4 v[120:123], v2, s[6:7] offset:2048
	global_load_dwordx4 v[124:127], v2, s[6:7] offset:2064
	s_add_u32 s6, s6, 0x1000
	s_addc_u32 s7, s7, 0
	s_waitcnt vmcnt(30)
; __device__ __forceinline__ unsigned cvt_pk_bf16(float lo, float hi) { unsigned r; asm("v_cvt_pk_bf16_f32 %0, %1, %2" : "=v"(r) : "v"(lo), "v"(hi)); return r; }
; __device__ __forceinline__ void norm_pass(const Ctx& X, const float* xs, const float* cs, int nrows, const float* gain, const float* modl, int si, bf16_t* HN) {
;     ...
;         const float* row = r < MX ? xs + (size_t)r * D : cs + (size_t)(r - MX) * D;
;         const int mb = r < MX ? (r >> 12) : 8;
;         const float* sh = modl + (size_t)mb * 9216 + si * 1024; const float* scl = sh + 1024;
;         f32x4 v[4]; float s = 0.f;
; #pragma unroll
;         for (int j = 0; j < 4; ++j) { v[j] = *(const f32x4*)(row + (X.lane + 64 * j) * 4); s += (v[j].x * v[j].x + v[j].y * v[j].y) + (v[j].z * v[j].z + v[j].w * v[j].w); }
;         const float rstd = rsqrtf(wave_sum(s) * (1.0f / 1024.0f) + 1e-6f);
; #pragma unroll
;         for (int j = 0; j < 4; ++j) { const int c = (X.lane + 64 * j) * 4; const f32x4 gn = *(const f32x4*)(gain + c), a = *(const f32x4*)(scl + c), b = *(const f32x4*)(sh + c);
;             const f32x4 o = v[j] * rstd * gn * (a + 1.0f) + b; u32x2 w; w.x = cvt_pk_bf16(o.x, o.y); w.y = cvt_pk_bf16(o.z, o.w); *(u32x2*)(HN + (size_t)r * D + c) = w; }
	v_pk_mul_f32 v[200:201], v[128:129], v[128:129]
	v_pk_fma_f32 v[200:201], v[130:131], v[130:131], v[200:201]
	v_pk_fma_f32 v[200:201], v[132:133], v[132:133], v[200:201]
	v_pk_fma_f32 v[200:201], v[134:135], v[134:135], v[200:201]
	v_pk_fma_f32 v[200:201], v[136:137], v[136:137], v[200:201]
	v_pk_fma_f32 v[200:201], v[138:139], v[138:139], v[200:201]
	v_pk_fma_f32 v[200:201], v[140:141], v[140:141], v[200:201]
	v_pk_fma_f32 v[200:201], v[142:143], v[142:143], v[200:201]
	v_add_f32_e32 v200, v200, v201
	s_nop 1
	v_add_f32_dpp v200, v200, v200 quad_perm:[1,0,3,2] row_mask:0xf bank_mask:0xf
	s_nop 1
	v_add_f32_dpp v200, v200, v200 quad_perm:[2,3,0,1] row_mask:0xf bank_mask:0xf
	s_nop 1
	v_add_f32_dpp v200, v200, v200 row_half_mirror row_mask:0xf bank_mask:0xf
	s_nop 1
	v_add_f32_dpp v200, v200, v200 row_mirror row_mask:0xf bank_mask:0xf
	s_nop 1
	v_mov_b32_e32 v201, v200
	s_nop 1
	v_permlane16_swap_b32_e32 v200, v201
	s_nop 0
	v_add_f32_e32 v200, v200, v201
	v_mov_b32_e32 v201, v200
	s_nop 1
	v_permlane32_swap_b32_e32 v200, v201
	s_nop 0
	v_add_f32_e32 v200, v200, v201
	v_fmamk_f32 v200, v200, 0x3a800000, v3
	v_rsq_f32_e32 v200, v200
	s_nop 0
	v_pk_mul_f32 v[128:129], v[128:129], v[200:201] op_sel_hi:[1,0]
	v_pk_mul_f32 v[130:131], v[130:131], v[200:201] op_sel_hi:[1,0]
	v_pk_mul_f32 v[132:133], v[132:133], v[200:201] op_sel_hi:[1,0]
	v_pk_mul_f32 v[134:135], v[134:135], v[200:201] op_sel_hi:[1,0]
	v_pk_mul_f32 v[136:137], v[136:137], v[200:201] op_sel_hi:[1,0]
	v_pk_mul_f32 v[138:139], v[138:139], v[200:201] op_sel_hi:[1,0]
	v_pk_mul_f32 v[140:141], v[140:141], v[200:201] op_sel_hi:[1,0]
	v_pk_mul_f32 v[142:143], v[142:143], v[200:201] op_sel_hi:[1,0]
	v_pk_mul_f32 v[128:129], v[16:17], v[128:129]
	v_pk_mul_f32 v[130:131], v[18:19], v[130:131]
	v_pk_mul_f32 v[132:133], v[20:21], v[132:133]
	v_pk_mul_f32 v[134:135], v[22:23], v[134:135]
	v_pk_mul_f32 v[136:137], v[24:25], v[136:137]
	v_pk_mul_f32 v[138:139], v[26:27], v[138:139]
	v_pk_mul_f32 v[140:141], v[28:29], v[140:141]
	v_pk_mul_f32 v[142:143], v[30:31], v[142:143]
	v_pk_fma_f32 v[128:129], v[32:33], v[128:129], v[48:49]
	v_pk_fma_f32 v[130:131], v[34:35], v[130:131], v[50:51]
	v_pk_fma_f32 v[132:133], v[36:37], v[132:133], v[52:53]
	v_pk_fma_f32 v[134:135], v[38:39], v[134:135], v[54:55]
	v_pk_fma_f32 v[136:137], v[40:41], v[136:137], v[56:57]
	v_pk_fma_f32 v[138:139], v[42:43], v[138:139], v[58:59]
	v_pk_fma_f32 v[140:141], v[44:45], v[140:141], v[60:61]
	v_pk_fma_f32 v[142:143], v[46:47], v[142:143], v[62:63]
	v_cvt_pk_bf16_f32 v192, v128, v129
	v_cvt_pk_bf16_f32 v193, v130, v131
	v_cvt_pk_bf16_f32 v194, v132, v133
	v_cvt_pk_bf16_f32 v195, v134, v135
	v_cvt_pk_bf16_f32 v196, v136, v137
	v_cvt_pk_bf16_f32 v197, v138, v139
	v_cvt_pk_bf16_f32 v198, v140, v141
	v_cvt_pk_bf16_f32 v199, v142, v143
	global_store_dwordx4 v1, v[192:195], s[8:9]
	global_store_dwordx4 v1, v[196:199], s[8:9] offset:1024
	global_load_dwordx4 v[128:131], v2, s[10:11]
	global_load_dwordx4 v[132:135], v2, s[10:11] offset:16
	global_load_dwordx4 v[136:139], v2, s[10:11] offset:2048
	global_load_dwordx4 v[140:143], v2, s[10:11] offset:2064
	s_waitcnt vmcnt(30)
	v_pk_mul_f32 v[200:201], v[144:145], v[144:145]
	v_pk_fma_f32 v[200:201], v[146:147], v[146:147], v[200:201]
	v_pk_fma_f32 v[200:201], v[148:149], v[148:149], v[200:201]
	v_pk_fma_f32 v[200:201], v[150:151], v[150:151], v[200:201]
	v_pk_fma_f32 v[200:201], v[152:153], v[152:153], v[200:201]
	v_pk_fma_f32 v[200:201], v[154:155], v[154:155], v[200:201]
	v_pk_fma_f32 v[200:201], v[156:157], v[156:157], v[200:201]
	v_pk_fma_f32 v[200:201], v[158:159], v[158:159], v[200:201]
	v_add_f32_e32 v200, v200, v201
	s_nop 1
	v_add_f32_dpp v200, v200, v200 quad_perm:[1,0,3,2] row_mask:0xf bank_mask:0xf
	s_nop 1
	v_add_f32_dpp v200, v200, v200 quad_perm:[2,3,0,1] row_mask:0xf bank_mask:0xf
	s_nop 1
	v_add_f32_dpp v200, v200, v200 row_half_mirror row_mask:0xf bank_mask:0xf
	s_nop 1
	v_add_f32_dpp v200, v200, v200 row_mirror row_mask:0xf bank_mask:0xf
	s_nop 1
	v_mov_b32_e32 v201, v200
	s_nop 1
	v_permlane16_swap_b32_e32 v200, v201
	s_nop 0
	v_add_f32_e32 v200, v200, v201
	v_mov_b32_e32 v201, v200
	s_nop 1
	v_permlane32_swap_b32_e32 v200, v201
	s_nop 0
	v_add_f32_e32 v200, v200, v201
	v_fmamk_f32 v200, v200, 0x3a800000, v3
	v_rsq_f32_e32 v200, v200
	s_nop 0
	v_pk_mul_f32 v[144:145], v[144:145], v[200:201] op_sel_hi:[1,0]
	v_pk_mul_f32 v[146:147], v[146:147], v[200:201] op_sel_hi:[1,0]
	v_pk_mul_f32 v[148:149], v[148:149], v[200:201] op_sel_hi:[1,0]
	v_pk_mul_f32 v[150:151], v[150:151], v[200:201] op_sel_hi:[1,0]
	v_pk_mul_f32 v[152:153], v[152:153], v[200:201] op_sel_hi:[1,0]
	v_pk_mul_f32 v[154:155], v[154:155], v[200:201] op_sel_hi:[1,0]
	v_pk_mul_f32 v[156:157], v[156:157], v[200:201] op_sel_hi:[1,0]
	v_pk_mul_f32 v[158:159], v[158:159], v[200:201] op_sel_hi:[1,0]
	v_pk_mul_f32 v[144:145], v[16:17], v[144:145]
	v_pk_mul_f32 v[146:147], v[18:19], v[146:147]
	v_pk_mul_f32 v[148:149], v[20:21], v[148:149]
	v_pk_mul_f32 v[150:151], v[22:23], v[150:151]
	v_pk_mul_f32 v[152:153], v[24:25], v[152:153]
	v_pk_mul_f32 v[154:155], v[26:27], v[154:155]
	v_pk_mul_f32 v[156:157], v[28:29], v[156:157]
	v_pk_mul_f32 v[158:159], v[30:31], v[158:159]
	v_pk_fma_f32 v[144:145], v[32:33], v[144:145], v[48:49]
	v_pk_fma_f32 v[146:147], v[34:35], v[146:147], v[50:51]
	v_pk_fma_f32 v[148:149], v[36:37], v[148:149], v[52:53]
	v_pk_fma_f32 v[150:151], v[38:39], v[150:151], v[54:55]
	v_pk_fma_f32 v[152:153], v[40:41], v[152:153], v[56:57]
	v_pk_fma_f32 v[154:155], v[42:43], v[154:155], v[58:59]
	v_pk_fma_f32 v[156:157], v[44:45], v[156:157], v[60:61]
	v_pk_fma_f32 v[158:159], v[46:47], v[158:159], v[62:63]
	v_cvt_pk_bf16_f32 v192, v144, v145
	v_cvt_pk_bf16_f32 v193, v146, v147
	v_cvt_pk_bf16_f32 v194, v148, v149
	v_cvt_pk_bf16_f32 v195, v150, v151
	v_cvt_pk_bf16_f32 v196, v152, v153
	v_cvt_pk_bf16_f32 v197, v154, v155
	v_cvt_pk_bf16_f32 v198, v156, v157
	v_cvt_pk_bf16_f32 v199, v158, v159
	global_store_dwordx4 v1, v[192:195], s[8:9] offset:2048
	global_store_dwordx4 v1, v[196:199], s[8:9] offset:3072
	s_add_u32 s8, s8, 0x1000
	s_addc_u32 s9, s9, 0
	s_waitcnt vmcnt(26)
; __device__ __forceinline__ unsigned cvt_pk_bf16(float lo, float hi) { unsigned r; asm("v_cvt_pk_bf16_f32 %0, %1, %2" : "=v"(r) : "v"(lo), "v"(hi)); return r; }
; __device__ __forceinline__ void norm_pass(const Ctx& X, const float* xs, const float* cs, int nrows, const float* gain, const float* modl, int si, bf16_t* HN) {
;     ...
;         f32x4 v[4]; float s = 0.f;
; #pragma unroll
;         for (int j = 0; j < 4; ++j) { v[j] = *(const f32x4*)(row + (X.lane + 64 * j) * 4); s += (v[j].x * v[j].x + v[j].y * v[j].y) + (v[j].z * v[j].z + v[j].w * v[j].w); }
;         const float rstd = rsqrtf(wave_sum(s) * (1.0f / 1024.0f) + 1e-6f);
; #pragma unroll
;         for (int j = 0; j < 4; ++j) { const int c = (X.lane + 64 * j) * 4; const f32x4 gn = *(const f32x4*)(gain + c), a = *(const f32x4*)(scl + c), b = *(const f32x4*)(sh + c);
;             const f32x4 o = v[j] * rstd * gn * (a + 1.0f) + b; u32x2 w; w.x = cvt_pk_bf16(o.x, o.y); w.y = cvt_pk_bf16(o.z, o.w); *(u32x2*)(HN + (size_t)r * D + c) = w; }
	v_pk_mul_f32 v[200:201], v[64:65], v[64:65]
	v_pk_fma_f32 v[200:201], v[66:67], v[66:67], v[200:201]
	v_pk_fma_f32 v[200:201], v[68:69], v[68:69], v[200:201]
	v_pk_fma_f32 v[200:201], v[70:71], v[70:71], v[200:201]
	v_pk_fma_f32 v[200:201], v[72:73], v[72:73], v[200:201]
	v_pk_fma_f32 v[200:201], v[74:75], v[74:75], v[200:201]
	v_pk_fma_f32 v[200:201], v[76:77], v[76:77], v[200:201]
	v_pk_fma_f32 v[200:201], v[78:79], v[78:79], v[200:201]
	v_add_f32_e32 v200, v200, v201
	s_nop 1
	v_add_f32_dpp v200, v200, v200 quad_perm:[1,0,3,2] row_mask:0xf bank_mask:0xf
	s_nop 1
	v_add_f32_dpp v200, v200, v200 quad_perm:[2,3,0,1] row_mask:0xf bank_mask:0xf
	s_nop 1
	v_add_f32_dpp v200, v200, v200 row_half_mirror row_mask:0xf bank_mask:0xf
	s_nop 1
	v_add_f32_dpp v200, v200, v200 row_mirror row_mask:0xf bank_mask:0xf
	s_nop 1
	v_mov_b32_e32 v201, v200
	s_nop 1
	v_permlane16_swap_b32_e32 v200, v201
	s_nop 0
	v_add_f32_e32 v200, v200, v201
	v_mov_b32_e32 v201, v200
	s_nop 1
	v_permlane32_swap_b32_e32 v200, v201
	s_nop 0
	v_add_f32_e32 v200, v200, v201
	v_fmamk_f32 v200, v200, 0x3a800000, v3
	v_rsq_f32_e32 v200, v200
	s_nop 0
	v_pk_mul_f32 v[64:65], v[64:65], v[200:201] op_sel_hi:[1,0]
	v_pk_mul_f32 v[66:67], v[66:67], v[200:201] op_sel_hi:[1,0]
	v_pk_mul_f32 v[68:69], v[68:69], v[200:201] op_sel_hi:[1,0]
	v_pk_mul_f32 v[70:71], v[70:71], v[200:201] op_sel_hi:[1,0]
	v_pk_mul_f32 v[72:73], v[72:73], v[200:201] op_sel_hi:[1,0]
	v_pk_mul_f32 v[74:75], v[74:75], v[200:201] op_sel_hi:[1,0]
	v_pk_mul_f32 v[76:77], v[76:77], v[200:201] op_sel_hi:[1,0]
	v_pk_mul_f32 v[78:79], v[78:79], v[200:201] op_sel_hi:[1,0]
	v_pk_mul_f32 v[64:65], v[16:17], v[64:65]
	v_pk_mul_f32 v[66:67], v[18:19], v[66:67]
	v_pk_mul_f32 v[68:69], v[20:21], v[68:69]
	v_pk_mul_f32 v[70:71], v[22:23], v[70:71]
	v_pk_mul_f32 v[72:73], v[24:25], v[72:73]
	v_pk_mul_f32 v[74:75], v[26:27], v[74:75]
	v_pk_mul_f32 v[76:77], v[28:29], v[76:77]
	v_pk_mul_f32 v[78:79], v[30:31], v[78:79]
	v_pk_fma_f32 v[64:65], v[32:33], v[64:65], v[48:49]
	v_pk_fma_f32 v[66:67], v[34:35], v[66:67], v[50:51]
	v_pk_fma_f32 v[68:69], v[36:37], v[68:69], v[52:53]
	v_pk_fma_f32 v[70:71], v[38:39], v[70:71], v[54:55]
	v_pk_fma_f32 v[72:73], v[40:41], v[72:73], v[56:57]
	v_pk_fma_f32 v[74:75], v[42:43], v[74:75], v[58:59]
	v_pk_fma_f32 v[76:77], v[44:45], v[76:77], v[60:61]
	v_pk_fma_f32 v[78:79], v[46:47], v[78:79], v[62:63]
	v_cvt_pk_bf16_f32 v192, v64, v65
	v_cvt_pk_bf16_f32 v193, v66, v67
	v_cvt_pk_bf16_f32 v194, v68, v69
	v_cvt_pk_bf16_f32 v195, v70, v71
	v_cvt_pk_bf16_f32 v196, v72, v73
	v_cvt_pk_bf16_f32 v197, v74, v75
	v_cvt_pk_bf16_f32 v198, v76, v77
	v_cvt_pk_bf16_f32 v199, v78, v79
	global_store_dwordx4 v1, v[192:195], s[8:9]
	global_store_dwordx4 v1, v[196:199], s[8:9] offset:1024
	s_waitcnt vmcnt(22)
	v_pk_mul_f32 v[200:201], v[80:81], v[80:81]
	v_pk_fma_f32 v[200:201], v[82:83], v[82:83], v[200:201]
	v_pk_fma_f32 v[200:201], v[84:85], v[84:85], v[200:201]
	v_pk_fma_f32 v[200:201], v[86:87], v[86:87], v[200:201]
	v_pk_fma_f32 v[200:201], v[88:89], v[88:89], v[200:201]
	v_pk_fma_f32 v[200:201], v[90:91], v[90:91], v[200:201]
	v_pk_fma_f32 v[200:201], v[92:93], v[92:93], v[200:201]
	v_pk_fma_f32 v[200:201], v[94:95], v[94:95], v[200:201]
	v_add_f32_e32 v200, v200, v201
	s_nop 1
	v_add_f32_dpp v200, v200, v200 quad_perm:[1,0,3,2] row_mask:0xf bank_mask:0xf
	s_nop 1
	v_add_f32_dpp v200, v200, v200 quad_perm:[2,3,0,1] row_mask:0xf bank_mask:0xf
	s_nop 1
	v_add_f32_dpp v200, v200, v200 row_half_mirror row_mask:0xf bank_mask:0xf
	s_nop 1
	v_add_f32_dpp v200, v200, v200 row_mirror row_mask:0xf bank_mask:0xf
	s_nop 1
	v_mov_b32_e32 v201, v200
	s_nop 1
	v_permlane16_swap_b32_e32 v200, v201
	s_nop 0
	v_add_f32_e32 v200, v200, v201
	v_mov_b32_e32 v201, v200
	s_nop 1
	v_permlane32_swap_b32_e32 v200, v201
	s_nop 0
	v_add_f32_e32 v200, v200, v201
	v_fmamk_f32 v200, v200, 0x3a800000, v3
	v_rsq_f32_e32 v200, v200
	s_nop 0
	v_pk_mul_f32 v[80:81], v[80:81], v[200:201] op_sel_hi:[1,0]
	v_pk_mul_f32 v[82:83], v[82:83], v[200:201] op_sel_hi:[1,0]
	v_pk_mul_f32 v[84:85], v[84:85], v[200:201] op_sel_hi:[1,0]
	v_pk_mul_f32 v[86:87], v[86:87], v[200:201] op_sel_hi:[1,0]
	v_pk_mul_f32 v[88:89], v[88:89], v[200:201] op_sel_hi:[1,0]
	v_pk_mul_f32 v[90:91], v[90:91], v[200:201] op_sel_hi:[1,0]
	v_pk_mul_f32 v[92:93], v[92:93], v[200:201] op_sel_hi:[1,0]
	v_pk_mul_f32 v[94:95], v[94:95], v[200:201] op_sel_hi:[1,0]
	v_pk_mul_f32 v[80:81], v[16:17], v[80:81]
	v_pk_mul_f32 v[82:83], v[18:19], v[82:83]
	v_pk_mul_f32 v[84:85], v[20:21], v[84:85]
	v_pk_mul_f32 v[86:87], v[22:23], v[86:87]
	v_pk_mul_f32 v[88:89], v[24:25], v[88:89]
	v_pk_mul_f32 v[90:91], v[26:27], v[90:91]
	v_pk_mul_f32 v[92:93], v[28:29], v[92:93]
	v_pk_mul_f32 v[94:95], v[30:31], v[94:95]
	v_pk_fma_f32 v[80:81], v[32:33], v[80:81], v[48:49]
	v_pk_fma_f32 v[82:83], v[34:35], v[82:83], v[50:51]
	v_pk_fma_f32 v[84:85], v[36:37], v[84:85], v[52:53]
	v_pk_fma_f32 v[86:87], v[38:39], v[86:87], v[54:55]
	v_pk_fma_f32 v[88:89], v[40:41], v[88:89], v[56:57]
	v_pk_fma_f32 v[90:91], v[42:43], v[90:91], v[58:59]
	v_pk_fma_f32 v[92:93], v[44:45], v[92:93], v[60:61]
	v_pk_fma_f32 v[94:95], v[46:47], v[94:95], v[62:63]
	v_cvt_pk_bf16_f32 v192, v80, v81
	v_cvt_pk_bf16_f32 v193, v82, v83
	v_cvt_pk_bf16_f32 v194, v84, v85
	v_cvt_pk_bf16_f32 v195, v86, v87
	v_cvt_pk_bf16_f32 v196, v88, v89
	v_cvt_pk_bf16_f32 v197, v90, v91
	v_cvt_pk_bf16_f32 v198, v92, v93
	v_cvt_pk_bf16_f32 v199, v94, v95
	global_store_dwordx4 v1, v[192:195], s[8:9] offset:2048
	global_store_dwordx4 v1, v[196:199], s[8:9] offset:3072
	s_add_u32 s8, s8, 0x1000
	s_addc_u32 s9, s9, 0
	s_waitcnt vmcnt(18)
; __device__ __forceinline__ unsigned cvt_pk_bf16(float lo, float hi) { unsigned r; asm("v_cvt_pk_bf16_f32 %0, %1, %2" : "=v"(r) : "v"(lo), "v"(hi)); return r; }
; __device__ __forceinline__ void norm_pass(const Ctx& X, const float* xs, const float* cs, int nrows, const float* gain, const float* modl, int si, bf16_t* HN) {
;     ...
;         f32x4 v[4]; float s = 0.f;
; #pragma unroll
;         for (int j = 0; j < 4; ++j) { v[j] = *(const f32x4*)(row + (X.lane + 64 * j) * 4); s += (v[j].x * v[j].x + v[j].y * v[j].y) + (v[j].z * v[j].z + v[j].w * v[j].w); }
;         const float rstd = rsqrtf(wave_sum(s) * (1.0f / 1024.0f) + 1e-6f);
; #pragma unroll
;         for (int j = 0; j < 4; ++j) { const int c = (X.lane + 64 * j) * 4; const f32x4 gn = *(const f32x4*)(gain + c), a = *(const f32x4*)(scl + c), b = *(const f32x4*)(sh + c);
;             const f32x4 o = v[j] * rstd * gn * (a + 1.0f) + b; u32x2 w; w.x = cvt_pk_bf16(o.x, o.y); w.y = cvt_pk_bf16(o.z, o.w); *(u32x2*)(HN + (size_t)r * D + c) = w; }
	v_pk_mul_f32 v[200:201], v[96:97], v[96:97]
	v_pk_fma_f32 v[200:201], v[98:99], v[98:99], v[200:201]
	v_pk_fma_f32 v[200:201], v[100:101], v[100:101], v[200:201]
	v_pk_fma_f32 v[200:201], v[102:103], v[102:103], v[200:201]
	v_pk_fma_f32 v[200:201], v[104:105], v[104:105], v[200:201]
	v_pk_fma_f32 v[200:201], v[106:107], v[106:107], v[200:201]
	v_pk_fma_f32 v[200:201], v[108:109], v[108:109], v[200:201]
	v_pk_fma_f32 v[200:201], v[110:111], v[110:111], v[200:201]
	v_add_f32_e32 v200, v200, v201
	s_nop 1
	v_add_f32_dpp v200, v200, v200 quad_perm:[1,0,3,2] row_mask:0xf bank_mask:0xf
	s_nop 1
	v_add_f32_dpp v200, v200, v200 quad_perm:[2,3,0,1] row_mask:0xf bank_mask:0xf
	s_nop 1
	v_add_f32_dpp v200, v200, v200 row_half_mirror row_mask:0xf bank_mask:0xf
	s_nop 1
	v_add_f32_dpp v200, v200, v200 row_mirror row_mask:0xf bank_mask:0xf
	s_nop 1
	v_mov_b32_e32 v201, v200
	s_nop 1
	v_permlane16_swap_b32_e32 v200, v201
	s_nop 0
	v_add_f32_e32 v200, v200, v201
	v_mov_b32_e32 v201, v200
	s_nop 1
	v_permlane32_swap_b32_e32 v200, v201
	s_nop 0
	v_add_f32_e32 v200, v200, v201
	v_fmamk_f32 v200, v200, 0x3a800000, v3
	v_rsq_f32_e32 v200, v200
	s_nop 0
	v_pk_mul_f32 v[96:97], v[96:97], v[200:201] op_sel_hi:[1,0]
	v_pk_mul_f32 v[98:99], v[98:99], v[200:201] op_sel_hi:[1,0]
	v_pk_mul_f32 v[100:101], v[100:101], v[200:201] op_sel_hi:[1,0]
	v_pk_mul_f32 v[102:103], v[102:103], v[200:201] op_sel_hi:[1,0]
	v_pk_mul_f32 v[104:105], v[104:105], v[200:201] op_sel_hi:[1,0]
	v_pk_mul_f32 v[106:107], v[106:107], v[200:201] op_sel_hi:[1,0]
	v_pk_mul_f32 v[108:109], v[108:109], v[200:201] op_sel_hi:[1,0]
	v_pk_mul_f32 v[110:111], v[110:111], v[200:201] op_sel_hi:[1,0]
	v_pk_mul_f32 v[96:97], v[16:17], v[96:97]
	v_pk_mul_f32 v[98:99], v[18:19], v[98:99]
	v_pk_mul_f32 v[100:101], v[20:21], v[100:101]
	v_pk_mul_f32 v[102:103], v[22:23], v[102:103]
	v_pk_mul_f32 v[104:105], v[24:25], v[104:105]
	v_pk_mul_f32 v[106:107], v[26:27], v[106:107]
	v_pk_mul_f32 v[108:109], v[28:29], v[108:109]
	v_pk_mul_f32 v[110:111], v[30:31], v[110:111]
	v_pk_fma_f32 v[96:97], v[32:33], v[96:97], v[48:49]
	v_pk_fma_f32 v[98:99], v[34:35], v[98:99], v[50:51]
	v_pk_fma_f32 v[100:101], v[36:37], v[100:101], v[52:53]
	v_pk_fma_f32 v[102:103], v[38:39], v[102:103], v[54:55]
	v_pk_fma_f32 v[104:105], v[40:41], v[104:105], v[56:57]
	v_pk_fma_f32 v[106:107], v[42:43], v[106:107], v[58:59]
	v_pk_fma_f32 v[108:109], v[44:45], v[108:109], v[60:61]
	v_pk_fma_f32 v[110:111], v[46:47], v[110:111], v[62:63]
	v_cvt_pk_bf16_f32 v192, v96, v97
	v_cvt_pk_bf16_f32 v193, v98, v99
	v_cvt_pk_bf16_f32 v194, v100, v101
	v_cvt_pk_bf16_f32 v195, v102, v103
	v_cvt_pk_bf16_f32 v196, v104, v105
	v_cvt_pk_bf16_f32 v197, v106, v107
	v_cvt_pk_bf16_f32 v198, v108, v109
	v_cvt_pk_bf16_f32 v199, v110, v111
	global_store_dwordx4 v1, v[192:195], s[8:9]
	global_store_dwordx4 v1, v[196:199], s[8:9] offset:1024
	s_waitcnt vmcnt(14)
	v_pk_mul_f32 v[200:201], v[112:113], v[112:113]
	v_pk_fma_f32 v[200:201], v[114:115], v[114:115], v[200:201]
	v_pk_fma_f32 v[200:201], v[116:117], v[116:117], v[200:201]
	v_pk_fma_f32 v[200:201], v[118:119], v[118:119], v[200:201]
	v_pk_fma_f32 v[200:201], v[120:121], v[120:121], v[200:201]
	v_pk_fma_f32 v[200:201], v[122:123], v[122:123], v[200:201]
	v_pk_fma_f32 v[200:201], v[124:125], v[124:125], v[200:201]
	v_pk_fma_f32 v[200:201], v[126:127], v[126:127], v[200:201]
	v_add_f32_e32 v200, v200, v201
	s_nop 1
	v_add_f32_dpp v200, v200, v200 quad_perm:[1,0,3,2] row_mask:0xf bank_mask:0xf
	s_nop 1
	v_add_f32_dpp v200, v200, v200 quad_perm:[2,3,0,1] row_mask:0xf bank_mask:0xf
	s_nop 1
	v_add_f32_dpp v200, v200, v200 row_half_mirror row_mask:0xf bank_mask:0xf
	s_nop 1
	v_add_f32_dpp v200, v200, v200 row_mirror row_mask:0xf bank_mask:0xf
	s_nop 1
	v_mov_b32_e32 v201, v200
	s_nop 1
	v_permlane16_swap_b32_e32 v200, v201
	s_nop 0
	v_add_f32_e32 v200, v200, v201
	v_mov_b32_e32 v201, v200
	s_nop 1
	v_permlane32_swap_b32_e32 v200, v201
	s_nop 0
	v_add_f32_e32 v200, v200, v201
	v_fmamk_f32 v200, v200, 0x3a800000, v3
	v_rsq_f32_e32 v200, v200
	s_nop 0
	v_pk_mul_f32 v[112:113], v[112:113], v[200:201] op_sel_hi:[1,0]
	v_pk_mul_f32 v[114:115], v[114:115], v[200:201] op_sel_hi:[1,0]
	v_pk_mul_f32 v[116:117], v[116:117], v[200:201] op_sel_hi:[1,0]
	v_pk_mul_f32 v[118:119], v[118:119], v[200:201] op_sel_hi:[1,0]
	v_pk_mul_f32 v[120:121], v[120:121], v[200:201] op_sel_hi:[1,0]
	v_pk_mul_f32 v[122:123], v[122:123], v[200:201] op_sel_hi:[1,0]
	v_pk_mul_f32 v[124:125], v[124:125], v[200:201] op_sel_hi:[1,0]
	v_pk_mul_f32 v[126:127], v[126:127], v[200:201] op_sel_hi:[1,0]
	v_pk_mul_f32 v[112:113], v[16:17], v[112:113]
	v_pk_mul_f32 v[114:115], v[18:19], v[114:115]
	v_pk_mul_f32 v[116:117], v[20:21], v[116:117]
	v_pk_mul_f32 v[118:119], v[22:23], v[118:119]
	v_pk_mul_f32 v[120:121], v[24:25], v[120:121]
	v_pk_mul_f32 v[122:123], v[26:27], v[122:123]
	v_pk_mul_f32 v[124:125], v[28:29], v[124:125]
	v_pk_mul_f32 v[126:127], v[30:31], v[126:127]
	v_pk_fma_f32 v[112:113], v[32:33], v[112:113], v[48:49]
	v_pk_fma_f32 v[114:115], v[34:35], v[114:115], v[50:51]
	v_pk_fma_f32 v[116:117], v[36:37], v[116:117], v[52:53]
	v_pk_fma_f32 v[118:119], v[38:39], v[118:119], v[54:55]
	v_pk_fma_f32 v[120:121], v[40:41], v[120:121], v[56:57]
	v_pk_fma_f32 v[122:123], v[42:43], v[122:123], v[58:59]
	v_pk_fma_f32 v[124:125], v[44:45], v[124:125], v[60:61]
	v_pk_fma_f32 v[126:127], v[46:47], v[126:127], v[62:63]
	v_cvt_pk_bf16_f32 v192, v112, v113
	v_cvt_pk_bf16_f32 v193, v114, v115
	v_cvt_pk_bf16_f32 v194, v116, v117
	v_cvt_pk_bf16_f32 v195, v118, v119
	v_cvt_pk_bf16_f32 v196, v120, v121
	v_cvt_pk_bf16_f32 v197, v122, v123
	v_cvt_pk_bf16_f32 v198, v124, v125
	v_cvt_pk_bf16_f32 v199, v126, v127
	global_store_dwordx4 v1, v[192:195], s[8:9] offset:2048
	global_store_dwordx4 v1, v[196:199], s[8:9] offset:3072
	s_add_u32 s8, s8, 0x1000
	s_addc_u32 s9, s9, 0
	s_waitcnt vmcnt(10)
; __device__ __forceinline__ unsigned cvt_pk_bf16(float lo, float hi) { unsigned r; asm("v_cvt_pk_bf16_f32 %0, %1, %2" : "=v"(r) : "v"(lo), "v"(hi)); return r; }
; __device__ __forceinline__ void norm_pass(const Ctx& X, const float* xs, const float* cs, int nrows, const float* gain, const float* modl, int si, bf16_t* HN) {
;     ...
;         const float* row = r < MX ? xs + (size_t)r * D : cs + (size_t)(r - MX) * D;
;         const int mb = r < MX ? (r >> 12) : 8;
;         const float* sh = modl + (size_t)mb * 9216 + si * 1024; const float* scl = sh + 1024;
;         f32x4 v[4]; float s = 0.f;
; #pragma unroll
;         for (int j = 0; j < 4; ++j) { v[j] = *(const f32x4*)(row + (X.lane + 64 * j) * 4); s += (v[j].x * v[j].x + v[j].y * v[j].y) + (v[j].z * v[j].z + v[j].w * v[j].w); }
;         const float rstd = rsqrtf(wave_sum(s) * (1.0f / 1024.0f) + 1e-6f);
; #pragma unroll
;         for (int j = 0; j < 4; ++j) { const int c = (X.lane + 64 * j) * 4; const f32x4 gn = *(const f32x4*)(gain + c), a = *(const f32x4*)(scl + c), b = *(const f32x4*)(sh + c);
;             const f32x4 o = v[j] * rstd * gn * (a + 1.0f) + b; u32x2 w; w.x = cvt_pk_bf16(o.x, o.y); w.y = cvt_pk_bf16(o.z, o.w); *(u32x2*)(HN + (size_t)r * D + c) = w; }
	v_pk_mul_f32 v[200:201], v[128:129], v[128:129]
	v_pk_fma_f32 v[200:201], v[130:131], v[130:131], v[200:201]
	v_pk_fma_f32 v[200:201], v[132:133], v[132:133], v[200:201]
	v_pk_fma_f32 v[200:201], v[134:135], v[134:135], v[200:201]
	v_pk_fma_f32 v[200:201], v[136:137], v[136:137], v[200:201]
	v_pk_fma_f32 v[200:201], v[138:139], v[138:139], v[200:201]
	v_pk_fma_f32 v[200:201], v[140:141], v[140:141], v[200:201]
	v_pk_fma_f32 v[200:201], v[142:143], v[142:143], v[200:201]
	v_add_f32_e32 v200, v200, v201
	s_nop 1
	v_add_f32_dpp v200, v200, v200 quad_perm:[1,0,3,2] row_mask:0xf bank_mask:0xf
	s_nop 1
	v_add_f32_dpp v200, v200, v200 quad_perm:[2,3,0,1] row_mask:0xf bank_mask:0xf
	s_nop 1
	v_add_f32_dpp v200, v200, v200 row_half_mirror row_mask:0xf bank_mask:0xf
	s_nop 1
	v_add_f32_dpp v200, v200, v200 row_mirror row_mask:0xf bank_mask:0xf
	s_nop 1
	v_mov_b32_e32 v201, v200
	s_nop 1
	v_permlane16_swap_b32_e32 v200, v201
	s_nop 0
	v_add_f32_e32 v200, v200, v201
	v_mov_b32_e32 v201, v200
	s_nop 1
	v_permlane32_swap_b32_e32 v200, v201
	s_nop 0
	v_add_f32_e32 v200, v200, v201
	v_fmamk_f32 v200, v200, 0x3a800000, v3
	v_rsq_f32_e32 v200, v200
	s_nop 0
	v_pk_mul_f32 v[128:129], v[128:129], v[200:201] op_sel_hi:[1,0]
	v_pk_mul_f32 v[130:131], v[130:131], v[200:201] op_sel_hi:[1,0]
	v_pk_mul_f32 v[132:133], v[132:133], v[200:201] op_sel_hi:[1,0]
	v_pk_mul_f32 v[134:135], v[134:135], v[200:201] op_sel_hi:[1,0]
	v_pk_mul_f32 v[136:137], v[136:137], v[200:201] op_sel_hi:[1,0]
	v_pk_mul_f32 v[138:139], v[138:139], v[200:201] op_sel_hi:[1,0]
	v_pk_mul_f32 v[140:141], v[140:141], v[200:201] op_sel_hi:[1,0]
	v_pk_mul_f32 v[142:143], v[142:143], v[200:201] op_sel_hi:[1,0]
	v_pk_mul_f32 v[128:129], v[16:17], v[128:129]
	v_pk_mul_f32 v[130:131], v[18:19], v[130:131]
	v_pk_mul_f32 v[132:133], v[20:21], v[132:133]
	v_pk_mul_f32 v[134:135], v[22:23], v[134:135]
	v_pk_mul_f32 v[136:137], v[24:25], v[136:137]
	v_pk_mul_f32 v[138:139], v[26:27], v[138:139]
	v_pk_mul_f32 v[140:141], v[28:29], v[140:141]
	v_pk_mul_f32 v[142:143], v[30:31], v[142:143]
	v_pk_fma_f32 v[128:129], v[160:161], v[128:129], v[176:177]
	v_pk_fma_f32 v[130:131], v[162:163], v[130:131], v[178:179]
	v_pk_fma_f32 v[132:133], v[164:165], v[132:133], v[180:181]
	v_pk_fma_f32 v[134:135], v[166:167], v[134:135], v[182:183]
	v_pk_fma_f32 v[136:137], v[168:169], v[136:137], v[184:185]
	v_pk_fma_f32 v[138:139], v[170:171], v[138:139], v[186:187]
	v_pk_fma_f32 v[140:141], v[172:173], v[140:141], v[188:189]
	v_pk_fma_f32 v[142:143], v[174:175], v[142:143], v[190:191]
	v_cvt_pk_bf16_f32 v192, v128, v129
	v_cvt_pk_bf16_f32 v193, v130, v131
	v_cvt_pk_bf16_f32 v194, v132, v133
	v_cvt_pk_bf16_f32 v195, v134, v135
	v_cvt_pk_bf16_f32 v196, v136, v137
	v_cvt_pk_bf16_f32 v197, v138, v139
	v_cvt_pk_bf16_f32 v198, v140, v141
	v_cvt_pk_bf16_f32 v199, v142, v143
	global_store_dwordx4 v1, v[192:195], s[12:13]
	global_store_dwordx4 v1, v[196:199], s[12:13] offset:1024
	s_add_i32 s14, s14, s20
	s_cmp_lt_i32 s14, 0x800
	s_cbranch_scc0 .LBB0_194
	s_waitcnt vmcnt(0)
	s_branch .Lhn32_blk

; __device__ __forceinline__ unsigned cvt_pk_bf16(float lo, float hi) { unsigned r; asm("v_cvt_pk_bf16_f32 %0, %1, %2" : "=v"(r) : "v"(lo), "v"(hi)); return r; }
; __device__ __forceinline__ void norm_pass_bf16(const Ctx& X, const bf16_t* xs, const bf16_t* cs, int nrows, const float* gain, const float* modl, int si, bf16_t* HN) {
;     for (int r = X.gw; r < nrows; r += X.NGW) {
;         const int mb = r < MX ? (r >> 12) : 8;
;         const float* sh = modl + (size_t)mb * 9216 + si * 1024; const float* scl = sh + 1024;
;         const bf16_t* rowp = r < MX ? xs + (size_t)r * D : cs + (size_t)(r - MX) * D;
;         u32x4 q[2]; float v[2][8]; float s = 0.f;
; #pragma unroll
;         for (int j = 0; j < 2; ++j) q[j] = *(const u32x4*)(rowp + (X.lane + 64 * j) * 8);
; #pragma unroll
;         for (int j = 0; j < 2; ++j) {
;             v[j][0] = bf2f(q[j].x & 0xffffu); v[j][1] = bf2f(q[j].x >> 16); v[j][2] = bf2f(q[j].y & 0xffffu); v[j][3] = bf2f(q[j].y >> 16);
;             v[j][4] = bf2f(q[j].z & 0xffffu); v[j][5] = bf2f(q[j].z >> 16); v[j][6] = bf2f(q[j].w & 0xffffu); v[j][7] = bf2f(q[j].w >> 16);
; #pragma unroll
;             for (int e = 0; e < 8; ++e) s += v[j][e] * v[j][e]; }
;         const float rstd = rsqrtf(wave_sum(s) * (1.0f / 1024.0f) + 1e-6f);
; #pragma unroll
;         for (int j = 0; j < 2; ++j) { const int c = (X.lane + 64 * j) * 8; float o[8];
; #pragma unroll
;             for (int h = 0; h < 2; ++h) { const f32x4 gn = *(const f32x4*)(gain + c + 4 * h), a = *(const f32x4*)(scl + c + 4 * h), b = *(const f32x4*)(sh + c + 4 * h);
; #pragma unroll
;                 for (int e = 0; e < 4; ++e) o[4 * h + e] = v[j][4 * h + e] * rstd * gn[e] * (a[e] + 1.0f) + b[e]; }
;             u32x4 w; w.x = cvt_pk_bf16(o[0], o[1]); w.y = cvt_pk_bf16(o[2], o[3]); w.z = cvt_pk_bf16(o[4], o[5]); w.w = cvt_pk_bf16(o[6], o[7]); *(u32x4*)(HN + (size_t)r * D + c) = w; }
.LBB0_417:
	s_or_b64 exec, exec, s[0:1]
	v_mov_b32_e32 v4, v206
	s_waitcnt lgkmcnt(0)
	s_barrier
	s_add_u32 s0, s48, 0x1000
	s_addc_u32 s1, s49, 0
	v_readfirstlane_b32 s4, v206
	s_ashr_i32 s4, s4, 6
	s_add_i32 s12, s4, s92
	s_cmp_lt_i32 s12, 0x800
	s_cbranch_scc0 .LBB0_420
	v_mbcnt_hi_u32_b32 v0, -1, v207
	v_lshlrev_b32_e32 v1, 4, v0
	v_lshlrev_b32_e32 v2, 5, v0
	v_mov_b32_e32 v3, 0x358637bd
.Lhn_A_blk:
	s_add_u32 s6, s48, 0x1000
	s_addc_u32 s7, s49, 0
	global_load_dwordx4 v[16:19], v2, s[6:7]
	global_load_dwordx4 v[20:23], v2, s[6:7] offset:16
	global_load_dwordx4 v[24:27], v2, s[6:7] offset:2048
	global_load_dwordx4 v[28:31], v2, s[6:7] offset:2064
	s_lshr_b32 s5, s12, 8
	s_mul_i32 s5, s5, 0x9000
	s_add_u32 s6, s88, s5
	s_addc_u32 s7, s89, 0
	s_add_u32 s6, s6, 0x3000
	s_addc_u32 s7, s7, 0
	global_load_dwordx4 v[48:51], v2, s[6:7]
	global_load_dwordx4 v[52:55], v2, s[6:7] offset:16
	global_load_dwordx4 v[56:59], v2, s[6:7] offset:2048
	global_load_dwordx4 v[60:63], v2, s[6:7] offset:2064
	s_add_u32 s6, s6, 0x1000
	s_addc_u32 s7, s7, 0
	global_load_dwordx4 v[32:35], v2, s[6:7]
	global_load_dwordx4 v[36:39], v2, s[6:7] offset:16
	global_load_dwordx4 v[40:43], v2, s[6:7] offset:2048
	global_load_dwordx4 v[44:47], v2, s[6:7] offset:2064
	s_lshl_b32 s5, s12, 15
	s_add_u32 s8, s86, s5
	s_addc_u32 s9, s87, 0
	s_add_u32 s10, s88, s5
	s_addc_u32 s11, s89, 0
	s_add_u32 s10, s10, 0x13000000
	s_addc_u32 s11, s11, 0
	global_load_dwordx4 v[64:67], v1, s[8:9]
	global_load_dwordx4 v[68:71], v1, s[8:9] offset:1024
	global_load_dwordx4 v[72:75], v1, s[8:9] offset:2048
	global_load_dwordx4 v[76:79], v1, s[8:9] offset:3072
	s_add_u32 s8, s8, 0x1000
	s_addc_u32 s9, s9, 0
	global_load_dwordx4 v[80:83], v1, s[8:9]
	global_load_dwordx4 v[84:87], v1, s[8:9] offset:1024
	global_load_dwordx4 v[88:91], v1, s[8:9] offset:2048
	global_load_dwordx4 v[92:95], v1, s[8:9] offset:3072
	s_add_u32 s8, s8, 0x1000
	s_addc_u32 s9, s9, 0
	global_load_dwordx4 v[96:99], v1, s[8:9]
	global_load_dwordx4 v[100:103], v1, s[8:9] offset:1024
	global_load_dwordx4 v[104:107], v1, s[8:9] offset:2048
	global_load_dwordx4 v[108:111], v1, s[8:9] offset:3072
	s_add_u32 s8, s8, 0x1000
	s_addc_u32 s9, s9, 0
	global_load_dwordx4 v[112:115], v1, s[8:9]
	global_load_dwordx4 v[116:119], v1, s[8:9] offset:1024
	global_load_dwordx4 v[120:123], v1, s[8:9] offset:2048
	global_load_dwordx4 v[124:127], v1, s[8:9] offset:3072
	s_add_u32 s8, s8, 0x1000
	s_addc_u32 s9, s9, 0
	s_waitcnt vmcnt(16)
	v_pk_add_f32 v[32:33], v[32:33], 1.0 op_sel_hi:[1,0]
	v_pk_add_f32 v[34:35], v[34:35], 1.0 op_sel_hi:[1,0]
	v_pk_add_f32 v[36:37], v[36:37], 1.0 op_sel_hi:[1,0]
	v_pk_add_f32 v[38:39], v[38:39], 1.0 op_sel_hi:[1,0]
	v_pk_add_f32 v[40:41], v[40:41], 1.0 op_sel_hi:[1,0]
	v_pk_add_f32 v[42:43], v[42:43], 1.0 op_sel_hi:[1,0]
	v_pk_add_f32 v[44:45], v[44:45], 1.0 op_sel_hi:[1,0]
	v_pk_add_f32 v[46:47], v[46:47], 1.0 op_sel_hi:[1,0]
	s_waitcnt vmcnt(14)
	v_lshlrev_b32_e32 v128, 16, v64
	v_and_b32_e32 v129, 0xffff0000, v64
	v_lshlrev_b32_e32 v130, 16, v65
	v_and_b32_e32 v131, 0xffff0000, v65
	v_lshlrev_b32_e32 v132, 16, v66
	v_and_b32_e32 v133, 0xffff0000, v66
	v_lshlrev_b32_e32 v134, 16, v67
	v_and_b32_e32 v135, 0xffff0000, v67
	v_lshlrev_b32_e32 v136, 16, v68
	v_and_b32_e32 v137, 0xffff0000, v68
	v_lshlrev_b32_e32 v138, 16, v69
	v_and_b32_e32 v139, 0xffff0000, v69
	v_lshlrev_b32_e32 v140, 16, v70
	v_and_b32_e32 v141, 0xffff0000, v70
	v_lshlrev_b32_e32 v142, 16, v71
	v_and_b32_e32 v143, 0xffff0000, v71
	v_pk_mul_f32 v[144:145], v[128:129], v[128:129]
	v_pk_fma_f32 v[144:145], v[130:131], v[130:131], v[144:145]
	v_pk_fma_f32 v[144:145], v[132:133], v[132:133], v[144:145]
	v_pk_fma_f32 v[144:145], v[134:135], v[134:135], v[144:145]
	v_pk_fma_f32 v[144:145], v[136:137], v[136:137], v[144:145]
	v_pk_fma_f32 v[144:145], v[138:139], v[138:139], v[144:145]
	v_pk_fma_f32 v[144:145], v[140:141], v[140:141], v[144:145]
	v_pk_fma_f32 v[144:145], v[142:143], v[142:143], v[144:145]
	v_add_f32_e32 v144, v144, v145
	s_nop 1
	v_add_f32_dpp v144, v144, v144 quad_perm:[1,0,3,2] row_mask:0xf bank_mask:0xf
	s_nop 1
	v_add_f32_dpp v144, v144, v144 quad_perm:[2,3,0,1] row_mask:0xf bank_mask:0xf
	s_nop 1
	v_add_f32_dpp v144, v144, v144 row_half_mirror row_mask:0xf bank_mask:0xf
	s_nop 1
	v_add_f32_dpp v144, v144, v144 row_mirror row_mask:0xf bank_mask:0xf
	s_nop 0
	v_mov_b32_e32 v145, v144
	s_nop 1
	v_permlane16_swap_b32_e32 v144, v145
	s_nop 0
	v_add_f32_e32 v144, v144, v145
	v_mov_b32_e32 v145, v144
	s_nop 1
	v_permlane32_swap_b32_e32 v144, v145
	s_nop 0
	v_add_f32_e32 v144, v144, v145
	v_fmamk_f32 v144, v144, 0x3a800000, v3
	v_rsq_f32_e32 v144, v144
	s_nop 0
	v_pk_mul_f32 v[128:129], v[128:129], v[144:145] op_sel_hi:[1,0]
	v_pk_mul_f32 v[130:131], v[130:131], v[144:145] op_sel_hi:[1,0]
	v_pk_mul_f32 v[132:133], v[132:133], v[144:145] op_sel_hi:[1,0]
	v_pk_mul_f32 v[134:135], v[134:135], v[144:145] op_sel_hi:[1,0]
	v_pk_mul_f32 v[136:137], v[136:137], v[144:145] op_sel_hi:[1,0]
	v_pk_mul_f32 v[138:139], v[138:139], v[144:145] op_sel_hi:[1,0]
	v_pk_mul_f32 v[140:141], v[140:141], v[144:145] op_sel_hi:[1,0]
	v_pk_mul_f32 v[142:143], v[142:143], v[144:145] op_sel_hi:[1,0]
	v_pk_mul_f32 v[128:129], v[16:17], v[128:129]
	v_pk_mul_f32 v[130:131], v[18:19], v[130:131]
	v_pk_mul_f32 v[132:133], v[20:21], v[132:133]
	v_pk_mul_f32 v[134:135], v[22:23], v[134:135]
	v_pk_mul_f32 v[136:137], v[24:25], v[136:137]
	v_pk_mul_f32 v[138:139], v[26:27], v[138:139]
	v_pk_mul_f32 v[140:141], v[28:29], v[140:141]
	v_pk_mul_f32 v[142:143], v[30:31], v[142:143]
	v_pk_fma_f32 v[128:129], v[32:33], v[128:129], v[48:49]
	v_pk_fma_f32 v[130:131], v[34:35], v[130:131], v[50:51]
	v_pk_fma_f32 v[132:133], v[36:37], v[132:133], v[52:53]
	v_pk_fma_f32 v[134:135], v[38:39], v[134:135], v[54:55]
	v_pk_fma_f32 v[136:137], v[40:41], v[136:137], v[56:57]
	v_pk_fma_f32 v[138:139], v[42:43], v[138:139], v[58:59]
	v_pk_fma_f32 v[140:141], v[44:45], v[140:141], v[60:61]
	v_pk_fma_f32 v[142:143], v[46:47], v[142:143], v[62:63]
	v_cvt_pk_bf16_f32 v148, v128, v129
	v_cvt_pk_bf16_f32 v149, v130, v131
	v_cvt_pk_bf16_f32 v150, v132, v133
	v_cvt_pk_bf16_f32 v151, v134, v135
	v_cvt_pk_bf16_f32 v152, v136, v137
	v_cvt_pk_bf16_f32 v153, v138, v139
	v_cvt_pk_bf16_f32 v154, v140, v141
	v_cvt_pk_bf16_f32 v155, v142, v143
	global_store_dwordx4 v1, v[148:151], s[10:11]
	global_store_dwordx4 v1, v[152:155], s[10:11] offset:1024
	global_load_dwordx4 v[64:67], v1, s[8:9]
	global_load_dwordx4 v[68:71], v1, s[8:9] offset:1024
	s_waitcnt vmcnt(16)
; __device__ __forceinline__ unsigned cvt_pk_bf16(float lo, float hi) { unsigned r; asm("v_cvt_pk_bf16_f32 %0, %1, %2" : "=v"(r) : "v"(lo), "v"(hi)); return r; }
; __device__ __forceinline__ void norm_pass_bf16(const Ctx& X, const bf16_t* xs, const bf16_t* cs, int nrows, const float* gain, const float* modl, int si, bf16_t* HN) {
;     ...
;         for (int j = 0; j < 2; ++j) q[j] = *(const u32x4*)(rowp + (X.lane + 64 * j) * 8);
; #pragma unroll
;         for (int j = 0; j < 2; ++j) {
;             v[j][0] = bf2f(q[j].x & 0xffffu); v[j][1] = bf2f(q[j].x >> 16); v[j][2] = bf2f(q[j].y & 0xffffu); v[j][3] = bf2f(q[j].y >> 16);
;             v[j][4] = bf2f(q[j].z & 0xffffu); v[j][5] = bf2f(q[j].z >> 16); v[j][6] = bf2f(q[j].w & 0xffffu); v[j][7] = bf2f(q[j].w >> 16);
; #pragma unroll
;             for (int e = 0; e < 8; ++e) s += v[j][e] * v[j][e]; }
;         const float rstd = rsqrtf(wave_sum(s) * (1.0f / 1024.0f) + 1e-6f);
; #pragma unroll
;         for (int j = 0; j < 2; ++j) { const int c = (X.lane + 64 * j) * 8; float o[8];
; #pragma unroll
;             for (int h = 0; h < 2; ++h) { const f32x4 gn = *(const f32x4*)(gain + c + 4 * h), a = *(const f32x4*)(scl + c + 4 * h), b = *(const f32x4*)(sh + c + 4 * h);
; #pragma unroll
;                 for (int e = 0; e < 4; ++e) o[4 * h + e] = v[j][4 * h + e] * rstd * gn[e] * (a[e] + 1.0f) + b[e]; }
;             u32x4 w; w.x = cvt_pk_bf16(o[0], o[1]); w.y = cvt_pk_bf16(o[2], o[3]); w.z = cvt_pk_bf16(o[4], o[5]); w.w = cvt_pk_bf16(o[6], o[7]); *(u32x4*)(HN + (size_t)r * D + c) = w; }
	v_lshlrev_b32_e32 v128, 16, v72
	v_and_b32_e32 v129, 0xffff0000, v72
	v_lshlrev_b32_e32 v130, 16, v73
	v_and_b32_e32 v131, 0xffff0000, v73
	v_lshlrev_b32_e32 v132, 16, v74
	v_and_b32_e32 v133, 0xffff0000, v74
	v_lshlrev_b32_e32 v134, 16, v75
	v_and_b32_e32 v135, 0xffff0000, v75
	v_lshlrev_b32_e32 v136, 16, v76
	v_and_b32_e32 v137, 0xffff0000, v76
	v_lshlrev_b32_e32 v138, 16, v77
	v_and_b32_e32 v139, 0xffff0000, v77
	v_lshlrev_b32_e32 v140, 16, v78
	v_and_b32_e32 v141, 0xffff0000, v78
	v_lshlrev_b32_e32 v142, 16, v79
	v_and_b32_e32 v143, 0xffff0000, v79
	v_pk_mul_f32 v[144:145], v[128:129], v[128:129]
	v_pk_fma_f32 v[144:145], v[130:131], v[130:131], v[144:145]
	v_pk_fma_f32 v[144:145], v[132:133], v[132:133], v[144:145]
	v_pk_fma_f32 v[144:145], v[134:135], v[134:135], v[144:145]
	v_pk_fma_f32 v[144:145], v[136:137], v[136:137], v[144:145]
	v_pk_fma_f32 v[144:145], v[138:139], v[138:139], v[144:145]
	v_pk_fma_f32 v[144:145], v[140:141], v[140:141], v[144:145]
	v_pk_fma_f32 v[144:145], v[142:143], v[142:143], v[144:145]
	v_add_f32_e32 v144, v144, v145
	s_nop 1
	v_add_f32_dpp v144, v144, v144 quad_perm:[1,0,3,2] row_mask:0xf bank_mask:0xf
	s_nop 1
	v_add_f32_dpp v144, v144, v144 quad_perm:[2,3,0,1] row_mask:0xf bank_mask:0xf
	s_nop 1
	v_add_f32_dpp v144, v144, v144 row_half_mirror row_mask:0xf bank_mask:0xf
	s_nop 1
	v_add_f32_dpp v144, v144, v144 row_mirror row_mask:0xf bank_mask:0xf
	s_nop 0
	v_mov_b32_e32 v145, v144
	s_nop 1
	v_permlane16_swap_b32_e32 v144, v145
	s_nop 0
	v_add_f32_e32 v144, v144, v145
	v_mov_b32_e32 v145, v144
	s_nop 1
	v_permlane32_swap_b32_e32 v144, v145
	s_nop 0
	v_add_f32_e32 v144, v144, v145
	v_fmamk_f32 v144, v144, 0x3a800000, v3
	v_rsq_f32_e32 v144, v144
	s_nop 0
	v_pk_mul_f32 v[128:129], v[128:129], v[144:145] op_sel_hi:[1,0]
	v_pk_mul_f32 v[130:131], v[130:131], v[144:145] op_sel_hi:[1,0]
	v_pk_mul_f32 v[132:133], v[132:133], v[144:145] op_sel_hi:[1,0]
	v_pk_mul_f32 v[134:135], v[134:135], v[144:145] op_sel_hi:[1,0]
	v_pk_mul_f32 v[136:137], v[136:137], v[144:145] op_sel_hi:[1,0]
	v_pk_mul_f32 v[138:139], v[138:139], v[144:145] op_sel_hi:[1,0]
	v_pk_mul_f32 v[140:141], v[140:141], v[144:145] op_sel_hi:[1,0]
	v_pk_mul_f32 v[142:143], v[142:143], v[144:145] op_sel_hi:[1,0]
	v_pk_mul_f32 v[128:129], v[16:17], v[128:129]
	v_pk_mul_f32 v[130:131], v[18:19], v[130:131]
	v_pk_mul_f32 v[132:133], v[20:21], v[132:133]
	v_pk_mul_f32 v[134:135], v[22:23], v[134:135]
	v_pk_mul_f32 v[136:137], v[24:25], v[136:137]
	v_pk_mul_f32 v[138:139], v[26:27], v[138:139]
	v_pk_mul_f32 v[140:141], v[28:29], v[140:141]
	v_pk_mul_f32 v[142:143], v[30:31], v[142:143]
	v_pk_fma_f32 v[128:129], v[32:33], v[128:129], v[48:49]
	v_pk_fma_f32 v[130:131], v[34:35], v[130:131], v[50:51]
	v_pk_fma_f32 v[132:133], v[36:37], v[132:133], v[52:53]
	v_pk_fma_f32 v[134:135], v[38:39], v[134:135], v[54:55]
	v_pk_fma_f32 v[136:137], v[40:41], v[136:137], v[56:57]
	v_pk_fma_f32 v[138:139], v[42:43], v[138:139], v[58:59]
	v_pk_fma_f32 v[140:141], v[44:45], v[140:141], v[60:61]
	v_pk_fma_f32 v[142:143], v[46:47], v[142:143], v[62:63]
	v_cvt_pk_bf16_f32 v148, v128, v129
	v_cvt_pk_bf16_f32 v149, v130, v131
	v_cvt_pk_bf16_f32 v150, v132, v133
	v_cvt_pk_bf16_f32 v151, v134, v135
	v_cvt_pk_bf16_f32 v152, v136, v137
	v_cvt_pk_bf16_f32 v153, v138, v139
	v_cvt_pk_bf16_f32 v154, v140, v141
	v_cvt_pk_bf16_f32 v155, v142, v143
	global_store_dwordx4 v1, v[148:151], s[10:11] offset:2048
	global_store_dwordx4 v1, v[152:155], s[10:11] offset:3072
	s_add_u32 s10, s10, 0x1000
	s_addc_u32 s11, s11, 0
	global_load_dwordx4 v[72:75], v1, s[8:9] offset:2048
	global_load_dwordx4 v[76:79], v1, s[8:9] offset:3072
	s_add_u32 s8, s8, 0x1000
	s_addc_u32 s9, s9, 0
	s_waitcnt vmcnt(18)
	v_lshlrev_b32_e32 v128, 16, v80
	v_and_b32_e32 v129, 0xffff0000, v80
	v_lshlrev_b32_e32 v130, 16, v81
	v_and_b32_e32 v131, 0xffff0000, v81
	v_lshlrev_b32_e32 v132, 16, v82
	v_and_b32_e32 v133, 0xffff0000, v82
	v_lshlrev_b32_e32 v134, 16, v83
	v_and_b32_e32 v135, 0xffff0000, v83
	v_lshlrev_b32_e32 v136, 16, v84
	v_and_b32_e32 v137, 0xffff0000, v84
	v_lshlrev_b32_e32 v138, 16, v85
	v_and_b32_e32 v139, 0xffff0000, v85
	v_lshlrev_b32_e32 v140, 16, v86
	v_and_b32_e32 v141, 0xffff0000, v86
	v_lshlrev_b32_e32 v142, 16, v87
	v_and_b32_e32 v143, 0xffff0000, v87
	v_pk_mul_f32 v[144:145], v[128:129], v[128:129]
	v_pk_fma_f32 v[144:145], v[130:131], v[130:131], v[144:145]
	v_pk_fma_f32 v[144:145], v[132:133], v[132:133], v[144:145]
	v_pk_fma_f32 v[144:145], v[134:135], v[134:135], v[144:145]
	v_pk_fma_f32 v[144:145], v[136:137], v[136:137], v[144:145]
	v_pk_fma_f32 v[144:145], v[138:139], v[138:139], v[144:145]
	v_pk_fma_f32 v[144:145], v[140:141], v[140:141], v[144:145]
	v_pk_fma_f32 v[144:145], v[142:143], v[142:143], v[144:145]
	v_add_f32_e32 v144, v144, v145
	s_nop 1
	v_add_f32_dpp v144, v144, v144 quad_perm:[1,0,3,2] row_mask:0xf bank_mask:0xf
	s_nop 1
	v_add_f32_dpp v144, v144, v144 quad_perm:[2,3,0,1] row_mask:0xf bank_mask:0xf
	s_nop 1
	v_add_f32_dpp v144, v144, v144 row_half_mirror row_mask:0xf bank_mask:0xf
	s_nop 1
	v_add_f32_dpp v144, v144, v144 row_mirror row_mask:0xf bank_mask:0xf
	s_nop 0
	v_mov_b32_e32 v145, v144
	s_nop 1
	v_permlane16_swap_b32_e32 v144, v145
	s_nop 0
	v_add_f32_e32 v144, v144, v145
	v_mov_b32_e32 v145, v144
	s_nop 1
	v_permlane32_swap_b32_e32 v144, v145
	s_nop 0
	v_add_f32_e32 v144, v144, v145
	v_fmamk_f32 v144, v144, 0x3a800000, v3
	v_rsq_f32_e32 v144, v144
	s_nop 0
	v_pk_mul_f32 v[128:129], v[128:129], v[144:145] op_sel_hi:[1,0]
	v_pk_mul_f32 v[130:131], v[130:131], v[144:145] op_sel_hi:[1,0]
	v_pk_mul_f32 v[132:133], v[132:133], v[144:145] op_sel_hi:[1,0]
; __device__ __forceinline__ unsigned cvt_pk_bf16(float lo, float hi) { unsigned r; asm("v_cvt_pk_bf16_f32 %0, %1, %2" : "=v"(r) : "v"(lo), "v"(hi)); return r; }
; __device__ __forceinline__ void norm_pass_bf16(const Ctx& X, const bf16_t* xs, const bf16_t* cs, int nrows, const float* gain, const float* modl, int si, bf16_t* HN) {
;     ...
;         for (int j = 0; j < 2; ++j) q[j] = *(const u32x4*)(rowp + (X.lane + 64 * j) * 8);
; #pragma unroll
;         for (int j = 0; j < 2; ++j) {
;             v[j][0] = bf2f(q[j].x & 0xffffu); v[j][1] = bf2f(q[j].x >> 16); v[j][2] = bf2f(q[j].y & 0xffffu); v[j][3] = bf2f(q[j].y >> 16);
;             v[j][4] = bf2f(q[j].z & 0xffffu); v[j][5] = bf2f(q[j].z >> 16); v[j][6] = bf2f(q[j].w & 0xffffu); v[j][7] = bf2f(q[j].w >> 16);
; #pragma unroll
;             for (int e = 0; e < 8; ++e) s += v[j][e] * v[j][e]; }
;         const float rstd = rsqrtf(wave_sum(s) * (1.0f / 1024.0f) + 1e-6f);
; #pragma unroll
;         for (int j = 0; j < 2; ++j) { const int c = (X.lane + 64 * j) * 8; float o[8];
; #pragma unroll
;             for (int h = 0; h < 2; ++h) { const f32x4 gn = *(const f32x4*)(gain + c + 4 * h), a = *(const f32x4*)(scl + c + 4 * h), b = *(const f32x4*)(sh + c + 4 * h);
; #pragma unroll
;                 for (int e = 0; e < 4; ++e) o[4 * h + e] = v[j][4 * h + e] * rstd * gn[e] * (a[e] + 1.0f) + b[e]; }
;             u32x4 w; w.x = cvt_pk_bf16(o[0], o[1]); w.y = cvt_pk_bf16(o[2], o[3]); w.z = cvt_pk_bf16(o[4], o[5]); w.w = cvt_pk_bf16(o[6], o[7]); *(u32x4*)(HN + (size_t)r * D + c) = w; }
	v_pk_mul_f32 v[134:135], v[134:135], v[144:145] op_sel_hi:[1,0]
	v_pk_mul_f32 v[136:137], v[136:137], v[144:145] op_sel_hi:[1,0]
	v_pk_mul_f32 v[138:139], v[138:139], v[144:145] op_sel_hi:[1,0]
	v_pk_mul_f32 v[140:141], v[140:141], v[144:145] op_sel_hi:[1,0]
	v_pk_mul_f32 v[142:143], v[142:143], v[144:145] op_sel_hi:[1,0]
	v_pk_mul_f32 v[128:129], v[16:17], v[128:129]
	v_pk_mul_f32 v[130:131], v[18:19], v[130:131]
	v_pk_mul_f32 v[132:133], v[20:21], v[132:133]
	v_pk_mul_f32 v[134:135], v[22:23], v[134:135]
	v_pk_mul_f32 v[136:137], v[24:25], v[136:137]
	v_pk_mul_f32 v[138:139], v[26:27], v[138:139]
	v_pk_mul_f32 v[140:141], v[28:29], v[140:141]
	v_pk_mul_f32 v[142:143], v[30:31], v[142:143]
	v_pk_fma_f32 v[128:129], v[32:33], v[128:129], v[48:49]
	v_pk_fma_f32 v[130:131], v[34:35], v[130:131], v[50:51]
	v_pk_fma_f32 v[132:133], v[36:37], v[132:133], v[52:53]
	v_pk_fma_f32 v[134:135], v[38:39], v[134:135], v[54:55]
	v_pk_fma_f32 v[136:137], v[40:41], v[136:137], v[56:57]
	v_pk_fma_f32 v[138:139], v[42:43], v[138:139], v[58:59]
	v_pk_fma_f32 v[140:141], v[44:45], v[140:141], v[60:61]
	v_pk_fma_f32 v[142:143], v[46:47], v[142:143], v[62:63]
	v_cvt_pk_bf16_f32 v148, v128, v129
	v_cvt_pk_bf16_f32 v149, v130, v131
	v_cvt_pk_bf16_f32 v150, v132, v133
	v_cvt_pk_bf16_f32 v151, v134, v135
	v_cvt_pk_bf16_f32 v152, v136, v137
	v_cvt_pk_bf16_f32 v153, v138, v139
	v_cvt_pk_bf16_f32 v154, v140, v141
	v_cvt_pk_bf16_f32 v155, v142, v143
	global_store_dwordx4 v1, v[148:151], s[10:11]
	global_store_dwordx4 v1, v[152:155], s[10:11] offset:1024
	global_load_dwordx4 v[80:83], v1, s[8:9]
	global_load_dwordx4 v[84:87], v1, s[8:9] offset:1024
	s_waitcnt vmcnt(20)
	v_lshlrev_b32_e32 v128, 16, v88
	v_and_b32_e32 v129, 0xffff0000, v88
	v_lshlrev_b32_e32 v130, 16, v89
	v_and_b32_e32 v131, 0xffff0000, v89
	v_lshlrev_b32_e32 v132, 16, v90
	v_and_b32_e32 v133, 0xffff0000, v90
	v_lshlrev_b32_e32 v134, 16, v91
	v_and_b32_e32 v135, 0xffff0000, v91
	v_lshlrev_b32_e32 v136, 16, v92
	v_and_b32_e32 v137, 0xffff0000, v92
	v_lshlrev_b32_e32 v138, 16, v93
	v_and_b32_e32 v139, 0xffff0000, v93
	v_lshlrev_b32_e32 v140, 16, v94
	v_and_b32_e32 v141, 0xffff0000, v94
	v_lshlrev_b32_e32 v142, 16, v95
	v_and_b32_e32 v143, 0xffff0000, v95
	v_pk_mul_f32 v[144:145], v[128:129], v[128:129]
	v_pk_fma_f32 v[144:145], v[130:131], v[130:131], v[144:145]
	v_pk_fma_f32 v[144:145], v[132:133], v[132:133], v[144:145]
	v_pk_fma_f32 v[144:145], v[134:135], v[134:135], v[144:145]
	v_pk_fma_f32 v[144:145], v[136:137], v[136:137], v[144:145]
	v_pk_fma_f32 v[144:145], v[138:139], v[138:139], v[144:145]
	v_pk_fma_f32 v[144:145], v[140:141], v[140:141], v[144:145]
	v_pk_fma_f32 v[144:145], v[142:143], v[142:143], v[144:145]
	v_add_f32_e32 v144, v144, v145
	s_nop 1
	v_add_f32_dpp v144, v144, v144 quad_perm:[1,0,3,2] row_mask:0xf bank_mask:0xf
	s_nop 1
	v_add_f32_dpp v144, v144, v144 quad_perm:[2,3,0,1] row_mask:0xf bank_mask:0xf
	s_nop 1
	v_add_f32_dpp v144, v144, v144 row_half_mirror row_mask:0xf bank_mask:0xf
	s_nop 1
	v_add_f32_dpp v144, v144, v144 row_mirror row_mask:0xf bank_mask:0xf
	s_nop 0
	v_mov_b32_e32 v145, v144
	s_nop 1
	v_permlane16_swap_b32_e32 v144, v145
	s_nop 0
	v_add_f32_e32 v144, v144, v145
	v_mov_b32_e32 v145, v144
	s_nop 1
	v_permlane32_swap_b32_e32 v144, v145
	s_nop 0
	v_add_f32_e32 v144, v144, v145
	v_fmamk_f32 v144, v144, 0x3a800000, v3
	v_rsq_f32_e32 v144, v144
	s_nop 0
	v_pk_mul_f32 v[128:129], v[128:129], v[144:145] op_sel_hi:[1,0]
	v_pk_mul_f32 v[130:131], v[130:131], v[144:145] op_sel_hi:[1,0]
	v_pk_mul_f32 v[132:133], v[132:133], v[144:145] op_sel_hi:[1,0]
	v_pk_mul_f32 v[134:135], v[134:135], v[144:145] op_sel_hi:[1,0]
	v_pk_mul_f32 v[136:137], v[136:137], v[144:145] op_sel_hi:[1,0]
	v_pk_mul_f32 v[138:139], v[138:139], v[144:145] op_sel_hi:[1,0]
	v_pk_mul_f32 v[140:141], v[140:141], v[144:145] op_sel_hi:[1,0]
	v_pk_mul_f32 v[142:143], v[142:143], v[144:145] op_sel_hi:[1,0]
	v_pk_mul_f32 v[128:129], v[16:17], v[128:129]
	v_pk_mul_f32 v[130:131], v[18:19], v[130:131]
	v_pk_mul_f32 v[132:133], v[20:21], v[132:133]
	v_pk_mul_f32 v[134:135], v[22:23], v[134:135]
	v_pk_mul_f32 v[136:137], v[24:25], v[136:137]
	v_pk_mul_f32 v[138:139], v[26:27], v[138:139]
	v_pk_mul_f32 v[140:141], v[28:29], v[140:141]
	v_pk_mul_f32 v[142:143], v[30:31], v[142:143]
	v_pk_fma_f32 v[128:129], v[32:33], v[128:129], v[48:49]
	v_pk_fma_f32 v[130:131], v[34:35], v[130:131], v[50:51]
	v_pk_fma_f32 v[132:133], v[36:37], v[132:133], v[52:53]
	v_pk_fma_f32 v[134:135], v[38:39], v[134:135], v[54:55]
	v_pk_fma_f32 v[136:137], v[40:41], v[136:137], v[56:57]
	v_pk_fma_f32 v[138:139], v[42:43], v[138:139], v[58:59]
	v_pk_fma_f32 v[140:141], v[44:45], v[140:141], v[60:61]
	v_pk_fma_f32 v[142:143], v[46:47], v[142:143], v[62:63]
	v_cvt_pk_bf16_f32 v148, v128, v129
	v_cvt_pk_bf16_f32 v149, v130, v131
	v_cvt_pk_bf16_f32 v150, v132, v133
	v_cvt_pk_bf16_f32 v151, v134, v135
	v_cvt_pk_bf16_f32 v152, v136, v137
	v_cvt_pk_bf16_f32 v153, v138, v139
	v_cvt_pk_bf16_f32 v154, v140, v141
	v_cvt_pk_bf16_f32 v155, v142, v143
	global_store_dwordx4 v1, v[148:151], s[10:11] offset:2048
	global_store_dwordx4 v1, v[152:155], s[10:11] offset:3072
	s_add_u32 s10, s10, 0x1000
	s_addc_u32 s11, s11, 0
	global_load_dwordx4 v[88:91], v1, s[8:9] offset:2048
	global_load_dwordx4 v[92:95], v1, s[8:9] offset:3072
	s_add_u32 s8, s8, 0x1000
	s_addc_u32 s9, s9, 0
	s_waitcnt vmcnt(22)
; __device__ __forceinline__ unsigned cvt_pk_bf16(float lo, float hi) { unsigned r; asm("v_cvt_pk_bf16_f32 %0, %1, %2" : "=v"(r) : "v"(lo), "v"(hi)); return r; }
; __device__ __forceinline__ void norm_pass_bf16(const Ctx& X, const bf16_t* xs, const bf16_t* cs, int nrows, const float* gain, const float* modl, int si, bf16_t* HN) {
;     ...
;         for (int j = 0; j < 2; ++j) q[j] = *(const u32x4*)(rowp + (X.lane + 64 * j) * 8);
; #pragma unroll
;         for (int j = 0; j < 2; ++j) {
;             v[j][0] = bf2f(q[j].x & 0xffffu); v[j][1] = bf2f(q[j].x >> 16); v[j][2] = bf2f(q[j].y & 0xffffu); v[j][3] = bf2f(q[j].y >> 16);
;             v[j][4] = bf2f(q[j].z & 0xffffu); v[j][5] = bf2f(q[j].z >> 16); v[j][6] = bf2f(q[j].w & 0xffffu); v[j][7] = bf2f(q[j].w >> 16);
; #pragma unroll
;             for (int e = 0; e < 8; ++e) s += v[j][e] * v[j][e]; }
;         const float rstd = rsqrtf(wave_sum(s) * (1.0f / 1024.0f) + 1e-6f);
; #pragma unroll
;         for (int j = 0; j < 2; ++j) { const int c = (X.lane + 64 * j) * 8; float o[8];
; #pragma unroll
;             for (int h = 0; h < 2; ++h) { const f32x4 gn = *(const f32x4*)(gain + c + 4 * h), a = *(const f32x4*)(scl + c + 4 * h), b = *(const f32x4*)(sh + c + 4 * h);
; #pragma unroll
;                 for (int e = 0; e < 4; ++e) o[4 * h + e] = v[j][4 * h + e] * rstd * gn[e] * (a[e] + 1.0f) + b[e]; }
;             u32x4 w; w.x = cvt_pk_bf16(o[0], o[1]); w.y = cvt_pk_bf16(o[2], o[3]); w.z = cvt_pk_bf16(o[4], o[5]); w.w = cvt_pk_bf16(o[6], o[7]); *(u32x4*)(HN + (size_t)r * D + c) = w; }
	v_lshlrev_b32_e32 v128, 16, v96
	v_and_b32_e32 v129, 0xffff0000, v96
	v_lshlrev_b32_e32 v130, 16, v97
	v_and_b32_e32 v131, 0xffff0000, v97
	v_lshlrev_b32_e32 v132, 16, v98
	v_and_b32_e32 v133, 0xffff0000, v98
	v_lshlrev_b32_e32 v134, 16, v99
	v_and_b32_e32 v135, 0xffff0000, v99
	v_lshlrev_b32_e32 v136, 16, v100
	v_and_b32_e32 v137, 0xffff0000, v100
	v_lshlrev_b32_e32 v138, 16, v101
	v_and_b32_e32 v139, 0xffff0000, v101
	v_lshlrev_b32_e32 v140, 16, v102
	v_and_b32_e32 v141, 0xffff0000, v102
	v_lshlrev_b32_e32 v142, 16, v103
	v_and_b32_e32 v143, 0xffff0000, v103
	v_pk_mul_f32 v[144:145], v[128:129], v[128:129]
	v_pk_fma_f32 v[144:145], v[130:131], v[130:131], v[144:145]
	v_pk_fma_f32 v[144:145], v[132:133], v[132:133], v[144:145]
	v_pk_fma_f32 v[144:145], v[134:135], v[134:135], v[144:145]
	v_pk_fma_f32 v[144:145], v[136:137], v[136:137], v[144:145]
	v_pk_fma_f32 v[144:145], v[138:139], v[138:139], v[144:145]
	v_pk_fma_f32 v[144:145], v[140:141], v[140:141], v[144:145]
	v_pk_fma_f32 v[144:145], v[142:143], v[142:143], v[144:145]
	v_add_f32_e32 v144, v144, v145
	s_nop 1
	v_add_f32_dpp v144, v144, v144 quad_perm:[1,0,3,2] row_mask:0xf bank_mask:0xf
	s_nop 1
	v_add_f32_dpp v144, v144, v144 quad_perm:[2,3,0,1] row_mask:0xf bank_mask:0xf
	s_nop 1
	v_add_f32_dpp v144, v144, v144 row_half_mirror row_mask:0xf bank_mask:0xf
	s_nop 1
	v_add_f32_dpp v144, v144, v144 row_mirror row_mask:0xf bank_mask:0xf
	s_nop 0
	v_mov_b32_e32 v145, v144
	s_nop 1
	v_permlane16_swap_b32_e32 v144, v145
	s_nop 0
	v_add_f32_e32 v144, v144, v145
	v_mov_b32_e32 v145, v144
	s_nop 1
	v_permlane32_swap_b32_e32 v144, v145
	s_nop 0
	v_add_f32_e32 v144, v144, v145
	v_fmamk_f32 v144, v144, 0x3a800000, v3
	v_rsq_f32_e32 v144, v144
	s_nop 0
	v_pk_mul_f32 v[128:129], v[128:129], v[144:145] op_sel_hi:[1,0]
	v_pk_mul_f32 v[130:131], v[130:131], v[144:145] op_sel_hi:[1,0]
	v_pk_mul_f32 v[132:133], v[132:133], v[144:145] op_sel_hi:[1,0]
	v_pk_mul_f32 v[134:135], v[134:135], v[144:145] op_sel_hi:[1,0]
	v_pk_mul_f32 v[136:137], v[136:137], v[144:145] op_sel_hi:[1,0]
	v_pk_mul_f32 v[138:139], v[138:139], v[144:145] op_sel_hi:[1,0]
	v_pk_mul_f32 v[140:141], v[140:141], v[144:145] op_sel_hi:[1,0]
	v_pk_mul_f32 v[142:143], v[142:143], v[144:145] op_sel_hi:[1,0]
	v_pk_mul_f32 v[128:129], v[16:17], v[128:129]
	v_pk_mul_f32 v[130:131], v[18:19], v[130:131]
	v_pk_mul_f32 v[132:133], v[20:21], v[132:133]
	v_pk_mul_f32 v[134:135], v[22:23], v[134:135]
	v_pk_mul_f32 v[136:137], v[24:25], v[136:137]
	v_pk_mul_f32 v[138:139], v[26:27], v[138:139]
	v_pk_mul_f32 v[140:141], v[28:29], v[140:141]
	v_pk_mul_f32 v[142:143], v[30:31], v[142:143]
	v_pk_fma_f32 v[128:129], v[32:33], v[128:129], v[48:49]
	v_pk_fma_f32 v[130:131], v[34:35], v[130:131], v[50:51]
	v_pk_fma_f32 v[132:133], v[36:37], v[132:133], v[52:53]
	v_pk_fma_f32 v[134:135], v[38:39], v[134:135], v[54:55]
	v_pk_fma_f32 v[136:137], v[40:41], v[136:137], v[56:57]
	v_pk_fma_f32 v[138:139], v[42:43], v[138:139], v[58:59]
	v_pk_fma_f32 v[140:141], v[44:45], v[140:141], v[60:61]
	v_pk_fma_f32 v[142:143], v[46:47], v[142:143], v[62:63]
	v_cvt_pk_bf16_f32 v148, v128, v129
	v_cvt_pk_bf16_f32 v149, v130, v131
	v_cvt_pk_bf16_f32 v150, v132, v133
	v_cvt_pk_bf16_f32 v151, v134, v135
	v_cvt_pk_bf16_f32 v152, v136, v137
	v_cvt_pk_bf16_f32 v153, v138, v139
	v_cvt_pk_bf16_f32 v154, v140, v141
	v_cvt_pk_bf16_f32 v155, v142, v143
	global_store_dwordx4 v1, v[148:151], s[10:11]
	global_store_dwordx4 v1, v[152:155], s[10:11] offset:1024
	global_load_dwordx4 v[96:99], v1, s[8:9]
	global_load_dwordx4 v[100:103], v1, s[8:9] offset:1024
	s_waitcnt vmcnt(24)
	v_lshlrev_b32_e32 v128, 16, v104
	v_and_b32_e32 v129, 0xffff0000, v104
	v_lshlrev_b32_e32 v130, 16, v105
	v_and_b32_e32 v131, 0xffff0000, v105
	v_lshlrev_b32_e32 v132, 16, v106
	v_and_b32_e32 v133, 0xffff0000, v106
	v_lshlrev_b32_e32 v134, 16, v107
	v_and_b32_e32 v135, 0xffff0000, v107
	v_lshlrev_b32_e32 v136, 16, v108
	v_and_b32_e32 v137, 0xffff0000, v108
	v_lshlrev_b32_e32 v138, 16, v109
	v_and_b32_e32 v139, 0xffff0000, v109
	v_lshlrev_b32_e32 v140, 16, v110
	v_and_b32_e32 v141, 0xffff0000, v110
	v_lshlrev_b32_e32 v142, 16, v111
	v_and_b32_e32 v143, 0xffff0000, v111
	v_pk_mul_f32 v[144:145], v[128:129], v[128:129]
	v_pk_fma_f32 v[144:145], v[130:131], v[130:131], v[144:145]
	v_pk_fma_f32 v[144:145], v[132:133], v[132:133], v[144:145]
	v_pk_fma_f32 v[144:145], v[134:135], v[134:135], v[144:145]
	v_pk_fma_f32 v[144:145], v[136:137], v[136:137], v[144:145]
	v_pk_fma_f32 v[144:145], v[138:139], v[138:139], v[144:145]
	v_pk_fma_f32 v[144:145], v[140:141], v[140:141], v[144:145]
	v_pk_fma_f32 v[144:145], v[142:143], v[142:143], v[144:145]
	v_add_f32_e32 v144, v144, v145
	s_nop 1
	v_add_f32_dpp v144, v144, v144 quad_perm:[1,0,3,2] row_mask:0xf bank_mask:0xf
	s_nop 1
	v_add_f32_dpp v144, v144, v144 quad_perm:[2,3,0,1] row_mask:0xf bank_mask:0xf
	s_nop 1
	v_add_f32_dpp v144, v144, v144 row_half_mirror row_mask:0xf bank_mask:0xf
	s_nop 1
	v_add_f32_dpp v144, v144, v144 row_mirror row_mask:0xf bank_mask:0xf
	s_nop 0
	v_mov_b32_e32 v145, v144
	s_nop 1
	v_permlane16_swap_b32_e32 v144, v145
	s_nop 0
	v_add_f32_e32 v144, v144, v145
	v_mov_b32_e32 v145, v144
	s_nop 1
	v_permlane32_swap_b32_e32 v144, v145
	s_nop 0
	v_add_f32_e32 v144, v144, v145
	v_fmamk_f32 v144, v144, 0x3a800000, v3
	v_rsq_f32_e32 v144, v144
	s_nop 0
	v_pk_mul_f32 v[128:129], v[128:129], v[144:145] op_sel_hi:[1,0]
	v_pk_mul_f32 v[130:131], v[130:131], v[144:145] op_sel_hi:[1,0]
	v_pk_mul_f32 v[132:133], v[132:133], v[144:145] op_sel_hi:[1,0]
	v_pk_mul_f32 v[134:135], v[134:135], v[144:145] op_sel_hi:[1,0]
	v_pk_mul_f32 v[136:137], v[136:137], v[144:145] op_sel_hi:[1,0]
; __device__ __forceinline__ unsigned cvt_pk_bf16(float lo, float hi) { unsigned r; asm("v_cvt_pk_bf16_f32 %0, %1, %2" : "=v"(r) : "v"(lo), "v"(hi)); return r; }
; __device__ __forceinline__ void norm_pass_bf16(const Ctx& X, const bf16_t* xs, const bf16_t* cs, int nrows, const float* gain, const float* modl, int si, bf16_t* HN) {
;     ...
;         for (int j = 0; j < 2; ++j) q[j] = *(const u32x4*)(rowp + (X.lane + 64 * j) * 8);
; #pragma unroll
;         for (int j = 0; j < 2; ++j) {
;             v[j][0] = bf2f(q[j].x & 0xffffu); v[j][1] = bf2f(q[j].x >> 16); v[j][2] = bf2f(q[j].y & 0xffffu); v[j][3] = bf2f(q[j].y >> 16);
;             v[j][4] = bf2f(q[j].z & 0xffffu); v[j][5] = bf2f(q[j].z >> 16); v[j][6] = bf2f(q[j].w & 0xffffu); v[j][7] = bf2f(q[j].w >> 16);
; #pragma unroll
;             for (int e = 0; e < 8; ++e) s += v[j][e] * v[j][e]; }
;         const float rstd = rsqrtf(wave_sum(s) * (1.0f / 1024.0f) + 1e-6f);
; #pragma unroll
;         for (int j = 0; j < 2; ++j) { const int c = (X.lane + 64 * j) * 8; float o[8];
; #pragma unroll
;             for (int h = 0; h < 2; ++h) { const f32x4 gn = *(const f32x4*)(gain + c + 4 * h), a = *(const f32x4*)(scl + c + 4 * h), b = *(const f32x4*)(sh + c + 4 * h);
; #pragma unroll
;                 for (int e = 0; e < 4; ++e) o[4 * h + e] = v[j][4 * h + e] * rstd * gn[e] * (a[e] + 1.0f) + b[e]; }
;             u32x4 w; w.x = cvt_pk_bf16(o[0], o[1]); w.y = cvt_pk_bf16(o[2], o[3]); w.z = cvt_pk_bf16(o[4], o[5]); w.w = cvt_pk_bf16(o[6], o[7]); *(u32x4*)(HN + (size_t)r * D + c) = w; }
	v_pk_mul_f32 v[138:139], v[138:139], v[144:145] op_sel_hi:[1,0]
	v_pk_mul_f32 v[140:141], v[140:141], v[144:145] op_sel_hi:[1,0]
	v_pk_mul_f32 v[142:143], v[142:143], v[144:145] op_sel_hi:[1,0]
	v_pk_mul_f32 v[128:129], v[16:17], v[128:129]
	v_pk_mul_f32 v[130:131], v[18:19], v[130:131]
	v_pk_mul_f32 v[132:133], v[20:21], v[132:133]
	v_pk_mul_f32 v[134:135], v[22:23], v[134:135]
	v_pk_mul_f32 v[136:137], v[24:25], v[136:137]
	v_pk_mul_f32 v[138:139], v[26:27], v[138:139]
	v_pk_mul_f32 v[140:141], v[28:29], v[140:141]
	v_pk_mul_f32 v[142:143], v[30:31], v[142:143]
	v_pk_fma_f32 v[128:129], v[32:33], v[128:129], v[48:49]
	v_pk_fma_f32 v[130:131], v[34:35], v[130:131], v[50:51]
	v_pk_fma_f32 v[132:133], v[36:37], v[132:133], v[52:53]
	v_pk_fma_f32 v[134:135], v[38:39], v[134:135], v[54:55]
	v_pk_fma_f32 v[136:137], v[40:41], v[136:137], v[56:57]
	v_pk_fma_f32 v[138:139], v[42:43], v[138:139], v[58:59]
	v_pk_fma_f32 v[140:141], v[44:45], v[140:141], v[60:61]
	v_pk_fma_f32 v[142:143], v[46:47], v[142:143], v[62:63]
	v_cvt_pk_bf16_f32 v148, v128, v129
	v_cvt_pk_bf16_f32 v149, v130, v131
	v_cvt_pk_bf16_f32 v150, v132, v133
	v_cvt_pk_bf16_f32 v151, v134, v135
	v_cvt_pk_bf16_f32 v152, v136, v137
	v_cvt_pk_bf16_f32 v153, v138, v139
	v_cvt_pk_bf16_f32 v154, v140, v141
	v_cvt_pk_bf16_f32 v155, v142, v143
	global_store_dwordx4 v1, v[148:151], s[10:11] offset:2048
	global_store_dwordx4 v1, v[152:155], s[10:11] offset:3072
	s_add_u32 s10, s10, 0x1000
	s_addc_u32 s11, s11, 0
	global_load_dwordx4 v[104:107], v1, s[8:9] offset:2048
	global_load_dwordx4 v[108:111], v1, s[8:9] offset:3072
	s_add_u32 s8, s8, 0x1000
	s_addc_u32 s9, s9, 0
	s_waitcnt vmcnt(26)
	v_lshlrev_b32_e32 v128, 16, v112
	v_and_b32_e32 v129, 0xffff0000, v112
	v_lshlrev_b32_e32 v130, 16, v113
	v_and_b32_e32 v131, 0xffff0000, v113
	v_lshlrev_b32_e32 v132, 16, v114
	v_and_b32_e32 v133, 0xffff0000, v114
	v_lshlrev_b32_e32 v134, 16, v115
	v_and_b32_e32 v135, 0xffff0000, v115
	v_lshlrev_b32_e32 v136, 16, v116
	v_and_b32_e32 v137, 0xffff0000, v116
	v_lshlrev_b32_e32 v138, 16, v117
	v_and_b32_e32 v139, 0xffff0000, v117
	v_lshlrev_b32_e32 v140, 16, v118
	v_and_b32_e32 v141, 0xffff0000, v118
	v_lshlrev_b32_e32 v142, 16, v119
	v_and_b32_e32 v143, 0xffff0000, v119
	v_pk_mul_f32 v[144:145], v[128:129], v[128:129]
	v_pk_fma_f32 v[144:145], v[130:131], v[130:131], v[144:145]
	v_pk_fma_f32 v[144:145], v[132:133], v[132:133], v[144:145]
	v_pk_fma_f32 v[144:145], v[134:135], v[134:135], v[144:145]
	v_pk_fma_f32 v[144:145], v[136:137], v[136:137], v[144:145]
	v_pk_fma_f32 v[144:145], v[138:139], v[138:139], v[144:145]
	v_pk_fma_f32 v[144:145], v[140:141], v[140:141], v[144:145]
	v_pk_fma_f32 v[144:145], v[142:143], v[142:143], v[144:145]
	v_add_f32_e32 v144, v144, v145
	s_nop 1
	v_add_f32_dpp v144, v144, v144 quad_perm:[1,0,3,2] row_mask:0xf bank_mask:0xf
	s_nop 1
	v_add_f32_dpp v144, v144, v144 quad_perm:[2,3,0,1] row_mask:0xf bank_mask:0xf
	s_nop 1
	v_add_f32_dpp v144, v144, v144 row_half_mirror row_mask:0xf bank_mask:0xf
	s_nop 1
	v_add_f32_dpp v144, v144, v144 row_mirror row_mask:0xf bank_mask:0xf
	s_nop 0
	v_mov_b32_e32 v145, v144
	s_nop 1
	v_permlane16_swap_b32_e32 v144, v145
	s_nop 0
	v_add_f32_e32 v144, v144, v145
	v_mov_b32_e32 v145, v144
	s_nop 1
	v_permlane32_swap_b32_e32 v144, v145
	s_nop 0
	v_add_f32_e32 v144, v144, v145
	v_fmamk_f32 v144, v144, 0x3a800000, v3
	v_rsq_f32_e32 v144, v144
	s_nop 0
	v_pk_mul_f32 v[128:129], v[128:129], v[144:145] op_sel_hi:[1,0]
	v_pk_mul_f32 v[130:131], v[130:131], v[144:145] op_sel_hi:[1,0]
	v_pk_mul_f32 v[132:133], v[132:133], v[144:145] op_sel_hi:[1,0]
	v_pk_mul_f32 v[134:135], v[134:135], v[144:145] op_sel_hi:[1,0]
	v_pk_mul_f32 v[136:137], v[136:137], v[144:145] op_sel_hi:[1,0]
	v_pk_mul_f32 v[138:139], v[138:139], v[144:145] op_sel_hi:[1,0]
	v_pk_mul_f32 v[140:141], v[140:141], v[144:145] op_sel_hi:[1,0]
	v_pk_mul_f32 v[142:143], v[142:143], v[144:145] op_sel_hi:[1,0]
	v_pk_mul_f32 v[128:129], v[16:17], v[128:129]
	v_pk_mul_f32 v[130:131], v[18:19], v[130:131]
	v_pk_mul_f32 v[132:133], v[20:21], v[132:133]
	v_pk_mul_f32 v[134:135], v[22:23], v[134:135]
	v_pk_mul_f32 v[136:137], v[24:25], v[136:137]
	v_pk_mul_f32 v[138:139], v[26:27], v[138:139]
	v_pk_mul_f32 v[140:141], v[28:29], v[140:141]
	v_pk_mul_f32 v[142:143], v[30:31], v[142:143]
	v_pk_fma_f32 v[128:129], v[32:33], v[128:129], v[48:49]
	v_pk_fma_f32 v[130:131], v[34:35], v[130:131], v[50:51]
	v_pk_fma_f32 v[132:133], v[36:37], v[132:133], v[52:53]
	v_pk_fma_f32 v[134:135], v[38:39], v[134:135], v[54:55]
	v_pk_fma_f32 v[136:137], v[40:41], v[136:137], v[56:57]
	v_pk_fma_f32 v[138:139], v[42:43], v[138:139], v[58:59]
	v_pk_fma_f32 v[140:141], v[44:45], v[140:141], v[60:61]
	v_pk_fma_f32 v[142:143], v[46:47], v[142:143], v[62:63]
	v_cvt_pk_bf16_f32 v148, v128, v129
	v_cvt_pk_bf16_f32 v149, v130, v131
	v_cvt_pk_bf16_f32 v150, v132, v133
	v_cvt_pk_bf16_f32 v151, v134, v135
	v_cvt_pk_bf16_f32 v152, v136, v137
	v_cvt_pk_bf16_f32 v153, v138, v139
	v_cvt_pk_bf16_f32 v154, v140, v141
	v_cvt_pk_bf16_f32 v155, v142, v143
	global_store_dwordx4 v1, v[148:151], s[10:11]
	global_store_dwordx4 v1, v[152:155], s[10:11] offset:1024
	global_load_dwordx4 v[112:115], v1, s[8:9]
	global_load_dwordx4 v[116:119], v1, s[8:9] offset:1024
	s_waitcnt vmcnt(28)
; __device__ __forceinline__ unsigned cvt_pk_bf16(float lo, float hi) { unsigned r; asm("v_cvt_pk_bf16_f32 %0, %1, %2" : "=v"(r) : "v"(lo), "v"(hi)); return r; }
; __device__ __forceinline__ void norm_pass_bf16(const Ctx& X, const bf16_t* xs, const bf16_t* cs, int nrows, const float* gain, const float* modl, int si, bf16_t* HN) {
;     ...
;         for (int j = 0; j < 2; ++j) q[j] = *(const u32x4*)(rowp + (X.lane + 64 * j) * 8);
; #pragma unroll
;         for (int j = 0; j < 2; ++j) {
;             v[j][0] = bf2f(q[j].x & 0xffffu); v[j][1] = bf2f(q[j].x >> 16); v[j][2] = bf2f(q[j].y & 0xffffu); v[j][3] = bf2f(q[j].y >> 16);
;             v[j][4] = bf2f(q[j].z & 0xffffu); v[j][5] = bf2f(q[j].z >> 16); v[j][6] = bf2f(q[j].w & 0xffffu); v[j][7] = bf2f(q[j].w >> 16);
; #pragma unroll
;             for (int e = 0; e < 8; ++e) s += v[j][e] * v[j][e]; }
;         const float rstd = rsqrtf(wave_sum(s) * (1.0f / 1024.0f) + 1e-6f);
; #pragma unroll
;         for (int j = 0; j < 2; ++j) { const int c = (X.lane + 64 * j) * 8; float o[8];
; #pragma unroll
;             for (int h = 0; h < 2; ++h) { const f32x4 gn = *(const f32x4*)(gain + c + 4 * h), a = *(const f32x4*)(scl + c + 4 * h), b = *(const f32x4*)(sh + c + 4 * h);
; #pragma unroll
;                 for (int e = 0; e < 4; ++e) o[4 * h + e] = v[j][4 * h + e] * rstd * gn[e] * (a[e] + 1.0f) + b[e]; }
;             u32x4 w; w.x = cvt_pk_bf16(o[0], o[1]); w.y = cvt_pk_bf16(o[2], o[3]); w.z = cvt_pk_bf16(o[4], o[5]); w.w = cvt_pk_bf16(o[6], o[7]); *(u32x4*)(HN + (size_t)r * D + c) = w; }
	v_lshlrev_b32_e32 v128, 16, v120
	v_and_b32_e32 v129, 0xffff0000, v120
	v_lshlrev_b32_e32 v130, 16, v121
	v_and_b32_e32 v131, 0xffff0000, v121
	v_lshlrev_b32_e32 v132, 16, v122
	v_and_b32_e32 v133, 0xffff0000, v122
	v_lshlrev_b32_e32 v134, 16, v123
	v_and_b32_e32 v135, 0xffff0000, v123
	v_lshlrev_b32_e32 v136, 16, v124
	v_and_b32_e32 v137, 0xffff0000, v124
	v_lshlrev_b32_e32 v138, 16, v125
	v_and_b32_e32 v139, 0xffff0000, v125
	v_lshlrev_b32_e32 v140, 16, v126
	v_and_b32_e32 v141, 0xffff0000, v126
	v_lshlrev_b32_e32 v142, 16, v127
	v_and_b32_e32 v143, 0xffff0000, v127
	v_pk_mul_f32 v[144:145], v[128:129], v[128:129]
	v_pk_fma_f32 v[144:145], v[130:131], v[130:131], v[144:145]
	v_pk_fma_f32 v[144:145], v[132:133], v[132:133], v[144:145]
	v_pk_fma_f32 v[144:145], v[134:135], v[134:135], v[144:145]
	v_pk_fma_f32 v[144:145], v[136:137], v[136:137], v[144:145]
	v_pk_fma_f32 v[144:145], v[138:139], v[138:139], v[144:145]
	v_pk_fma_f32 v[144:145], v[140:141], v[140:141], v[144:145]
	v_pk_fma_f32 v[144:145], v[142:143], v[142:143], v[144:145]
	v_add_f32_e32 v144, v144, v145
	s_nop 1
	v_add_f32_dpp v144, v144, v144 quad_perm:[1,0,3,2] row_mask:0xf bank_mask:0xf
	s_nop 1
	v_add_f32_dpp v144, v144, v144 quad_perm:[2,3,0,1] row_mask:0xf bank_mask:0xf
	s_nop 1
	v_add_f32_dpp v144, v144, v144 row_half_mirror row_mask:0xf bank_mask:0xf
	s_nop 1
	v_add_f32_dpp v144, v144, v144 row_mirror row_mask:0xf bank_mask:0xf
	s_nop 0
	v_mov_b32_e32 v145, v144
	s_nop 1
	v_permlane16_swap_b32_e32 v144, v145
	s_nop 0
	v_add_f32_e32 v144, v144, v145
	v_mov_b32_e32 v145, v144
	s_nop 1
	v_permlane32_swap_b32_e32 v144, v145
	s_nop 0
	v_add_f32_e32 v144, v144, v145
	v_fmamk_f32 v144, v144, 0x3a800000, v3
	v_rsq_f32_e32 v144, v144
	s_nop 0
	v_pk_mul_f32 v[128:129], v[128:129], v[144:145] op_sel_hi:[1,0]
	v_pk_mul_f32 v[130:131], v[130:131], v[144:145] op_sel_hi:[1,0]
	v_pk_mul_f32 v[132:133], v[132:133], v[144:145] op_sel_hi:[1,0]
	v_pk_mul_f32 v[134:135], v[134:135], v[144:145] op_sel_hi:[1,0]
	v_pk_mul_f32 v[136:137], v[136:137], v[144:145] op_sel_hi:[1,0]
	v_pk_mul_f32 v[138:139], v[138:139], v[144:145] op_sel_hi:[1,0]
	v_pk_mul_f32 v[140:141], v[140:141], v[144:145] op_sel_hi:[1,0]
	v_pk_mul_f32 v[142:143], v[142:143], v[144:145] op_sel_hi:[1,0]
	v_pk_mul_f32 v[128:129], v[16:17], v[128:129]
	v_pk_mul_f32 v[130:131], v[18:19], v[130:131]
	v_pk_mul_f32 v[132:133], v[20:21], v[132:133]
	v_pk_mul_f32 v[134:135], v[22:23], v[134:135]
	v_pk_mul_f32 v[136:137], v[24:25], v[136:137]
	v_pk_mul_f32 v[138:139], v[26:27], v[138:139]
	v_pk_mul_f32 v[140:141], v[28:29], v[140:141]
	v_pk_mul_f32 v[142:143], v[30:31], v[142:143]
	v_pk_fma_f32 v[128:129], v[32:33], v[128:129], v[48:49]
	v_pk_fma_f32 v[130:131], v[34:35], v[130:131], v[50:51]
	v_pk_fma_f32 v[132:133], v[36:37], v[132:133], v[52:53]
	v_pk_fma_f32 v[134:135], v[38:39], v[134:135], v[54:55]
	v_pk_fma_f32 v[136:137], v[40:41], v[136:137], v[56:57]
	v_pk_fma_f32 v[138:139], v[42:43], v[138:139], v[58:59]
	v_pk_fma_f32 v[140:141], v[44:45], v[140:141], v[60:61]
	v_pk_fma_f32 v[142:143], v[46:47], v[142:143], v[62:63]
	v_cvt_pk_bf16_f32 v148, v128, v129
	v_cvt_pk_bf16_f32 v149, v130, v131
	v_cvt_pk_bf16_f32 v150, v132, v133
	v_cvt_pk_bf16_f32 v151, v134, v135
	v_cvt_pk_bf16_f32 v152, v136, v137
	v_cvt_pk_bf16_f32 v153, v138, v139
	v_cvt_pk_bf16_f32 v154, v140, v141
	v_cvt_pk_bf16_f32 v155, v142, v143
	global_store_dwordx4 v1, v[148:151], s[10:11] offset:2048
	global_store_dwordx4 v1, v[152:155], s[10:11] offset:3072
	s_add_u32 s10, s10, 0x1000
	s_addc_u32 s11, s11, 0
	global_load_dwordx4 v[120:123], v1, s[8:9] offset:2048
	global_load_dwordx4 v[124:127], v1, s[8:9] offset:3072
	s_add_u32 s8, s8, 0x1000
	s_addc_u32 s9, s9, 0
	s_waitcnt vmcnt(28)
	v_lshlrev_b32_e32 v128, 16, v64
	v_and_b32_e32 v129, 0xffff0000, v64
	v_lshlrev_b32_e32 v130, 16, v65
	v_and_b32_e32 v131, 0xffff0000, v65
	v_lshlrev_b32_e32 v132, 16, v66
	v_and_b32_e32 v133, 0xffff0000, v66
	v_lshlrev_b32_e32 v134, 16, v67
	v_and_b32_e32 v135, 0xffff0000, v67
	v_lshlrev_b32_e32 v136, 16, v68
	v_and_b32_e32 v137, 0xffff0000, v68
	v_lshlrev_b32_e32 v138, 16, v69
	v_and_b32_e32 v139, 0xffff0000, v69
	v_lshlrev_b32_e32 v140, 16, v70
	v_and_b32_e32 v141, 0xffff0000, v70
	v_lshlrev_b32_e32 v142, 16, v71
	v_and_b32_e32 v143, 0xffff0000, v71
	v_pk_mul_f32 v[144:145], v[128:129], v[128:129]
	v_pk_fma_f32 v[144:145], v[130:131], v[130:131], v[144:145]
	v_pk_fma_f32 v[144:145], v[132:133], v[132:133], v[144:145]
	v_pk_fma_f32 v[144:145], v[134:135], v[134:135], v[144:145]
	v_pk_fma_f32 v[144:145], v[136:137], v[136:137], v[144:145]
	v_pk_fma_f32 v[144:145], v[138:139], v[138:139], v[144:145]
	v_pk_fma_f32 v[144:145], v[140:141], v[140:141], v[144:145]
	v_pk_fma_f32 v[144:145], v[142:143], v[142:143], v[144:145]
	v_add_f32_e32 v144, v144, v145
	s_nop 1
	v_add_f32_dpp v144, v144, v144 quad_perm:[1,0,3,2] row_mask:0xf bank_mask:0xf
	s_nop 1
	v_add_f32_dpp v144, v144, v144 quad_perm:[2,3,0,1] row_mask:0xf bank_mask:0xf
	s_nop 1
	v_add_f32_dpp v144, v144, v144 row_half_mirror row_mask:0xf bank_mask:0xf
	s_nop 1
	v_add_f32_dpp v144, v144, v144 row_mirror row_mask:0xf bank_mask:0xf
	s_nop 0
	v_mov_b32_e32 v145, v144
	s_nop 1
	v_permlane16_swap_b32_e32 v144, v145
	s_nop 0
	v_add_f32_e32 v144, v144, v145
	v_mov_b32_e32 v145, v144
	s_nop 1
	v_permlane32_swap_b32_e32 v144, v145
	s_nop 0
	v_add_f32_e32 v144, v144, v145
	v_fmamk_f32 v144, v144, 0x3a800000, v3
	v_rsq_f32_e32 v144, v144
	s_nop 0
	v_pk_mul_f32 v[128:129], v[128:129], v[144:145] op_sel_hi:[1,0]
	v_pk_mul_f32 v[130:131], v[130:131], v[144:145] op_sel_hi:[1,0]
	v_pk_mul_f32 v[132:133], v[132:133], v[144:145] op_sel_hi:[1,0]
; __device__ __forceinline__ unsigned cvt_pk_bf16(float lo, float hi) { unsigned r; asm("v_cvt_pk_bf16_f32 %0, %1, %2" : "=v"(r) : "v"(lo), "v"(hi)); return r; }
; __device__ __forceinline__ void norm_pass_bf16(const Ctx& X, const bf16_t* xs, const bf16_t* cs, int nrows, const float* gain, const float* modl, int si, bf16_t* HN) {
;     ...
;         for (int j = 0; j < 2; ++j) q[j] = *(const u32x4*)(rowp + (X.lane + 64 * j) * 8);
; #pragma unroll
;         for (int j = 0; j < 2; ++j) {
;             v[j][0] = bf2f(q[j].x & 0xffffu); v[j][1] = bf2f(q[j].x >> 16); v[j][2] = bf2f(q[j].y & 0xffffu); v[j][3] = bf2f(q[j].y >> 16);
;             v[j][4] = bf2f(q[j].z & 0xffffu); v[j][5] = bf2f(q[j].z >> 16); v[j][6] = bf2f(q[j].w & 0xffffu); v[j][7] = bf2f(q[j].w >> 16);
; #pragma unroll
;             for (int e = 0; e < 8; ++e) s += v[j][e] * v[j][e]; }
;         const float rstd = rsqrtf(wave_sum(s) * (1.0f / 1024.0f) + 1e-6f);
; #pragma unroll
;         for (int j = 0; j < 2; ++j) { const int c = (X.lane + 64 * j) * 8; float o[8];
; #pragma unroll
;             for (int h = 0; h < 2; ++h) { const f32x4 gn = *(const f32x4*)(gain + c + 4 * h), a = *(const f32x4*)(scl + c + 4 * h), b = *(const f32x4*)(sh + c + 4 * h);
; #pragma unroll
;                 for (int e = 0; e < 4; ++e) o[4 * h + e] = v[j][4 * h + e] * rstd * gn[e] * (a[e] + 1.0f) + b[e]; }
;             u32x4 w; w.x = cvt_pk_bf16(o[0], o[1]); w.y = cvt_pk_bf16(o[2], o[3]); w.z = cvt_pk_bf16(o[4], o[5]); w.w = cvt_pk_bf16(o[6], o[7]); *(u32x4*)(HN + (size_t)r * D + c) = w; }
	v_pk_mul_f32 v[134:135], v[134:135], v[144:145] op_sel_hi:[1,0]
	v_pk_mul_f32 v[136:137], v[136:137], v[144:145] op_sel_hi:[1,0]
	v_pk_mul_f32 v[138:139], v[138:139], v[144:145] op_sel_hi:[1,0]
	v_pk_mul_f32 v[140:141], v[140:141], v[144:145] op_sel_hi:[1,0]
	v_pk_mul_f32 v[142:143], v[142:143], v[144:145] op_sel_hi:[1,0]
	v_pk_mul_f32 v[128:129], v[16:17], v[128:129]
	v_pk_mul_f32 v[130:131], v[18:19], v[130:131]
	v_pk_mul_f32 v[132:133], v[20:21], v[132:133]
	v_pk_mul_f32 v[134:135], v[22:23], v[134:135]
	v_pk_mul_f32 v[136:137], v[24:25], v[136:137]
	v_pk_mul_f32 v[138:139], v[26:27], v[138:139]
	v_pk_mul_f32 v[140:141], v[28:29], v[140:141]
	v_pk_mul_f32 v[142:143], v[30:31], v[142:143]
	v_pk_fma_f32 v[128:129], v[32:33], v[128:129], v[48:49]
	v_pk_fma_f32 v[130:131], v[34:35], v[130:131], v[50:51]
	v_pk_fma_f32 v[132:133], v[36:37], v[132:133], v[52:53]
	v_pk_fma_f32 v[134:135], v[38:39], v[134:135], v[54:55]
	v_pk_fma_f32 v[136:137], v[40:41], v[136:137], v[56:57]
	v_pk_fma_f32 v[138:139], v[42:43], v[138:139], v[58:59]
	v_pk_fma_f32 v[140:141], v[44:45], v[140:141], v[60:61]
	v_pk_fma_f32 v[142:143], v[46:47], v[142:143], v[62:63]
	v_cvt_pk_bf16_f32 v148, v128, v129
	v_cvt_pk_bf16_f32 v149, v130, v131
	v_cvt_pk_bf16_f32 v150, v132, v133
	v_cvt_pk_bf16_f32 v151, v134, v135
	v_cvt_pk_bf16_f32 v152, v136, v137
	v_cvt_pk_bf16_f32 v153, v138, v139
	v_cvt_pk_bf16_f32 v154, v140, v141
	v_cvt_pk_bf16_f32 v155, v142, v143
	global_store_dwordx4 v1, v[148:151], s[10:11]
	global_store_dwordx4 v1, v[152:155], s[10:11] offset:1024
	s_waitcnt vmcnt(26)
	v_lshlrev_b32_e32 v128, 16, v72
	v_and_b32_e32 v129, 0xffff0000, v72
	v_lshlrev_b32_e32 v130, 16, v73
	v_and_b32_e32 v131, 0xffff0000, v73
	v_lshlrev_b32_e32 v132, 16, v74
	v_and_b32_e32 v133, 0xffff0000, v74
	v_lshlrev_b32_e32 v134, 16, v75
	v_and_b32_e32 v135, 0xffff0000, v75
	v_lshlrev_b32_e32 v136, 16, v76
	v_and_b32_e32 v137, 0xffff0000, v76
	v_lshlrev_b32_e32 v138, 16, v77
	v_and_b32_e32 v139, 0xffff0000, v77
	v_lshlrev_b32_e32 v140, 16, v78
	v_and_b32_e32 v141, 0xffff0000, v78
	v_lshlrev_b32_e32 v142, 16, v79
	v_and_b32_e32 v143, 0xffff0000, v79
	v_pk_mul_f32 v[144:145], v[128:129], v[128:129]
	v_pk_fma_f32 v[144:145], v[130:131], v[130:131], v[144:145]
	v_pk_fma_f32 v[144:145], v[132:133], v[132:133], v[144:145]
	v_pk_fma_f32 v[144:145], v[134:135], v[134:135], v[144:145]
	v_pk_fma_f32 v[144:145], v[136:137], v[136:137], v[144:145]
	v_pk_fma_f32 v[144:145], v[138:139], v[138:139], v[144:145]
	v_pk_fma_f32 v[144:145], v[140:141], v[140:141], v[144:145]
	v_pk_fma_f32 v[144:145], v[142:143], v[142:143], v[144:145]
	v_add_f32_e32 v144, v144, v145
	s_nop 1
	v_add_f32_dpp v144, v144, v144 quad_perm:[1,0,3,2] row_mask:0xf bank_mask:0xf
	s_nop 1
	v_add_f32_dpp v144, v144, v144 quad_perm:[2,3,0,1] row_mask:0xf bank_mask:0xf
	s_nop 1
	v_add_f32_dpp v144, v144, v144 row_half_mirror row_mask:0xf bank_mask:0xf
	s_nop 1
	v_add_f32_dpp v144, v144, v144 row_mirror row_mask:0xf bank_mask:0xf
	s_nop 0
	v_mov_b32_e32 v145, v144
	s_nop 1
	v_permlane16_swap_b32_e32 v144, v145
	s_nop 0
	v_add_f32_e32 v144, v144, v145
	v_mov_b32_e32 v145, v144
	s_nop 1
	v_permlane32_swap_b32_e32 v144, v145
	s_nop 0
	v_add_f32_e32 v144, v144, v145
	v_fmamk_f32 v144, v144, 0x3a800000, v3
	v_rsq_f32_e32 v144, v144
	s_nop 0
	v_pk_mul_f32 v[128:129], v[128:129], v[144:145] op_sel_hi:[1,0]
	v_pk_mul_f32 v[130:131], v[130:131], v[144:145] op_sel_hi:[1,0]
	v_pk_mul_f32 v[132:133], v[132:133], v[144:145] op_sel_hi:[1,0]
	v_pk_mul_f32 v[134:135], v[134:135], v[144:145] op_sel_hi:[1,0]
	v_pk_mul_f32 v[136:137], v[136:137], v[144:145] op_sel_hi:[1,0]
	v_pk_mul_f32 v[138:139], v[138:139], v[144:145] op_sel_hi:[1,0]
	v_pk_mul_f32 v[140:141], v[140:141], v[144:145] op_sel_hi:[1,0]
	v_pk_mul_f32 v[142:143], v[142:143], v[144:145] op_sel_hi:[1,0]
	v_pk_mul_f32 v[128:129], v[16:17], v[128:129]
	v_pk_mul_f32 v[130:131], v[18:19], v[130:131]
	v_pk_mul_f32 v[132:133], v[20:21], v[132:133]
	v_pk_mul_f32 v[134:135], v[22:23], v[134:135]
	v_pk_mul_f32 v[136:137], v[24:25], v[136:137]
	v_pk_mul_f32 v[138:139], v[26:27], v[138:139]
	v_pk_mul_f32 v[140:141], v[28:29], v[140:141]
	v_pk_mul_f32 v[142:143], v[30:31], v[142:143]
	v_pk_fma_f32 v[128:129], v[32:33], v[128:129], v[48:49]
	v_pk_fma_f32 v[130:131], v[34:35], v[130:131], v[50:51]
	v_pk_fma_f32 v[132:133], v[36:37], v[132:133], v[52:53]
	v_pk_fma_f32 v[134:135], v[38:39], v[134:135], v[54:55]
	v_pk_fma_f32 v[136:137], v[40:41], v[136:137], v[56:57]
	v_pk_fma_f32 v[138:139], v[42:43], v[138:139], v[58:59]
	v_pk_fma_f32 v[140:141], v[44:45], v[140:141], v[60:61]
	v_pk_fma_f32 v[142:143], v[46:47], v[142:143], v[62:63]
	v_cvt_pk_bf16_f32 v148, v128, v129
	v_cvt_pk_bf16_f32 v149, v130, v131
	v_cvt_pk_bf16_f32 v150, v132, v133
	v_cvt_pk_bf16_f32 v151, v134, v135
	v_cvt_pk_bf16_f32 v152, v136, v137
	v_cvt_pk_bf16_f32 v153, v138, v139
	v_cvt_pk_bf16_f32 v154, v140, v141
	v_cvt_pk_bf16_f32 v155, v142, v143
	global_store_dwordx4 v1, v[148:151], s[10:11] offset:2048
	global_store_dwordx4 v1, v[152:155], s[10:11] offset:3072
	s_add_u32 s10, s10, 0x1000
	s_addc_u32 s11, s11, 0
	s_waitcnt vmcnt(24)
; __device__ __forceinline__ unsigned cvt_pk_bf16(float lo, float hi) { unsigned r; asm("v_cvt_pk_bf16_f32 %0, %1, %2" : "=v"(r) : "v"(lo), "v"(hi)); return r; }
; __device__ __forceinline__ void norm_pass_bf16(const Ctx& X, const bf16_t* xs, const bf16_t* cs, int nrows, const float* gain, const float* modl, int si, bf16_t* HN) {
;     ...
;         for (int j = 0; j < 2; ++j) q[j] = *(const u32x4*)(rowp + (X.lane + 64 * j) * 8);
; #pragma unroll
;         for (int j = 0; j < 2; ++j) {
;             v[j][0] = bf2f(q[j].x & 0xffffu); v[j][1] = bf2f(q[j].x >> 16); v[j][2] = bf2f(q[j].y & 0xffffu); v[j][3] = bf2f(q[j].y >> 16);
;             v[j][4] = bf2f(q[j].z & 0xffffu); v[j][5] = bf2f(q[j].z >> 16); v[j][6] = bf2f(q[j].w & 0xffffu); v[j][7] = bf2f(q[j].w >> 16);
; #pragma unroll
;             for (int e = 0; e < 8; ++e) s += v[j][e] * v[j][e]; }
;         const float rstd = rsqrtf(wave_sum(s) * (1.0f / 1024.0f) + 1e-6f);
; #pragma unroll
;         for (int j = 0; j < 2; ++j) { const int c = (X.lane + 64 * j) * 8; float o[8];
; #pragma unroll
;             for (int h = 0; h < 2; ++h) { const f32x4 gn = *(const f32x4*)(gain + c + 4 * h), a = *(const f32x4*)(scl + c + 4 * h), b = *(const f32x4*)(sh + c + 4 * h);
; #pragma unroll
;                 for (int e = 0; e < 4; ++e) o[4 * h + e] = v[j][4 * h + e] * rstd * gn[e] * (a[e] + 1.0f) + b[e]; }
;             u32x4 w; w.x = cvt_pk_bf16(o[0], o[1]); w.y = cvt_pk_bf16(o[2], o[3]); w.z = cvt_pk_bf16(o[4], o[5]); w.w = cvt_pk_bf16(o[6], o[7]); *(u32x4*)(HN + (size_t)r * D + c) = w; }
	v_lshlrev_b32_e32 v128, 16, v80
	v_and_b32_e32 v129, 0xffff0000, v80
	v_lshlrev_b32_e32 v130, 16, v81
	v_and_b32_e32 v131, 0xffff0000, v81
	v_lshlrev_b32_e32 v132, 16, v82
	v_and_b32_e32 v133, 0xffff0000, v82
	v_lshlrev_b32_e32 v134, 16, v83
	v_and_b32_e32 v135, 0xffff0000, v83
	v_lshlrev_b32_e32 v136, 16, v84
	v_and_b32_e32 v137, 0xffff0000, v84
	v_lshlrev_b32_e32 v138, 16, v85
	v_and_b32_e32 v139, 0xffff0000, v85
	v_lshlrev_b32_e32 v140, 16, v86
	v_and_b32_e32 v141, 0xffff0000, v86
	v_lshlrev_b32_e32 v142, 16, v87
	v_and_b32_e32 v143, 0xffff0000, v87
	v_pk_mul_f32 v[144:145], v[128:129], v[128:129]
	v_pk_fma_f32 v[144:145], v[130:131], v[130:131], v[144:145]
	v_pk_fma_f32 v[144:145], v[132:133], v[132:133], v[144:145]
	v_pk_fma_f32 v[144:145], v[134:135], v[134:135], v[144:145]
	v_pk_fma_f32 v[144:145], v[136:137], v[136:137], v[144:145]
	v_pk_fma_f32 v[144:145], v[138:139], v[138:139], v[144:145]
	v_pk_fma_f32 v[144:145], v[140:141], v[140:141], v[144:145]
	v_pk_fma_f32 v[144:145], v[142:143], v[142:143], v[144:145]
	v_add_f32_e32 v144, v144, v145
	s_nop 1
	v_add_f32_dpp v144, v144, v144 quad_perm:[1,0,3,2] row_mask:0xf bank_mask:0xf
	s_nop 1
	v_add_f32_dpp v144, v144, v144 quad_perm:[2,3,0,1] row_mask:0xf bank_mask:0xf
	s_nop 1
	v_add_f32_dpp v144, v144, v144 row_half_mirror row_mask:0xf bank_mask:0xf
	s_nop 1
	v_add_f32_dpp v144, v144, v144 row_mirror row_mask:0xf bank_mask:0xf
	s_nop 0
	v_mov_b32_e32 v145, v144
	s_nop 1
	v_permlane16_swap_b32_e32 v144, v145
	s_nop 0
	v_add_f32_e32 v144, v144, v145
	v_mov_b32_e32 v145, v144
	s_nop 1
	v_permlane32_swap_b32_e32 v144, v145
	s_nop 0
	v_add_f32_e32 v144, v144, v145
	v_fmamk_f32 v144, v144, 0x3a800000, v3
	v_rsq_f32_e32 v144, v144
	s_nop 0
	v_pk_mul_f32 v[128:129], v[128:129], v[144:145] op_sel_hi:[1,0]
	v_pk_mul_f32 v[130:131], v[130:131], v[144:145] op_sel_hi:[1,0]
	v_pk_mul_f32 v[132:133], v[132:133], v[144:145] op_sel_hi:[1,0]
	v_pk_mul_f32 v[134:135], v[134:135], v[144:145] op_sel_hi:[1,0]
	v_pk_mul_f32 v[136:137], v[136:137], v[144:145] op_sel_hi:[1,0]
	v_pk_mul_f32 v[138:139], v[138:139], v[144:145] op_sel_hi:[1,0]
	v_pk_mul_f32 v[140:141], v[140:141], v[144:145] op_sel_hi:[1,0]
	v_pk_mul_f32 v[142:143], v[142:143], v[144:145] op_sel_hi:[1,0]
	v_pk_mul_f32 v[128:129], v[16:17], v[128:129]
	v_pk_mul_f32 v[130:131], v[18:19], v[130:131]
	v_pk_mul_f32 v[132:133], v[20:21], v[132:133]
	v_pk_mul_f32 v[134:135], v[22:23], v[134:135]
	v_pk_mul_f32 v[136:137], v[24:25], v[136:137]
	v_pk_mul_f32 v[138:139], v[26:27], v[138:139]
	v_pk_mul_f32 v[140:141], v[28:29], v[140:141]
	v_pk_mul_f32 v[142:143], v[30:31], v[142:143]
	v_pk_fma_f32 v[128:129], v[32:33], v[128:129], v[48:49]
	v_pk_fma_f32 v[130:131], v[34:35], v[130:131], v[50:51]
	v_pk_fma_f32 v[132:133], v[36:37], v[132:133], v[52:53]
	v_pk_fma_f32 v[134:135], v[38:39], v[134:135], v[54:55]
	v_pk_fma_f32 v[136:137], v[40:41], v[136:137], v[56:57]
	v_pk_fma_f32 v[138:139], v[42:43], v[138:139], v[58:59]
	v_pk_fma_f32 v[140:141], v[44:45], v[140:141], v[60:61]
	v_pk_fma_f32 v[142:143], v[46:47], v[142:143], v[62:63]
	v_cvt_pk_bf16_f32 v148, v128, v129
	v_cvt_pk_bf16_f32 v149, v130, v131
	v_cvt_pk_bf16_f32 v150, v132, v133
	v_cvt_pk_bf16_f32 v151, v134, v135
	v_cvt_pk_bf16_f32 v152, v136, v137
	v_cvt_pk_bf16_f32 v153, v138, v139
	v_cvt_pk_bf16_f32 v154, v140, v141
	v_cvt_pk_bf16_f32 v155, v142, v143
	global_store_dwordx4 v1, v[148:151], s[10:11]
	global_store_dwordx4 v1, v[152:155], s[10:11] offset:1024
	s_waitcnt vmcnt(22)
	v_lshlrev_b32_e32 v128, 16, v88
	v_and_b32_e32 v129, 0xffff0000, v88
	v_lshlrev_b32_e32 v130, 16, v89
	v_and_b32_e32 v131, 0xffff0000, v89
	v_lshlrev_b32_e32 v132, 16, v90
	v_and_b32_e32 v133, 0xffff0000, v90
	v_lshlrev_b32_e32 v134, 16, v91
	v_and_b32_e32 v135, 0xffff0000, v91
	v_lshlrev_b32_e32 v136, 16, v92
	v_and_b32_e32 v137, 0xffff0000, v92
	v_lshlrev_b32_e32 v138, 16, v93
	v_and_b32_e32 v139, 0xffff0000, v93
	v_lshlrev_b32_e32 v140, 16, v94
	v_and_b32_e32 v141, 0xffff0000, v94
	v_lshlrev_b32_e32 v142, 16, v95
	v_and_b32_e32 v143, 0xffff0000, v95
	v_pk_mul_f32 v[144:145], v[128:129], v[128:129]
	v_pk_fma_f32 v[144:145], v[130:131], v[130:131], v[144:145]
	v_pk_fma_f32 v[144:145], v[132:133], v[132:133], v[144:145]
	v_pk_fma_f32 v[144:145], v[134:135], v[134:135], v[144:145]
	v_pk_fma_f32 v[144:145], v[136:137], v[136:137], v[144:145]
	v_pk_fma_f32 v[144:145], v[138:139], v[138:139], v[144:145]
	v_pk_fma_f32 v[144:145], v[140:141], v[140:141], v[144:145]
	v_pk_fma_f32 v[144:145], v[142:143], v[142:143], v[144:145]
	v_add_f32_e32 v144, v144, v145
	s_nop 1
	v_add_f32_dpp v144, v144, v144 quad_perm:[1,0,3,2] row_mask:0xf bank_mask:0xf
	s_nop 1
	v_add_f32_dpp v144, v144, v144 quad_perm:[2,3,0,1] row_mask:0xf bank_mask:0xf
	s_nop 1
	v_add_f32_dpp v144, v144, v144 row_half_mirror row_mask:0xf bank_mask:0xf
	s_nop 1
	v_add_f32_dpp v144, v144, v144 row_mirror row_mask:0xf bank_mask:0xf
	s_nop 0
	v_mov_b32_e32 v145, v144
	s_nop 1
	v_permlane16_swap_b32_e32 v144, v145
	s_nop 0
	v_add_f32_e32 v144, v144, v145
	v_mov_b32_e32 v145, v144
	s_nop 1
	v_permlane32_swap_b32_e32 v144, v145
	s_nop 0
	v_add_f32_e32 v144, v144, v145
	v_fmamk_f32 v144, v144, 0x3a800000, v3
	v_rsq_f32_e32 v144, v144
	s_nop 0
	v_pk_mul_f32 v[128:129], v[128:129], v[144:145] op_sel_hi:[1,0]
	v_pk_mul_f32 v[130:131], v[130:131], v[144:145] op_sel_hi:[1,0]
	v_pk_mul_f32 v[132:133], v[132:133], v[144:145] op_sel_hi:[1,0]
	v_pk_mul_f32 v[134:135], v[134:135], v[144:145] op_sel_hi:[1,0]
	v_pk_mul_f32 v[136:137], v[136:137], v[144:145] op_sel_hi:[1,0]
	v_pk_mul_f32 v[138:139], v[138:139], v[144:145] op_sel_hi:[1,0]
	v_pk_mul_f32 v[140:141], v[140:141], v[144:145] op_sel_hi:[1,0]
	v_pk_mul_f32 v[142:143], v[142:143], v[144:145] op_sel_hi:[1,0]
	v_pk_mul_f32 v[128:129], v[16:17], v[128:129]
	v_pk_mul_f32 v[130:131], v[18:19], v[130:131]
	v_pk_mul_f32 v[132:133], v[20:21], v[132:133]
	v_pk_mul_f32 v[134:135], v[22:23], v[134:135]
	v_pk_mul_f32 v[136:137], v[24:25], v[136:137]
	v_pk_mul_f32 v[138:139], v[26:27], v[138:139]
	v_pk_mul_f32 v[140:141], v[28:29], v[140:141]
	v_pk_mul_f32 v[142:143], v[30:31], v[142:143]
	v_pk_fma_f32 v[128:129], v[32:33], v[128:129], v[48:49]
	v_pk_fma_f32 v[130:131], v[34:35], v[130:131], v[50:51]
	v_pk_fma_f32 v[132:133], v[36:37], v[132:133], v[52:53]
	v_pk_fma_f32 v[134:135], v[38:39], v[134:135], v[54:55]
	v_pk_fma_f32 v[136:137], v[40:41], v[136:137], v[56:57]
	v_pk_fma_f32 v[138:139], v[42:43], v[138:139], v[58:59]
	v_pk_fma_f32 v[140:141], v[44:45], v[140:141], v[60:61]
	v_pk_fma_f32 v[142:143], v[46:47], v[142:143], v[62:63]
	v_cvt_pk_bf16_f32 v148, v128, v129
	v_cvt_pk_bf16_f32 v149, v130, v131
	v_cvt_pk_bf16_f32 v150, v132, v133
	v_cvt_pk_bf16_f32 v151, v134, v135
	v_cvt_pk_bf16_f32 v152, v136, v137
	v_cvt_pk_bf16_f32 v153, v138, v139
	v_cvt_pk_bf16_f32 v154, v140, v141
	v_cvt_pk_bf16_f32 v155, v142, v143
	global_store_dwordx4 v1, v[148:151], s[10:11] offset:2048
	global_store_dwordx4 v1, v[152:155], s[10:11] offset:3072
	s_add_u32 s10, s10, 0x1000
	s_addc_u32 s11, s11, 0
	s_waitcnt vmcnt(20)
; __device__ __forceinline__ unsigned cvt_pk_bf16(float lo, float hi) { unsigned r; asm("v_cvt_pk_bf16_f32 %0, %1, %2" : "=v"(r) : "v"(lo), "v"(hi)); return r; }
; __device__ __forceinline__ void norm_pass_bf16(const Ctx& X, const bf16_t* xs, const bf16_t* cs, int nrows, const float* gain, const float* modl, int si, bf16_t* HN) {
;     ...
;         for (int j = 0; j < 2; ++j) q[j] = *(const u32x4*)(rowp + (X.lane + 64 * j) * 8);
; #pragma unroll
;         for (int j = 0; j < 2; ++j) {
;             v[j][0] = bf2f(q[j].x & 0xffffu); v[j][1] = bf2f(q[j].x >> 16); v[j][2] = bf2f(q[j].y & 0xffffu); v[j][3] = bf2f(q[j].y >> 16);
;             v[j][4] = bf2f(q[j].z & 0xffffu); v[j][5] = bf2f(q[j].z >> 16); v[j][6] = bf2f(q[j].w & 0xffffu); v[j][7] = bf2f(q[j].w >> 16);
; #pragma unroll
;             for (int e = 0; e < 8; ++e) s += v[j][e] * v[j][e]; }
;         const float rstd = rsqrtf(wave_sum(s) * (1.0f / 1024.0f) + 1e-6f);
; #pragma unroll
;         for (int j = 0; j < 2; ++j) { const int c = (X.lane + 64 * j) * 8; float o[8];
; #pragma unroll
;             for (int h = 0; h < 2; ++h) { const f32x4 gn = *(const f32x4*)(gain + c + 4 * h), a = *(const f32x4*)(scl + c + 4 * h), b = *(const f32x4*)(sh + c + 4 * h);
; #pragma unroll
;                 for (int e = 0; e < 4; ++e) o[4 * h + e] = v[j][4 * h + e] * rstd * gn[e] * (a[e] + 1.0f) + b[e]; }
;             u32x4 w; w.x = cvt_pk_bf16(o[0], o[1]); w.y = cvt_pk_bf16(o[2], o[3]); w.z = cvt_pk_bf16(o[4], o[5]); w.w = cvt_pk_bf16(o[6], o[7]); *(u32x4*)(HN + (size_t)r * D + c) = w; }
	v_lshlrev_b32_e32 v128, 16, v96
	v_and_b32_e32 v129, 0xffff0000, v96
	v_lshlrev_b32_e32 v130, 16, v97
	v_and_b32_e32 v131, 0xffff0000, v97
	v_lshlrev_b32_e32 v132, 16, v98
	v_and_b32_e32 v133, 0xffff0000, v98
	v_lshlrev_b32_e32 v134, 16, v99
	v_and_b32_e32 v135, 0xffff0000, v99
	v_lshlrev_b32_e32 v136, 16, v100
	v_and_b32_e32 v137, 0xffff0000, v100
	v_lshlrev_b32_e32 v138, 16, v101
	v_and_b32_e32 v139, 0xffff0000, v101
	v_lshlrev_b32_e32 v140, 16, v102
	v_and_b32_e32 v141, 0xffff0000, v102
	v_lshlrev_b32_e32 v142, 16, v103
	v_and_b32_e32 v143, 0xffff0000, v103
	v_pk_mul_f32 v[144:145], v[128:129], v[128:129]
	v_pk_fma_f32 v[144:145], v[130:131], v[130:131], v[144:145]
	v_pk_fma_f32 v[144:145], v[132:133], v[132:133], v[144:145]
	v_pk_fma_f32 v[144:145], v[134:135], v[134:135], v[144:145]
	v_pk_fma_f32 v[144:145], v[136:137], v[136:137], v[144:145]
	v_pk_fma_f32 v[144:145], v[138:139], v[138:139], v[144:145]
	v_pk_fma_f32 v[144:145], v[140:141], v[140:141], v[144:145]
	v_pk_fma_f32 v[144:145], v[142:143], v[142:143], v[144:145]
	v_add_f32_e32 v144, v144, v145
	s_nop 1
	v_add_f32_dpp v144, v144, v144 quad_perm:[1,0,3,2] row_mask:0xf bank_mask:0xf
	s_nop 1
	v_add_f32_dpp v144, v144, v144 quad_perm:[2,3,0,1] row_mask:0xf bank_mask:0xf
	s_nop 1
	v_add_f32_dpp v144, v144, v144 row_half_mirror row_mask:0xf bank_mask:0xf
	s_nop 1
	v_add_f32_dpp v144, v144, v144 row_mirror row_mask:0xf bank_mask:0xf
	s_nop 0
	v_mov_b32_e32 v145, v144
	s_nop 1
	v_permlane16_swap_b32_e32 v144, v145
	s_nop 0
	v_add_f32_e32 v144, v144, v145
	v_mov_b32_e32 v145, v144
	s_nop 1
	v_permlane32_swap_b32_e32 v144, v145
	s_nop 0
	v_add_f32_e32 v144, v144, v145
	v_fmamk_f32 v144, v144, 0x3a800000, v3
	v_rsq_f32_e32 v144, v144
	s_nop 0
	v_pk_mul_f32 v[128:129], v[128:129], v[144:145] op_sel_hi:[1,0]
	v_pk_mul_f32 v[130:131], v[130:131], v[144:145] op_sel_hi:[1,0]
	v_pk_mul_f32 v[132:133], v[132:133], v[144:145] op_sel_hi:[1,0]
	v_pk_mul_f32 v[134:135], v[134:135], v[144:145] op_sel_hi:[1,0]
	v_pk_mul_f32 v[136:137], v[136:137], v[144:145] op_sel_hi:[1,0]
	v_pk_mul_f32 v[138:139], v[138:139], v[144:145] op_sel_hi:[1,0]
	v_pk_mul_f32 v[140:141], v[140:141], v[144:145] op_sel_hi:[1,0]
	v_pk_mul_f32 v[142:143], v[142:143], v[144:145] op_sel_hi:[1,0]
	v_pk_mul_f32 v[128:129], v[16:17], v[128:129]
	v_pk_mul_f32 v[130:131], v[18:19], v[130:131]
	v_pk_mul_f32 v[132:133], v[20:21], v[132:133]
	v_pk_mul_f32 v[134:135], v[22:23], v[134:135]
	v_pk_mul_f32 v[136:137], v[24:25], v[136:137]
	v_pk_mul_f32 v[138:139], v[26:27], v[138:139]
	v_pk_mul_f32 v[140:141], v[28:29], v[140:141]
	v_pk_mul_f32 v[142:143], v[30:31], v[142:143]
	v_pk_fma_f32 v[128:129], v[32:33], v[128:129], v[48:49]
	v_pk_fma_f32 v[130:131], v[34:35], v[130:131], v[50:51]
	v_pk_fma_f32 v[132:133], v[36:37], v[132:133], v[52:53]
	v_pk_fma_f32 v[134:135], v[38:39], v[134:135], v[54:55]
	v_pk_fma_f32 v[136:137], v[40:41], v[136:137], v[56:57]
	v_pk_fma_f32 v[138:139], v[42:43], v[138:139], v[58:59]
	v_pk_fma_f32 v[140:141], v[44:45], v[140:141], v[60:61]
	v_pk_fma_f32 v[142:143], v[46:47], v[142:143], v[62:63]
	v_cvt_pk_bf16_f32 v148, v128, v129
	v_cvt_pk_bf16_f32 v149, v130, v131
	v_cvt_pk_bf16_f32 v150, v132, v133
	v_cvt_pk_bf16_f32 v151, v134, v135
	v_cvt_pk_bf16_f32 v152, v136, v137
	v_cvt_pk_bf16_f32 v153, v138, v139
	v_cvt_pk_bf16_f32 v154, v140, v141
	v_cvt_pk_bf16_f32 v155, v142, v143
	global_store_dwordx4 v1, v[148:151], s[10:11]
	global_store_dwordx4 v1, v[152:155], s[10:11] offset:1024
	s_waitcnt vmcnt(18)
	v_lshlrev_b32_e32 v128, 16, v104
	v_and_b32_e32 v129, 0xffff0000, v104
	v_lshlrev_b32_e32 v130, 16, v105
	v_and_b32_e32 v131, 0xffff0000, v105
	v_lshlrev_b32_e32 v132, 16, v106
	v_and_b32_e32 v133, 0xffff0000, v106
	v_lshlrev_b32_e32 v134, 16, v107
	v_and_b32_e32 v135, 0xffff0000, v107
	v_lshlrev_b32_e32 v136, 16, v108
	v_and_b32_e32 v137, 0xffff0000, v108
	v_lshlrev_b32_e32 v138, 16, v109
	v_and_b32_e32 v139, 0xffff0000, v109
	v_lshlrev_b32_e32 v140, 16, v110
	v_and_b32_e32 v141, 0xffff0000, v110
	v_lshlrev_b32_e32 v142, 16, v111
	v_and_b32_e32 v143, 0xffff0000, v111
	v_pk_mul_f32 v[144:145], v[128:129], v[128:129]
	v_pk_fma_f32 v[144:145], v[130:131], v[130:131], v[144:145]
	v_pk_fma_f32 v[144:145], v[132:133], v[132:133], v[144:145]
	v_pk_fma_f32 v[144:145], v[134:135], v[134:135], v[144:145]
	v_pk_fma_f32 v[144:145], v[136:137], v[136:137], v[144:145]
	v_pk_fma_f32 v[144:145], v[138:139], v[138:139], v[144:145]
	v_pk_fma_f32 v[144:145], v[140:141], v[140:141], v[144:145]
	v_pk_fma_f32 v[144:145], v[142:143], v[142:143], v[144:145]
	v_add_f32_e32 v144, v144, v145
	s_nop 1
	v_add_f32_dpp v144, v144, v144 quad_perm:[1,0,3,2] row_mask:0xf bank_mask:0xf
	s_nop 1
	v_add_f32_dpp v144, v144, v144 quad_perm:[2,3,0,1] row_mask:0xf bank_mask:0xf
	s_nop 1
	v_add_f32_dpp v144, v144, v144 row_half_mirror row_mask:0xf bank_mask:0xf
	s_nop 1
	v_add_f32_dpp v144, v144, v144 row_mirror row_mask:0xf bank_mask:0xf
	s_nop 0
	v_mov_b32_e32 v145, v144
	s_nop 1
	v_permlane16_swap_b32_e32 v144, v145
	s_nop 0
	v_add_f32_e32 v144, v144, v145
	v_mov_b32_e32 v145, v144
	s_nop 1
	v_permlane32_swap_b32_e32 v144, v145
	s_nop 0
	v_add_f32_e32 v144, v144, v145
	v_fmamk_f32 v144, v144, 0x3a800000, v3
	v_rsq_f32_e32 v144, v144
	s_nop 0
	v_pk_mul_f32 v[128:129], v[128:129], v[144:145] op_sel_hi:[1,0]
	v_pk_mul_f32 v[130:131], v[130:131], v[144:145] op_sel_hi:[1,0]
	v_pk_mul_f32 v[132:133], v[132:133], v[144:145] op_sel_hi:[1,0]
	v_pk_mul_f32 v[134:135], v[134:135], v[144:145] op_sel_hi:[1,0]
	v_pk_mul_f32 v[136:137], v[136:137], v[144:145] op_sel_hi:[1,0]
	v_pk_mul_f32 v[138:139], v[138:139], v[144:145] op_sel_hi:[1,0]
; __device__ __forceinline__ unsigned cvt_pk_bf16(float lo, float hi) { unsigned r; asm("v_cvt_pk_bf16_f32 %0, %1, %2" : "=v"(r) : "v"(lo), "v"(hi)); return r; }
; __device__ __forceinline__ void norm_pass_bf16(const Ctx& X, const bf16_t* xs, const bf16_t* cs, int nrows, const float* gain, const float* modl, int si, bf16_t* HN) {
;     ...
;         for (int j = 0; j < 2; ++j) q[j] = *(const u32x4*)(rowp + (X.lane + 64 * j) * 8);
; #pragma unroll
;         for (int j = 0; j < 2; ++j) {
;             v[j][0] = bf2f(q[j].x & 0xffffu); v[j][1] = bf2f(q[j].x >> 16); v[j][2] = bf2f(q[j].y & 0xffffu); v[j][3] = bf2f(q[j].y >> 16);
;             v[j][4] = bf2f(q[j].z & 0xffffu); v[j][5] = bf2f(q[j].z >> 16); v[j][6] = bf2f(q[j].w & 0xffffu); v[j][7] = bf2f(q[j].w >> 16);
; #pragma unroll
;             for (int e = 0; e < 8; ++e) s += v[j][e] * v[j][e]; }
;         const float rstd = rsqrtf(wave_sum(s) * (1.0f / 1024.0f) + 1e-6f);
; #pragma unroll
;         for (int j = 0; j < 2; ++j) { const int c = (X.lane + 64 * j) * 8; float o[8];
; #pragma unroll
;             for (int h = 0; h < 2; ++h) { const f32x4 gn = *(const f32x4*)(gain + c + 4 * h), a = *(const f32x4*)(scl + c + 4 * h), b = *(const f32x4*)(sh + c + 4 * h);
; #pragma unroll
;                 for (int e = 0; e < 4; ++e) o[4 * h + e] = v[j][4 * h + e] * rstd * gn[e] * (a[e] + 1.0f) + b[e]; }
;             u32x4 w; w.x = cvt_pk_bf16(o[0], o[1]); w.y = cvt_pk_bf16(o[2], o[3]); w.z = cvt_pk_bf16(o[4], o[5]); w.w = cvt_pk_bf16(o[6], o[7]); *(u32x4*)(HN + (size_t)r * D + c) = w; }
	v_pk_mul_f32 v[140:141], v[140:141], v[144:145] op_sel_hi:[1,0]
	v_pk_mul_f32 v[142:143], v[142:143], v[144:145] op_sel_hi:[1,0]
	v_pk_mul_f32 v[128:129], v[16:17], v[128:129]
	v_pk_mul_f32 v[130:131], v[18:19], v[130:131]
	v_pk_mul_f32 v[132:133], v[20:21], v[132:133]
	v_pk_mul_f32 v[134:135], v[22:23], v[134:135]
	v_pk_mul_f32 v[136:137], v[24:25], v[136:137]
	v_pk_mul_f32 v[138:139], v[26:27], v[138:139]
	v_pk_mul_f32 v[140:141], v[28:29], v[140:141]
	v_pk_mul_f32 v[142:143], v[30:31], v[142:143]
	v_pk_fma_f32 v[128:129], v[32:33], v[128:129], v[48:49]
	v_pk_fma_f32 v[130:131], v[34:35], v[130:131], v[50:51]
	v_pk_fma_f32 v[132:133], v[36:37], v[132:133], v[52:53]
	v_pk_fma_f32 v[134:135], v[38:39], v[134:135], v[54:55]
	v_pk_fma_f32 v[136:137], v[40:41], v[136:137], v[56:57]
	v_pk_fma_f32 v[138:139], v[42:43], v[138:139], v[58:59]
	v_pk_fma_f32 v[140:141], v[44:45], v[140:141], v[60:61]
	v_pk_fma_f32 v[142:143], v[46:47], v[142:143], v[62:63]
	v_cvt_pk_bf16_f32 v148, v128, v129
	v_cvt_pk_bf16_f32 v149, v130, v131
	v_cvt_pk_bf16_f32 v150, v132, v133
	v_cvt_pk_bf16_f32 v151, v134, v135
	v_cvt_pk_bf16_f32 v152, v136, v137
	v_cvt_pk_bf16_f32 v153, v138, v139
	v_cvt_pk_bf16_f32 v154, v140, v141
	v_cvt_pk_bf16_f32 v155, v142, v143
	global_store_dwordx4 v1, v[148:151], s[10:11] offset:2048
	global_store_dwordx4 v1, v[152:155], s[10:11] offset:3072
	s_add_u32 s10, s10, 0x1000
	s_addc_u32 s11, s11, 0
	s_waitcnt vmcnt(16)
	v_lshlrev_b32_e32 v128, 16, v112
	v_and_b32_e32 v129, 0xffff0000, v112
	v_lshlrev_b32_e32 v130, 16, v113
	v_and_b32_e32 v131, 0xffff0000, v113
	v_lshlrev_b32_e32 v132, 16, v114
	v_and_b32_e32 v133, 0xffff0000, v114
	v_lshlrev_b32_e32 v134, 16, v115
	v_and_b32_e32 v135, 0xffff0000, v115
	v_lshlrev_b32_e32 v136, 16, v116
	v_and_b32_e32 v137, 0xffff0000, v116
	v_lshlrev_b32_e32 v138, 16, v117
	v_and_b32_e32 v139, 0xffff0000, v117
	v_lshlrev_b32_e32 v140, 16, v118
	v_and_b32_e32 v141, 0xffff0000, v118
	v_lshlrev_b32_e32 v142, 16, v119
	v_and_b32_e32 v143, 0xffff0000, v119
	v_pk_mul_f32 v[144:145], v[128:129], v[128:129]
	v_pk_fma_f32 v[144:145], v[130:131], v[130:131], v[144:145]
	v_pk_fma_f32 v[144:145], v[132:133], v[132:133], v[144:145]
	v_pk_fma_f32 v[144:145], v[134:135], v[134:135], v[144:145]
	v_pk_fma_f32 v[144:145], v[136:137], v[136:137], v[144:145]
	v_pk_fma_f32 v[144:145], v[138:139], v[138:139], v[144:145]
	v_pk_fma_f32 v[144:145], v[140:141], v[140:141], v[144:145]
	v_pk_fma_f32 v[144:145], v[142:143], v[142:143], v[144:145]
	v_add_f32_e32 v144, v144, v145
	s_nop 1
	v_add_f32_dpp v144, v144, v144 quad_perm:[1,0,3,2] row_mask:0xf bank_mask:0xf
	s_nop 1
	v_add_f32_dpp v144, v144, v144 quad_perm:[2,3,0,1] row_mask:0xf bank_mask:0xf
	s_nop 1
	v_add_f32_dpp v144, v144, v144 row_half_mirror row_mask:0xf bank_mask:0xf
	s_nop 1
	v_add_f32_dpp v144, v144, v144 row_mirror row_mask:0xf bank_mask:0xf
	s_nop 0
	v_mov_b32_e32 v145, v144
	s_nop 1
	v_permlane16_swap_b32_e32 v144, v145
	s_nop 0
	v_add_f32_e32 v144, v144, v145
	v_mov_b32_e32 v145, v144
	s_nop 1
	v_permlane32_swap_b32_e32 v144, v145
	s_nop 0
	v_add_f32_e32 v144, v144, v145
	v_fmamk_f32 v144, v144, 0x3a800000, v3
	v_rsq_f32_e32 v144, v144
	s_nop 0
	v_pk_mul_f32 v[128:129], v[128:129], v[144:145] op_sel_hi:[1,0]
	v_pk_mul_f32 v[130:131], v[130:131], v[144:145] op_sel_hi:[1,0]
	v_pk_mul_f32 v[132:133], v[132:133], v[144:145] op_sel_hi:[1,0]
	v_pk_mul_f32 v[134:135], v[134:135], v[144:145] op_sel_hi:[1,0]
	v_pk_mul_f32 v[136:137], v[136:137], v[144:145] op_sel_hi:[1,0]
	v_pk_mul_f32 v[138:139], v[138:139], v[144:145] op_sel_hi:[1,0]
	v_pk_mul_f32 v[140:141], v[140:141], v[144:145] op_sel_hi:[1,0]
	v_pk_mul_f32 v[142:143], v[142:143], v[144:145] op_sel_hi:[1,0]
	v_pk_mul_f32 v[128:129], v[16:17], v[128:129]
	v_pk_mul_f32 v[130:131], v[18:19], v[130:131]
	v_pk_mul_f32 v[132:133], v[20:21], v[132:133]
	v_pk_mul_f32 v[134:135], v[22:23], v[134:135]
	v_pk_mul_f32 v[136:137], v[24:25], v[136:137]
	v_pk_mul_f32 v[138:139], v[26:27], v[138:139]
	v_pk_mul_f32 v[140:141], v[28:29], v[140:141]
	v_pk_mul_f32 v[142:143], v[30:31], v[142:143]
	v_pk_fma_f32 v[128:129], v[32:33], v[128:129], v[48:49]
	v_pk_fma_f32 v[130:131], v[34:35], v[130:131], v[50:51]
	v_pk_fma_f32 v[132:133], v[36:37], v[132:133], v[52:53]
	v_pk_fma_f32 v[134:135], v[38:39], v[134:135], v[54:55]
	v_pk_fma_f32 v[136:137], v[40:41], v[136:137], v[56:57]
	v_pk_fma_f32 v[138:139], v[42:43], v[138:139], v[58:59]
	v_pk_fma_f32 v[140:141], v[44:45], v[140:141], v[60:61]
	v_pk_fma_f32 v[142:143], v[46:47], v[142:143], v[62:63]
	v_cvt_pk_bf16_f32 v148, v128, v129
	v_cvt_pk_bf16_f32 v149, v130, v131
	v_cvt_pk_bf16_f32 v150, v132, v133
	v_cvt_pk_bf16_f32 v151, v134, v135
	v_cvt_pk_bf16_f32 v152, v136, v137
	v_cvt_pk_bf16_f32 v153, v138, v139
	v_cvt_pk_bf16_f32 v154, v140, v141
	v_cvt_pk_bf16_f32 v155, v142, v143
	global_store_dwordx4 v1, v[148:151], s[10:11]
	global_store_dwordx4 v1, v[152:155], s[10:11] offset:1024
	s_waitcnt vmcnt(14)
; __device__ __forceinline__ unsigned cvt_pk_bf16(float lo, float hi) { unsigned r; asm("v_cvt_pk_bf16_f32 %0, %1, %2" : "=v"(r) : "v"(lo), "v"(hi)); return r; }
; __device__ __forceinline__ float wave_sum(float v) {
; #pragma unroll
;     for (int o = 1; o < 64; o <<= 1) v += __shfl_xor(v, o);
;     return v;
; __device__ __forceinline__ void norm_pass_bf16(const Ctx& X, const bf16_t* xs, const bf16_t* cs, int nrows, const float* gain, const float* modl, int si, bf16_t* HN) {
;     for (int r = X.gw; r < nrows; r += X.NGW) {
;         const int mb = r < MX ? (r >> 12) : 8;
;         const float* sh = modl + (size_t)mb * 9216 + si * 1024; const float* scl = sh + 1024;
;         const bf16_t* rowp = r < MX ? xs + (size_t)r * D : cs + (size_t)(r - MX) * D;
;         u32x4 q[2]; float v[2][8]; float s = 0.f;
; #pragma unroll
;         for (int j = 0; j < 2; ++j) q[j] = *(const u32x4*)(rowp + (X.lane + 64 * j) * 8);
; #pragma unroll
;         for (int j = 0; j < 2; ++j) {
;             v[j][0] = bf2f(q[j].x & 0xffffu); v[j][1] = bf2f(q[j].x >> 16); v[j][2] = bf2f(q[j].y & 0xffffu); v[j][3] = bf2f(q[j].y >> 16);
;             v[j][4] = bf2f(q[j].z & 0xffffu); v[j][5] = bf2f(q[j].z >> 16); v[j][6] = bf2f(q[j].w & 0xffffu); v[j][7] = bf2f(q[j].w >> 16);
; #pragma unroll
;             for (int e = 0; e < 8; ++e) s += v[j][e] * v[j][e]; }
;         const float rstd = rsqrtf(wave_sum(s) * (1.0f / 1024.0f) + 1e-6f);
; #pragma unroll
;         for (int j = 0; j < 2; ++j) { const int c = (X.lane + 64 * j) * 8; float o[8];
; #pragma unroll
;             for (int h = 0; h < 2; ++h) { const f32x4 gn = *(const f32x4*)(gain + c + 4 * h), a = *(const f32x4*)(scl + c + 4 * h), b = *(const f32x4*)(sh + c + 4 * h);
; #pragma unroll
;                 for (int e = 0; e < 4; ++e) o[4 * h + e] = v[j][4 * h + e] * rstd * gn[e] * (a[e] + 1.0f) + b[e]; }
;             u32x4 w; w.x = cvt_pk_bf16(o[0], o[1]); w.y = cvt_pk_bf16(o[2], o[3]); w.z = cvt_pk_bf16(o[4], o[5]); w.w = cvt_pk_bf16(o[6], o[7]); *(u32x4*)(HN + (size_t)r * D + c) = w; }
;     }
	v_lshlrev_b32_e32 v128, 16, v120
	v_and_b32_e32 v129, 0xffff0000, v120
	v_lshlrev_b32_e32 v130, 16, v121
	v_and_b32_e32 v131, 0xffff0000, v121
	v_lshlrev_b32_e32 v132, 16, v122
	v_and_b32_e32 v133, 0xffff0000, v122
	v_lshlrev_b32_e32 v134, 16, v123
	v_and_b32_e32 v135, 0xffff0000, v123
	v_lshlrev_b32_e32 v136, 16, v124
	v_and_b32_e32 v137, 0xffff0000, v124
	v_lshlrev_b32_e32 v138, 16, v125
	v_and_b32_e32 v139, 0xffff0000, v125
	v_lshlrev_b32_e32 v140, 16, v126
	v_and_b32_e32 v141, 0xffff0000, v126
	v_lshlrev_b32_e32 v142, 16, v127
	v_and_b32_e32 v143, 0xffff0000, v127
	v_pk_mul_f32 v[144:145], v[128:129], v[128:129]
	v_pk_fma_f32 v[144:145], v[130:131], v[130:131], v[144:145]
	v_pk_fma_f32 v[144:145], v[132:133], v[132:133], v[144:145]
	v_pk_fma_f32 v[144:145], v[134:135], v[134:135], v[144:145]
	v_pk_fma_f32 v[144:145], v[136:137], v[136:137], v[144:145]
	v_pk_fma_f32 v[144:145], v[138:139], v[138:139], v[144:145]
	v_pk_fma_f32 v[144:145], v[140:141], v[140:141], v[144:145]
	v_pk_fma_f32 v[144:145], v[142:143], v[142:143], v[144:145]
	v_add_f32_e32 v144, v144, v145
	s_nop 1
	v_add_f32_dpp v144, v144, v144 quad_perm:[1,0,3,2] row_mask:0xf bank_mask:0xf
	s_nop 1
	v_add_f32_dpp v144, v144, v144 quad_perm:[2,3,0,1] row_mask:0xf bank_mask:0xf
	s_nop 1
	v_add_f32_dpp v144, v144, v144 row_half_mirror row_mask:0xf bank_mask:0xf
	s_nop 1
	v_add_f32_dpp v144, v144, v144 row_mirror row_mask:0xf bank_mask:0xf
	s_nop 0
	v_mov_b32_e32 v145, v144
	s_nop 1
	v_permlane16_swap_b32_e32 v144, v145
	s_nop 0
	v_add_f32_e32 v144, v144, v145
	v_mov_b32_e32 v145, v144
	s_nop 1
	v_permlane32_swap_b32_e32 v144, v145
	s_nop 0
	v_add_f32_e32 v144, v144, v145
	v_fmamk_f32 v144, v144, 0x3a800000, v3
	v_rsq_f32_e32 v144, v144
	s_nop 0
	v_pk_mul_f32 v[128:129], v[128:129], v[144:145] op_sel_hi:[1,0]
	v_pk_mul_f32 v[130:131], v[130:131], v[144:145] op_sel_hi:[1,0]
	v_pk_mul_f32 v[132:133], v[132:133], v[144:145] op_sel_hi:[1,0]
	v_pk_mul_f32 v[134:135], v[134:135], v[144:145] op_sel_hi:[1,0]
	v_pk_mul_f32 v[136:137], v[136:137], v[144:145] op_sel_hi:[1,0]
	v_pk_mul_f32 v[138:139], v[138:139], v[144:145] op_sel_hi:[1,0]
	v_pk_mul_f32 v[140:141], v[140:141], v[144:145] op_sel_hi:[1,0]
	v_pk_mul_f32 v[142:143], v[142:143], v[144:145] op_sel_hi:[1,0]
	v_pk_mul_f32 v[128:129], v[16:17], v[128:129]
	v_pk_mul_f32 v[130:131], v[18:19], v[130:131]
	v_pk_mul_f32 v[132:133], v[20:21], v[132:133]
	v_pk_mul_f32 v[134:135], v[22:23], v[134:135]
	v_pk_mul_f32 v[136:137], v[24:25], v[136:137]
	v_pk_mul_f32 v[138:139], v[26:27], v[138:139]
	v_pk_mul_f32 v[140:141], v[28:29], v[140:141]
	v_pk_mul_f32 v[142:143], v[30:31], v[142:143]
	v_pk_fma_f32 v[128:129], v[32:33], v[128:129], v[48:49]
	v_pk_fma_f32 v[130:131], v[34:35], v[130:131], v[50:51]
	v_pk_fma_f32 v[132:133], v[36:37], v[132:133], v[52:53]
	v_pk_fma_f32 v[134:135], v[38:39], v[134:135], v[54:55]
	v_pk_fma_f32 v[136:137], v[40:41], v[136:137], v[56:57]
	v_pk_fma_f32 v[138:139], v[42:43], v[138:139], v[58:59]
	v_pk_fma_f32 v[140:141], v[44:45], v[140:141], v[60:61]
	v_pk_fma_f32 v[142:143], v[46:47], v[142:143], v[62:63]
	v_cvt_pk_bf16_f32 v148, v128, v129
	v_cvt_pk_bf16_f32 v149, v130, v131
	v_cvt_pk_bf16_f32 v150, v132, v133
	v_cvt_pk_bf16_f32 v151, v134, v135
	v_cvt_pk_bf16_f32 v152, v136, v137
	v_cvt_pk_bf16_f32 v153, v138, v139
	v_cvt_pk_bf16_f32 v154, v140, v141
	v_cvt_pk_bf16_f32 v155, v142, v143
	global_store_dwordx4 v1, v[148:151], s[10:11] offset:2048
	global_store_dwordx4 v1, v[152:155], s[10:11] offset:3072
	s_add_u32 s10, s10, 0x1000
	s_addc_u32 s11, s11, 0
	s_add_i32 s12, s12, s20
	s_cmp_lt_i32 s12, 0x800
	s_cbranch_scc0 .LBB0_420
	s_waitcnt vmcnt(0)
	s_branch .Lhn_A_blk
